# GEMM K loop at priority 1 throughout (2 over the MFMA runs), 0 again for epilogue and tile header
# speedup vs baseline: 1.0695x; 1.0084x over previous
.LBB0_601:
	s_lshr_b32 s2, s21, 3
	s_or_b32 s2, s2, s22
	s_lshl_b32 s28, s2, 18
	s_and_b32 s27, s21, 7
	v_or_b32_e32 v1, s28, v129
	s_lshl_b32 s2, s27, 18
	s_add_u32 s14, s16, s2
	v_or_b32_e32 v0, v1, v128
	v_readfirstlane_b32 s2, v148
	v_lshlrev_b32_e32 v130, 1, v0
	s_mov_b32 m0, s2
	v_readfirstlane_b32 s2, v157
	v_add_lshl_u32 v0, v1, v154, 1
	s_waitcnt vmcnt(0)
	s_barrier
	s_nop 0
	s_mov_b32 m0, s2
	v_readfirstlane_b32 s2, v158
	s_addc_u32 s15, s17, 0
	v_add_lshl_u32 v2, v1, v155, 1
	s_nop 0
	s_mov_b32 m0, s2
	v_readfirstlane_b32 s2, v159
	v_add_lshl_u32 v4, v1, v156, 1
	v_lshl_add_u64 v[6:7], s[14:15], 0, v[132:133]
	s_nop 0
	s_mov_b32 m0, s2
	v_readfirstlane_b32 s2, v160
	v_lshl_add_u64 v[136:137], v[6:7], 0, v[134:135]
	s_nop 0
	s_mov_b32 m0, s2
	v_readfirstlane_b32 s2, v161
	v_lshl_add_u64 v[138:139], s[0:1], 0, v[130:131]
	v_mov_b32_e32 v1, v131
	v_lshl_add_u64 v[146:147], v[136:137], 0, s[4:5]
	s_nop 0
	s_mov_b32 m0, s2
	v_readfirstlane_b32 s2, v162
	v_lshl_add_u64 v[140:141], s[0:1], 0, v[0:1]
	v_mov_b32_e32 v3, v131
	s_nop 0
	v_lshl_add_u64 v[0:1], v[138:139], 0, 64
	s_mov_b32 m0, s2
	v_readfirstlane_b32 s2, v163
	v_lshl_add_u64 v[142:143], s[0:1], 0, v[2:3]
	v_mov_b32_e32 v5, v131
	s_nop 0
	v_lshl_add_u64 v[0:1], v[140:141], 0, 64
	s_mov_b32 m0, s2
	v_readfirstlane_b32 s2, v164
	v_lshl_add_u64 v[144:145], s[0:1], 0, v[4:5]
	s_nop 0
	v_lshl_add_u64 v[0:1], v[142:143], 0, 64
	s_mov_b32 m0, s2
	v_readfirstlane_b32 s2, v165
	s_nop 0
	v_lshl_add_u64 v[0:1], v[144:145], 0, 64
	s_mov_b32 m0, s2
	v_readfirstlane_b32 s2, v166
	s_nop 0
	v_lshl_add_u64 v[0:1], v[136:137], 0, 64
	s_mov_b32 m0, s2
	v_readfirstlane_b32 s2, v167
	s_nop 0
	v_lshl_add_u64 v[0:1], v[136:137], 0, s[10:11]
	s_mov_b32 m0, s2
	s_mov_b32 s14, s3
	s_nop 0
	s_mov_b32 s15, 2
	s_mov_b32 s29, s3
	v_mov_b32_e32 v0, 0
	v_mov_b32_e32 v1, v131
	v_mov_b32_e32 v2, v131
	v_mov_b32_e32 v4, v131
	v_mov_b32_e32 v6, v131
	v_mov_b32_e32 v7, v131
	v_mov_b32_e32 v8, v131
	v_mov_b32_e32 v9, v131
	v_mov_b32_e32 v10, v131
	v_mov_b32_e32 v11, v131
	v_mov_b32_e32 v12, v131
	v_mov_b32_e32 v13, v131
	v_mov_b32_e32 v14, v131
	v_mov_b32_e32 v15, v131
	v_mov_b32_e32 v16, 0
	v_mov_b32_e32 v17, v131
	v_mov_b32_e32 v18, v131
	v_mov_b32_e32 v19, v131
	v_mov_b32_e32 v20, v131
	v_mov_b32_e32 v21, v131
	v_mov_b32_e32 v22, v131
	v_mov_b32_e32 v23, v131
	v_mov_b32_e32 v24, v131
	v_mov_b32_e32 v25, v131
	v_mov_b32_e32 v26, v131
	v_mov_b32_e32 v27, v131
	v_mov_b32_e32 v28, v131
	v_mov_b32_e32 v29, v131
	v_mov_b32_e32 v30, v131
	v_mov_b32_e32 v31, v131
	v_mov_b32_e32 v32, 0
	v_mov_b32_e32 v33, v131
	v_mov_b32_e32 v34, v131
	v_mov_b32_e32 v35, v131
	v_mov_b32_e32 v36, v131
	v_mov_b32_e32 v37, v131
	v_mov_b32_e32 v38, v131
	v_mov_b32_e32 v39, v131
	v_mov_b32_e32 v40, v131
	v_mov_b32_e32 v41, v131
	v_mov_b32_e32 v42, v131
	v_mov_b32_e32 v43, v131
	v_mov_b32_e32 v44, v131
	v_mov_b32_e32 v45, v131
	v_mov_b32_e32 v46, v131
	v_mov_b32_e32 v47, v131
	v_mov_b32_e32 v48, 0
	v_mov_b32_e32 v49, v131
	v_mov_b32_e32 v50, v131
	v_mov_b32_e32 v51, v131
	v_mov_b32_e32 v52, v131
	v_mov_b32_e32 v53, v131
	v_mov_b32_e32 v54, v131
	v_mov_b32_e32 v55, v131
	v_mov_b32_e32 v56, v131
	v_mov_b32_e32 v57, v131
	v_mov_b32_e32 v58, v131
	v_mov_b32_e32 v59, v131
	v_mov_b32_e32 v60, v131
	v_mov_b32_e32 v61, v131
	v_mov_b32_e32 v62, v131
	v_mov_b32_e32 v63, v131
	v_mov_b32_e32 v64, 0
	v_mov_b32_e32 v65, v131
	v_mov_b32_e32 v66, v131
	v_mov_b32_e32 v67, v131
	v_mov_b32_e32 v68, v131
	v_mov_b32_e32 v69, v131
	v_mov_b32_e32 v70, v131
	v_mov_b32_e32 v71, v131
	v_mov_b32_e32 v72, v131
	v_mov_b32_e32 v73, v131
	v_mov_b32_e32 v74, v131
	v_mov_b32_e32 v75, v131
	v_mov_b32_e32 v76, v131
	v_mov_b32_e32 v77, v131
	v_mov_b32_e32 v78, v131
	v_mov_b32_e32 v79, v131
	v_mov_b32_e32 v80, 0
	v_mov_b32_e32 v81, v131
	v_mov_b32_e32 v82, v131
	v_mov_b32_e32 v83, v131
	v_mov_b32_e32 v84, v131
	v_mov_b32_e32 v85, v131
	v_mov_b32_e32 v86, v131
	v_mov_b32_e32 v87, v131
	v_mov_b32_e32 v88, v131
	v_mov_b32_e32 v89, v131
	v_mov_b32_e32 v90, v131
	v_mov_b32_e32 v91, v131
	v_mov_b32_e32 v92, v131
	v_mov_b32_e32 v93, v131
	v_mov_b32_e32 v94, v131
	v_mov_b32_e32 v95, v131
	v_mov_b32_e32 v96, 0
	v_mov_b32_e32 v97, v131
	v_mov_b32_e32 v98, v131
	v_mov_b32_e32 v99, v131
	v_mov_b32_e32 v100, v131
	v_mov_b32_e32 v101, v131
	v_mov_b32_e32 v102, v131
	v_mov_b32_e32 v103, v131
	v_mov_b32_e32 v104, v131
	v_mov_b32_e32 v105, v131
	v_mov_b32_e32 v106, v131
	v_mov_b32_e32 v107, v131
	v_mov_b32_e32 v108, v131
	v_mov_b32_e32 v109, v131
	v_mov_b32_e32 v110, v131
	v_mov_b32_e32 v111, v131
	v_mov_b32_e32 v112, 0
	v_mov_b32_e32 v113, v131
	v_mov_b32_e32 v114, v131
	v_mov_b32_e32 v115, v131
	v_mov_b32_e32 v116, v131
	v_mov_b32_e32 v117, v131
	v_mov_b32_e32 v118, v131
	v_mov_b32_e32 v119, v131
	v_mov_b32_e32 v120, v131
	v_mov_b32_e32 v121, v131
	v_mov_b32_e32 v122, v131
	v_mov_b32_e32 v123, v131
	v_mov_b32_e32 v124, v131
	v_mov_b32_e32 v125, v131
	v_mov_b32_e32 v126, v131
	v_mov_b32_e32 v127, v131
	s_mov_b64 s[50:51], 0x80
	v_lshrrev_b32_e32 v174, 6, v180
	v_lshlrev_b32_e32 v184, 11, v174
	v_and_b32_e32 v170, 63, v180
	v_readfirstlane_b32 s49, v184
	v_lshrrev_b32_e32 v171, 4, v170
	v_bfe_u32 v172, v170, 1, 3
	v_xor_b32_e32 v172, v171, v172
	v_and_b32_e32 v173, 31, v170
	v_lshlrev_b32_e32 v173, 7, v173
	v_lshrrev_b32_e32 v173, 3, v170
	v_lshlrev_b32_e32 v184, 4, v173
	v_add_u32_e32 v185, 0x80, v184
	v_and_b32_e32 v173, 7, v170
	v_lshrrev_b32_e32 v171, 4, v170
	v_xor_b32_e32 v171, v173, v171
	v_lshrrev_b32_e32 v173, 5, v170
	v_sub_u32_e32 v186, v171, v173
	v_xor_b32_e32 v171, 4, v171
	v_add_u32_e32 v173, 2, v173
	v_sub_u32_e32 v188, v171, v173
	v_lshlrev_b32_e32 v186, 4, v186
	v_ashrrev_i32_e32 v187, 31, v186
	v_lshlrev_b32_e32 v188, 4, v188
	v_ashrrev_i32_e32 v189, 31, v188
	ds_bpermute_b32 v244, v184, v136
	ds_bpermute_b32 v245, v184, v137
	ds_bpermute_b32 v246, v185, v136
	ds_bpermute_b32 v247, v185, v137
	ds_bpermute_b32 v248, v184, v146
	ds_bpermute_b32 v249, v184, v147
	ds_bpermute_b32 v250, v185, v146
	ds_bpermute_b32 v251, v185, v147
	s_waitcnt lgkmcnt(0)
	ds_bpermute_b32 v178, v184, v138
	ds_bpermute_b32 v179, v184, v139
	ds_bpermute_b32 v234, v185, v138
	ds_bpermute_b32 v235, v185, v139
	ds_bpermute_b32 v236, v184, v140
	ds_bpermute_b32 v237, v184, v141
	ds_bpermute_b32 v238, v185, v140
	ds_bpermute_b32 v239, v185, v141
	ds_bpermute_b32 v240, v184, v142
	ds_bpermute_b32 v241, v184, v143
	ds_bpermute_b32 v242, v185, v142
	ds_bpermute_b32 v243, v185, v143
	ds_bpermute_b32 v136, v184, v144
	ds_bpermute_b32 v137, v184, v145
	ds_bpermute_b32 v146, v185, v144
	ds_bpermute_b32 v147, v185, v145
	s_waitcnt lgkmcnt(0)
	v_and_b32_e32 v173, 15, v170
	v_lshlrev_b32_e32 v173, 7, v173
	v_lshrrev_b32_e32 v171, 1, v174
	v_lshl_add_u32 v138, v171, 14, v173
	v_and_b32_e32 v171, 1, v174
	v_lshl_add_u32 v142, v171, 13, v173
	v_add_u32_e32 v142, 0x10000, v142
	v_xor_b32_e32 v173, 4, v172
	v_lshl_add_u32 v139, v173, 4, v138
	v_lshl_add_u32 v143, v173, 4, v142
	v_xor_b32_e32 v173, 0, v172
	v_lshl_add_u32 v138, v173, 4, v138
	v_lshl_add_u32 v142, v173, 4, v142
	v_lshl_add_u64 v[178:179], v[178:179], 0, v[186:187]
	v_lshl_add_u64 v[234:235], v[234:235], 0, v[188:189]
	v_lshl_add_u64 v[236:237], v[236:237], 0, v[186:187]
	v_lshl_add_u64 v[238:239], v[238:239], 0, v[188:189]
	v_lshl_add_u64 v[240:241], v[240:241], 0, v[186:187]
	v_lshl_add_u64 v[242:243], v[242:243], 0, v[188:189]
	v_lshl_add_u64 v[136:137], v[136:137], 0, v[186:187]
	v_lshl_add_u64 v[146:147], v[146:147], 0, v[188:189]
	v_lshl_add_u64 v[244:245], v[244:245], 0, v[186:187]
	v_lshl_add_u64 v[246:247], v[246:247], 0, v[188:189]
	v_lshl_add_u64 v[248:249], v[248:249], 0, v[186:187]
	v_lshl_add_u64 v[250:251], v[250:251], 0, v[188:189]
	s_mov_b32 s54, s49
	s_add_i32 m0, s54, 0x0
	s_nop 0
	global_load_lds_dwordx4 v[178:179], off
	s_add_i32 m0, s54, 0x400
	v_lshl_add_u64 v[178:179], v[178:179], 0, s[50:51]
	global_load_lds_dwordx4 v[234:235], off
	s_add_i32 m0, s54, 0x2000
	v_lshl_add_u64 v[234:235], v[234:235], 0, s[50:51]
	global_load_lds_dwordx4 v[236:237], off
	s_add_i32 m0, s54, 0x2400
	v_lshl_add_u64 v[236:237], v[236:237], 0, s[50:51]
	global_load_lds_dwordx4 v[238:239], off
	s_add_i32 m0, s54, 0x4000
	v_lshl_add_u64 v[238:239], v[238:239], 0, s[50:51]
	global_load_lds_dwordx4 v[240:241], off
	s_add_i32 m0, s54, 0x4400
	v_lshl_add_u64 v[240:241], v[240:241], 0, s[50:51]
	global_load_lds_dwordx4 v[242:243], off
	s_add_i32 m0, s54, 0x6000
	v_lshl_add_u64 v[242:243], v[242:243], 0, s[50:51]
	global_load_lds_dwordx4 v[136:137], off
	s_add_i32 m0, s54, 0x6400
	v_lshl_add_u64 v[136:137], v[136:137], 0, s[50:51]
	global_load_lds_dwordx4 v[146:147], off
	v_lshl_add_u64 v[146:147], v[146:147], 0, s[50:51]
	s_add_i32 s54, s49, 0x10000
	s_add_i32 m0, s54, 0x0
	s_nop 0
	global_load_lds_dwordx4 v[244:245], off
	s_add_i32 m0, s54, 0x400
	v_lshl_add_u64 v[244:245], v[244:245], 0, s[50:51]
	global_load_lds_dwordx4 v[246:247], off
	s_add_i32 m0, s54, 0x2000
	v_lshl_add_u64 v[246:247], v[246:247], 0, s[50:51]
	global_load_lds_dwordx4 v[248:249], off
	s_add_i32 m0, s54, 0x2400
	v_lshl_add_u64 v[248:249], v[248:249], 0, s[50:51]
	global_load_lds_dwordx4 v[250:251], off
	v_lshl_add_u64 v[250:251], v[250:251], 0, s[50:51]
	s_mov_b32 s14, 0
	s_mov_b32 s15, 0
	s_setprio 1

.Lg_ph5_noB:
	s_setprio 2
	s_waitcnt lgkmcnt(3)
	v_mfma_f32_16x16x32_bf16 v[0:3], v[170:173], v[190:193], v[0:3]
	v_mfma_f32_16x16x32_bf16 v[4:7], v[170:173], v[194:197], v[4:7]
	v_mfma_f32_16x16x32_bf16 v[8:11], v[170:173], v[198:201], v[8:11]
	v_mfma_f32_16x16x32_bf16 v[12:15], v[170:173], v[202:205], v[12:15]
	ds_read_b128 v[170:173], v138 offset:8192
	s_waitcnt lgkmcnt(3)
	v_mfma_f32_16x16x32_bf16 v[16:19], v[174:177], v[190:193], v[16:19]
	v_mfma_f32_16x16x32_bf16 v[20:23], v[174:177], v[194:197], v[20:23]
	v_mfma_f32_16x16x32_bf16 v[24:27], v[174:177], v[198:201], v[24:27]
	v_mfma_f32_16x16x32_bf16 v[28:31], v[174:177], v[202:205], v[28:31]
	ds_read_b128 v[174:177], v138 offset:10240
	s_waitcnt lgkmcnt(3)
	v_mfma_f32_16x16x32_bf16 v[32:35], v[182:185], v[190:193], v[32:35]
	v_mfma_f32_16x16x32_bf16 v[36:39], v[182:185], v[194:197], v[36:39]
	v_mfma_f32_16x16x32_bf16 v[40:43], v[182:185], v[198:201], v[40:43]
	v_mfma_f32_16x16x32_bf16 v[44:47], v[182:185], v[202:205], v[44:47]
	ds_read_b128 v[182:185], v138 offset:12288
	s_waitcnt lgkmcnt(3)
	v_mfma_f32_16x16x32_bf16 v[48:51], v[186:189], v[190:193], v[48:51]
	v_mfma_f32_16x16x32_bf16 v[52:55], v[186:189], v[194:197], v[52:55]
	v_mfma_f32_16x16x32_bf16 v[56:59], v[186:189], v[198:201], v[56:59]
	v_mfma_f32_16x16x32_bf16 v[60:63], v[186:189], v[202:205], v[60:63]
	ds_read_b128 v[186:189], v138 offset:14336
	s_waitcnt lgkmcnt(3)
	v_mfma_f32_16x16x32_bf16 v[64:67], v[170:173], v[190:193], v[64:67]
	v_mfma_f32_16x16x32_bf16 v[68:71], v[170:173], v[194:197], v[68:71]
	v_mfma_f32_16x16x32_bf16 v[72:75], v[170:173], v[198:201], v[72:75]
	v_mfma_f32_16x16x32_bf16 v[76:79], v[170:173], v[202:205], v[76:79]
	ds_read_b128 v[170:173], v139
	s_waitcnt lgkmcnt(3)
	v_mfma_f32_16x16x32_bf16 v[80:83], v[174:177], v[190:193], v[80:83]
	v_mfma_f32_16x16x32_bf16 v[84:87], v[174:177], v[194:197], v[84:87]
	v_mfma_f32_16x16x32_bf16 v[88:91], v[174:177], v[198:201], v[88:91]
	v_mfma_f32_16x16x32_bf16 v[92:95], v[174:177], v[202:205], v[92:95]
	ds_read_b128 v[174:177], v139 offset:2048
	s_waitcnt lgkmcnt(3)
	v_mfma_f32_16x16x32_bf16 v[96:99], v[182:185], v[190:193], v[96:99]
	v_mfma_f32_16x16x32_bf16 v[100:103], v[182:185], v[194:197], v[100:103]
	v_mfma_f32_16x16x32_bf16 v[104:107], v[182:185], v[198:201], v[104:107]
	v_mfma_f32_16x16x32_bf16 v[108:111], v[182:185], v[202:205], v[108:111]
	ds_read_b128 v[182:185], v139 offset:4096
	s_waitcnt lgkmcnt(3)
	v_mfma_f32_16x16x32_bf16 v[112:115], v[186:189], v[190:193], v[112:115]
	v_mfma_f32_16x16x32_bf16 v[116:119], v[186:189], v[194:197], v[116:119]
	v_mfma_f32_16x16x32_bf16 v[120:123], v[186:189], v[198:201], v[120:123]
	v_mfma_f32_16x16x32_bf16 v[124:127], v[186:189], v[202:205], v[124:127]
	ds_read_b128 v[186:189], v139 offset:6144
	s_waitcnt lgkmcnt(3)
	v_mfma_f32_16x16x32_bf16 v[0:3], v[170:173], v[206:209], v[0:3]
	v_mfma_f32_16x16x32_bf16 v[4:7], v[170:173], v[222:225], v[4:7]
	v_mfma_f32_16x16x32_bf16 v[8:11], v[170:173], v[226:229], v[8:11]
	v_mfma_f32_16x16x32_bf16 v[12:15], v[170:173], v[230:233], v[12:15]
	ds_read_b128 v[170:173], v139 offset:8192
	s_waitcnt lgkmcnt(3)
	v_mfma_f32_16x16x32_bf16 v[16:19], v[174:177], v[206:209], v[16:19]
	v_mfma_f32_16x16x32_bf16 v[20:23], v[174:177], v[222:225], v[20:23]
	v_mfma_f32_16x16x32_bf16 v[24:27], v[174:177], v[226:229], v[24:27]
	v_mfma_f32_16x16x32_bf16 v[28:31], v[174:177], v[230:233], v[28:31]
	ds_read_b128 v[174:177], v139 offset:10240
	s_waitcnt lgkmcnt(3)
	v_mfma_f32_16x16x32_bf16 v[32:35], v[182:185], v[206:209], v[32:35]
	v_mfma_f32_16x16x32_bf16 v[36:39], v[182:185], v[222:225], v[36:39]
	v_mfma_f32_16x16x32_bf16 v[40:43], v[182:185], v[226:229], v[40:43]
	v_mfma_f32_16x16x32_bf16 v[44:47], v[182:185], v[230:233], v[44:47]
	ds_read_b128 v[182:185], v139 offset:12288
	s_waitcnt lgkmcnt(3)
	v_mfma_f32_16x16x32_bf16 v[48:51], v[186:189], v[206:209], v[48:51]
	v_mfma_f32_16x16x32_bf16 v[52:55], v[186:189], v[222:225], v[52:55]
	v_mfma_f32_16x16x32_bf16 v[56:59], v[186:189], v[226:229], v[56:59]
	v_mfma_f32_16x16x32_bf16 v[60:63], v[186:189], v[230:233], v[60:63]
	ds_read_b128 v[186:189], v139 offset:14336
	s_waitcnt lgkmcnt(3)
	v_mfma_f32_16x16x32_bf16 v[64:67], v[170:173], v[206:209], v[64:67]
	v_mfma_f32_16x16x32_bf16 v[68:71], v[170:173], v[222:225], v[68:71]
	v_mfma_f32_16x16x32_bf16 v[72:75], v[170:173], v[226:229], v[72:75]
	v_mfma_f32_16x16x32_bf16 v[76:79], v[170:173], v[230:233], v[76:79]
	s_waitcnt lgkmcnt(2)
	v_mfma_f32_16x16x32_bf16 v[80:83], v[174:177], v[206:209], v[80:83]
	v_mfma_f32_16x16x32_bf16 v[84:87], v[174:177], v[222:225], v[84:87]
	v_mfma_f32_16x16x32_bf16 v[88:91], v[174:177], v[226:229], v[88:91]
	v_mfma_f32_16x16x32_bf16 v[92:95], v[174:177], v[230:233], v[92:95]
	s_waitcnt lgkmcnt(1)
	v_mfma_f32_16x16x32_bf16 v[96:99], v[182:185], v[206:209], v[96:99]
	v_mfma_f32_16x16x32_bf16 v[100:103], v[182:185], v[222:225], v[100:103]
	v_mfma_f32_16x16x32_bf16 v[104:107], v[182:185], v[226:229], v[104:107]
	v_mfma_f32_16x16x32_bf16 v[108:111], v[182:185], v[230:233], v[108:111]
	s_waitcnt lgkmcnt(0)
	v_mfma_f32_16x16x32_bf16 v[112:115], v[186:189], v[206:209], v[112:115]
	v_mfma_f32_16x16x32_bf16 v[116:119], v[186:189], v[222:225], v[116:119]
	v_mfma_f32_16x16x32_bf16 v[120:123], v[186:189], v[226:229], v[120:123]
	v_mfma_f32_16x16x32_bf16 v[124:127], v[186:189], v[230:233], v[124:127]
	s_setprio 1
	v_xor_b32_e32 v138, 0x8000, v138
	v_xor_b32_e32 v139, 0x8000, v139
	s_xor_b32 s15, s15, 0x8000
	s_add_i32 s14, s14, 1
	s_cmp_eq_u32 s14, 16
	s_cbranch_scc0 .Lg_ph5_top
	s_setprio 0
	s_waitcnt vmcnt(0)
	v_mov_b32_e32 v130, v180
	v_add_u32_e32 v201, 0x400, v153
	v_add_u32_e32 v200, 0x1000, v153
	v_add_u32_e32 v199, 0x1400, v153
	v_add_u32_e32 v198, 0x2000, v153
	v_add_u32_e32 v192, 0x2400, v153
	v_add_u32_e32 v193, 0x3000, v153
	v_add_u32_e32 v194, 0x3200, v153
	v_add_u32_e32 v195, 0x3400, v153
	v_add_u32_e32 v196, 0x3600, v153
	v_add_u32_e32 v197, 0x4000, v153
	v_add_u32_e32 v189, 0x4400, v153
	v_add_u32_e32 v190, 0x4800, v153
	v_add_u32_e32 v191, 0x5000, v153
	v_add_u32_e32 v186, 0x5400, v153
	v_add_u32_e32 v187, 0x5800, v153
	v_add_u32_e32 v188, 0x6000, v153
	v_add_u32_e32 v179, 0x6400, v153
	v_add_u32_e32 v181, 0x6800, v153
	v_add_u32_e32 v182, 0x7200, v153
	v_add_u32_e32 v183, 0x7400, v153
	v_add_u32_e32 v184, 0x7600, v153
	v_add_u32_e32 v185, 0x7800, v153
	v_add_u32_e32 v178, 0x8400, v153
	v_add_u32_e32 v177, 0x8800, v153
	v_add_u32_e32 v176, 0x9400, v153
	v_add_u32_e32 v175, 0x9800, v153
	v_add_u32_e32 v174, 0xa400, v153
	v_add_u32_e32 v147, 0xa800, v153
	v_add_u32_e32 v169, 0xb400, v153
	v_add_u32_e32 v170, 0xb600, v153
	v_add_u32_e32 v171, 0xb800, v153
	v_add_u32_e32 v172, 0xba00, v153
	s_waitcnt vmcnt(0)
	s_barrier
	s_and_saveexec_b64 s[14:15], s[6:7]
	s_cbranch_execz .LBB0_605
	v_and_b32_e32 v254, 63, v180
	v_lshrrev_b32_e32 v253, 4, v254
	v_mul_u32_u24_e32 v253, 0x840, v253
	v_and_b32_e32 v254, 15, v254
	v_lshl_add_u32 v253, v254, 2, v253
	v_and_b32_e32 v254, 64, v180
	v_lshl_add_u32 v253, v254, 2, v253
	ds_write_b32 v253, v0 offset:0
	ds_write_b32 v253, v1 offset:528
	ds_write_b32 v253, v2 offset:1056
	ds_write_b32 v253, v3 offset:1584
	ds_write_b32 v253, v4 offset:64
	ds_write_b32 v253, v5 offset:592
	ds_write_b32 v253, v6 offset:1120
	ds_write_b32 v253, v7 offset:1648
	ds_write_b32 v253, v8 offset:128
	ds_write_b32 v253, v9 offset:656
	ds_write_b32 v253, v10 offset:1184
	ds_write_b32 v253, v11 offset:1712
	ds_write_b32 v253, v12 offset:192
	ds_write_b32 v253, v13 offset:720
	ds_write_b32 v253, v14 offset:1248
	ds_write_b32 v253, v15 offset:1776
	ds_write_b32 v253, v16 offset:8448
	ds_write_b32 v253, v17 offset:8976
	ds_write_b32 v253, v18 offset:9504
	ds_write_b32 v253, v19 offset:10032
	ds_write_b32 v253, v20 offset:8512
	ds_write_b32 v253, v21 offset:9040
	ds_write_b32 v253, v22 offset:9568
	ds_write_b32 v253, v23 offset:10096
	ds_write_b32 v253, v24 offset:8576
	ds_write_b32 v253, v25 offset:9104
	ds_write_b32 v253, v26 offset:9632
	ds_write_b32 v253, v27 offset:10160
	ds_write_b32 v253, v28 offset:8640
	ds_write_b32 v253, v29 offset:9168
	ds_write_b32 v253, v30 offset:9696
	ds_write_b32 v253, v31 offset:10224
	ds_write_b32 v253, v32 offset:16896
	ds_write_b32 v253, v33 offset:17424
	ds_write_b32 v253, v34 offset:17952
	ds_write_b32 v253, v35 offset:18480
	ds_write_b32 v253, v36 offset:16960
	ds_write_b32 v253, v37 offset:17488
	ds_write_b32 v253, v38 offset:18016
	ds_write_b32 v253, v39 offset:18544
	ds_write_b32 v253, v40 offset:17024
	ds_write_b32 v253, v41 offset:17552
	ds_write_b32 v253, v42 offset:18080
	ds_write_b32 v253, v43 offset:18608
	ds_write_b32 v253, v44 offset:17088
	ds_write_b32 v253, v45 offset:17616
	ds_write_b32 v253, v46 offset:18144
	ds_write_b32 v253, v47 offset:18672
	ds_write_b32 v253, v48 offset:25344
	ds_write_b32 v253, v49 offset:25872
	ds_write_b32 v253, v50 offset:26400
	ds_write_b32 v253, v51 offset:26928
	ds_write_b32 v253, v52 offset:25408
	ds_write_b32 v253, v53 offset:25936
	ds_write_b32 v253, v54 offset:26464
	ds_write_b32 v253, v55 offset:26992
	ds_write_b32 v253, v56 offset:25472
	ds_write_b32 v253, v57 offset:26000
	ds_write_b32 v253, v58 offset:26528
	ds_write_b32 v253, v59 offset:27056
	ds_write_b32 v253, v60 offset:25536
	ds_write_b32 v253, v61 offset:26064
	ds_write_b32 v253, v62 offset:26592
	ds_write_b32 v253, v63 offset:27120
	ds_write_b32 v253, v64 offset:33792
	ds_write_b32 v253, v65 offset:34320
	ds_write_b32 v253, v66 offset:34848
	ds_write_b32 v253, v67 offset:35376
	ds_write_b32 v253, v68 offset:33856
	ds_write_b32 v253, v69 offset:34384
	ds_write_b32 v253, v70 offset:34912
	ds_write_b32 v253, v71 offset:35440
	ds_write_b32 v253, v72 offset:33920
	ds_write_b32 v253, v73 offset:34448
	ds_write_b32 v253, v74 offset:34976
	ds_write_b32 v253, v75 offset:35504
	ds_write_b32 v253, v76 offset:33984
	ds_write_b32 v253, v77 offset:34512
	ds_write_b32 v253, v78 offset:35040
	ds_write_b32 v253, v79 offset:35568
	ds_write_b32 v253, v80 offset:42240
	ds_write_b32 v253, v81 offset:42768
	ds_write_b32 v253, v82 offset:43296
	ds_write_b32 v253, v83 offset:43824
	ds_write_b32 v253, v84 offset:42304
	ds_write_b32 v253, v85 offset:42832
	ds_write_b32 v253, v86 offset:43360
	ds_write_b32 v253, v87 offset:43888
	ds_write_b32 v253, v88 offset:42368
	ds_write_b32 v253, v89 offset:42896
	ds_write_b32 v253, v90 offset:43424
	ds_write_b32 v253, v91 offset:43952
	ds_write_b32 v253, v92 offset:42432
	ds_write_b32 v253, v93 offset:42960
	ds_write_b32 v253, v94 offset:43488
	ds_write_b32 v253, v95 offset:44016
	ds_write_b32 v253, v96 offset:50688
	ds_write_b32 v253, v97 offset:51216
	ds_write_b32 v253, v98 offset:51744
	ds_write_b32 v253, v99 offset:52272
	ds_write_b32 v253, v100 offset:50752
	ds_write_b32 v253, v101 offset:51280
	ds_write_b32 v253, v102 offset:51808
	ds_write_b32 v253, v103 offset:52336
	ds_write_b32 v253, v104 offset:50816
	ds_write_b32 v253, v105 offset:51344
	ds_write_b32 v253, v106 offset:51872
	ds_write_b32 v253, v107 offset:52400
	ds_write_b32 v253, v108 offset:50880
	ds_write_b32 v253, v109 offset:51408
	ds_write_b32 v253, v110 offset:51936
	ds_write_b32 v253, v111 offset:52464
	ds_write_b32 v253, v112 offset:59136
	ds_write_b32 v253, v113 offset:59664
	ds_write_b32 v253, v114 offset:60192
	ds_write_b32 v253, v115 offset:60720
	ds_write_b32 v253, v116 offset:59200
	ds_write_b32 v253, v117 offset:59728
	ds_write_b32 v253, v118 offset:60256
	ds_write_b32 v253, v119 offset:60784
	ds_write_b32 v253, v120 offset:59264
	ds_write_b32 v253, v121 offset:59792
	ds_write_b32 v253, v122 offset:60320
	ds_write_b32 v253, v123 offset:60848
	ds_write_b32 v253, v124 offset:59328
	ds_write_b32 v253, v125 offset:59856
	ds_write_b32 v253, v126 offset:60384
	ds_write_b32 v253, v127 offset:60912

.LBB0_955:
	s_lshr_b32 s10, s19, 4
	s_and_b32 s10, s10, 12
	s_bfe_u32 s28, s19, 0x20001
	s_or_b32 s10, s10, s20
	s_lshl_b32 s14, s28, 4
	s_and_b32 s26, s19, 1
	s_or_b32 s27, s14, s10
	s_lshl_b32 s14, s27, 9
	s_lshl_b32 s15, s26, 8
	s_or_b32 s14, s14, s15
	v_or_b32_e32 v0, s14, v146
	v_lshlrev_b32_e32 v0, 2, v0
	global_load_dword v2, v0, s[2:3]
	global_load_dword v4, v0, s[2:3] offset:256
	global_load_dword v10, v0, s[2:3] offset:512
	global_load_dword v11, v0, s[2:3] offset:768
	s_lshl_b32 s44, s28, 22
	v_readfirstlane_b32 s30, v148
	s_bfe_u32 s29, s19, 0x30003
	v_readfirstlane_b32 s31, v154
	s_mov_b32 m0, s30
	v_readfirstlane_b32 s34, v155
	s_or_b32 s28, s29, s21
	s_waitcnt vmcnt(0)
	s_barrier
	v_readfirstlane_b32 s35, v156
	s_lshl_b32 s29, s28, 17
	s_lshl_b32 s10, s10, 21
	v_readfirstlane_b32 s36, v157
	s_or_b32 s10, s10, s29
	v_readfirstlane_b32 s37, v158
	v_lshl_add_u64 v[134:135], v[130:131], 0, s[10:11]
	v_mov_b32_e32 v1, v129
	v_readfirstlane_b32 s38, v159
	v_lshl_add_u64 v[136:137], v[132:133], 0, s[10:11]
	v_mov_b32_e32 v3, v129
	v_readfirstlane_b32 s39, v160
	v_mov_b32_e32 v5, v129
	v_readfirstlane_b32 s40, v161
	v_readfirstlane_b32 s41, v162
	v_readfirstlane_b32 s42, v163
	v_readfirstlane_b32 s43, v164
	v_lshl_add_u64 v[6:7], v[134:135], 0, 64
	v_lshl_add_u64 v[8:9], v[136:137], 0, 64
	s_mov_b32 s14, s11
	s_mov_b32 s15, 2
	s_mov_b32 s29, s11
	v_mov_b32_e32 v16, 0
	v_mov_b32_e32 v17, v129
	v_mov_b32_e32 v18, v129
	v_mov_b32_e32 v19, v129
	v_mov_b32_e32 v20, v129
	v_mov_b32_e32 v21, v129
	v_mov_b32_e32 v22, v129
	v_mov_b32_e32 v23, v129
	v_mov_b32_e32 v24, v129
	v_mov_b32_e32 v25, v129
	v_mov_b32_e32 v26, v129
	v_mov_b32_e32 v27, v129
	v_mov_b32_e32 v28, v129
	v_mov_b32_e32 v29, v129
	v_mov_b32_e32 v30, v129
	v_mov_b32_e32 v31, v129
	v_mov_b32_e32 v32, 0
	v_mov_b32_e32 v33, v129
	v_mov_b32_e32 v34, v129
	v_mov_b32_e32 v35, v129
	v_mov_b32_e32 v36, v129
	v_mov_b32_e32 v37, v129
	v_mov_b32_e32 v38, v129
	v_mov_b32_e32 v39, v129
	v_mov_b32_e32 v40, v129
	v_mov_b32_e32 v41, v129
	v_mov_b32_e32 v42, v129
	v_mov_b32_e32 v43, v129
	v_mov_b32_e32 v44, v129
	v_mov_b32_e32 v45, v129
	v_mov_b32_e32 v46, v129
	v_mov_b32_e32 v47, v129
	v_mov_b32_e32 v48, 0
	v_mov_b32_e32 v49, v129
	v_mov_b32_e32 v50, v129
	v_mov_b32_e32 v51, v129
	v_mov_b32_e32 v52, v129
	v_mov_b32_e32 v53, v129
	v_mov_b32_e32 v54, v129
	v_mov_b32_e32 v55, v129
	v_mov_b32_e32 v56, v129
	v_mov_b32_e32 v57, v129
	v_mov_b32_e32 v58, v129
	s_waitcnt vmcnt(3)
	v_lshl_add_u32 v0, v2, 10, s44
	s_waitcnt vmcnt(2)
	v_lshl_add_u32 v2, v4, 10, s44
	v_or_b32_e32 v0, v0, v147
	s_waitcnt vmcnt(1)
	v_lshl_add_u32 v4, v10, 10, s44
	v_or_b32_e32 v2, v2, v147
	v_lshlrev_b32_e32 v128, 1, v0
	s_waitcnt vmcnt(0)
	v_lshl_add_u32 v10, v11, 10, s44
	v_or_b32_e32 v4, v4, v147
	v_lshlrev_b32_e32 v0, 1, v2
	s_nop 0
	s_mov_b32 m0, s31
	v_or_b32_e32 v10, v10, v147
	v_lshlrev_b32_e32 v2, 1, v4
	s_nop 0
	s_mov_b32 m0, s34
	v_lshlrev_b32_e32 v4, 1, v10
	s_nop 0
	s_mov_b32 m0, s35
	v_lshl_add_u64 v[138:139], s[4:5], 0, v[128:129]
	s_nop 0
	s_mov_b32 m0, s36
	v_lshl_add_u64 v[140:141], s[4:5], 0, v[0:1]
	s_nop 0
	s_mov_b32 m0, s37
	v_lshl_add_u64 v[0:1], v[138:139], 0, 64
	s_nop 0
	s_mov_b32 m0, s38
	v_lshl_add_u64 v[142:143], s[4:5], 0, v[2:3]
	v_lshl_add_u64 v[10:11], v[140:141], 0, 64
	s_nop 0
	s_mov_b32 m0, s39
	v_lshl_add_u64 v[144:145], s[4:5], 0, v[4:5]
	v_lshl_add_u64 v[12:13], v[142:143], 0, 64
	s_nop 0
	s_mov_b32 m0, s40
	v_lshl_add_u64 v[14:15], v[144:145], 0, 64
	s_nop 0
	s_mov_b32 m0, s41
	v_mov_b32_e32 v0, 0
	s_nop 0
	s_mov_b32 m0, s42
	v_mov_b32_e32 v1, v129
	s_nop 0
	s_mov_b32 m0, s43
	v_mov_b32_e32 v2, v129
	s_nop 0
	v_mov_b32_e32 v4, v129
	v_mov_b32_e32 v6, v129
	v_mov_b32_e32 v7, v129
	v_mov_b32_e32 v8, v129
	v_mov_b32_e32 v9, v129
	v_mov_b32_e32 v10, v129
	v_mov_b32_e32 v11, v129
	v_mov_b32_e32 v12, v129
	v_mov_b32_e32 v13, v129
	v_mov_b32_e32 v14, v129
	v_mov_b32_e32 v15, v129
	v_mov_b32_e32 v59, v129
	v_mov_b32_e32 v60, v129
	v_mov_b32_e32 v61, v129
	v_mov_b32_e32 v62, v129
	v_mov_b32_e32 v63, v129
	v_mov_b32_e32 v64, 0
	v_mov_b32_e32 v65, v129
	v_mov_b32_e32 v66, v129
	v_mov_b32_e32 v67, v129
	v_mov_b32_e32 v68, v129
	v_mov_b32_e32 v69, v129
	v_mov_b32_e32 v70, v129
	v_mov_b32_e32 v71, v129
	v_mov_b32_e32 v72, v129
	v_mov_b32_e32 v73, v129
	v_mov_b32_e32 v74, v129
	v_mov_b32_e32 v75, v129
	v_mov_b32_e32 v76, v129
	v_mov_b32_e32 v77, v129
	v_mov_b32_e32 v78, v129
	v_mov_b32_e32 v79, v129
	v_mov_b32_e32 v80, 0
	v_mov_b32_e32 v81, v129
	v_mov_b32_e32 v82, v129
	v_mov_b32_e32 v83, v129
	v_mov_b32_e32 v84, v129
	v_mov_b32_e32 v85, v129
	v_mov_b32_e32 v86, v129
	v_mov_b32_e32 v87, v129
	v_mov_b32_e32 v88, v129
	v_mov_b32_e32 v89, v129
	v_mov_b32_e32 v90, v129
	v_mov_b32_e32 v91, v129
	v_mov_b32_e32 v92, v129
	v_mov_b32_e32 v93, v129
	v_mov_b32_e32 v94, v129
	v_mov_b32_e32 v95, v129
	v_mov_b32_e32 v96, 0
	v_mov_b32_e32 v97, v129
	v_mov_b32_e32 v98, v129
	v_mov_b32_e32 v99, v129
	v_mov_b32_e32 v100, v129
	v_mov_b32_e32 v101, v129
	v_mov_b32_e32 v102, v129
	v_mov_b32_e32 v103, v129
	v_mov_b32_e32 v104, v129
	v_mov_b32_e32 v105, v129
	v_mov_b32_e32 v106, v129
	v_mov_b32_e32 v107, v129
	v_mov_b32_e32 v108, v129
	v_mov_b32_e32 v109, v129
	v_mov_b32_e32 v110, v129
	v_mov_b32_e32 v111, v129
	v_mov_b32_e32 v112, 0
	v_mov_b32_e32 v113, v129
	v_mov_b32_e32 v114, v129
	v_mov_b32_e32 v115, v129
	v_mov_b32_e32 v116, v129
	v_mov_b32_e32 v117, v129
	v_mov_b32_e32 v118, v129
	v_mov_b32_e32 v119, v129
	v_mov_b32_e32 v120, v129
	v_mov_b32_e32 v121, v129
	v_mov_b32_e32 v122, v129
	v_mov_b32_e32 v123, v129
	v_mov_b32_e32 v124, v129
	v_mov_b32_e32 v125, v129
	v_mov_b32_e32 v126, v129
	v_mov_b32_e32 v127, v129
	s_mov_b64 s[54:55], 0x80
	v_lshrrev_b32_e32 v170, 6, v180
	v_lshlrev_b32_e32 v176, 11, v170
	v_and_b32_e32 v166, 63, v180
	v_readfirstlane_b32 s53, v176
	v_lshrrev_b32_e32 v167, 4, v166
	v_bfe_u32 v168, v166, 1, 3
	v_xor_b32_e32 v168, v167, v168
	v_and_b32_e32 v169, 31, v166
	v_lshlrev_b32_e32 v169, 7, v169
	v_lshrrev_b32_e32 v169, 3, v166
	v_lshlrev_b32_e32 v176, 4, v169
	v_add_u32_e32 v177, 0x80, v176
	v_and_b32_e32 v169, 7, v166
	v_lshrrev_b32_e32 v167, 4, v166
	v_xor_b32_e32 v167, v169, v167
	v_lshrrev_b32_e32 v169, 5, v166
	v_sub_u32_e32 v182, v167, v169
	v_xor_b32_e32 v167, 4, v167
	v_add_u32_e32 v169, 2, v169
	v_sub_u32_e32 v184, v167, v169
	v_lshlrev_b32_e32 v182, 4, v182
	v_ashrrev_i32_e32 v183, 31, v182
	v_lshlrev_b32_e32 v184, 4, v184
	v_ashrrev_i32_e32 v185, 31, v184
	ds_bpermute_b32 v242, v176, v134
	ds_bpermute_b32 v243, v176, v135
	ds_bpermute_b32 v244, v177, v134
	ds_bpermute_b32 v245, v177, v135
	ds_bpermute_b32 v246, v176, v136
	ds_bpermute_b32 v247, v176, v137
	ds_bpermute_b32 v248, v177, v136
	ds_bpermute_b32 v249, v177, v137
	s_waitcnt lgkmcnt(0)
	ds_bpermute_b32 v178, v176, v138
	ds_bpermute_b32 v179, v176, v139
	ds_bpermute_b32 v232, v177, v138
	ds_bpermute_b32 v233, v177, v139
	ds_bpermute_b32 v234, v176, v140
	ds_bpermute_b32 v235, v176, v141
	ds_bpermute_b32 v236, v177, v140
	ds_bpermute_b32 v237, v177, v141
	ds_bpermute_b32 v238, v176, v142
	ds_bpermute_b32 v239, v176, v143
	ds_bpermute_b32 v240, v177, v142
	ds_bpermute_b32 v241, v177, v143
	ds_bpermute_b32 v134, v176, v144
	ds_bpermute_b32 v135, v176, v145
	ds_bpermute_b32 v136, v177, v144
	ds_bpermute_b32 v137, v177, v145
	s_waitcnt lgkmcnt(0)
	v_and_b32_e32 v169, 15, v166
	v_lshlrev_b32_e32 v169, 7, v169
	v_lshrrev_b32_e32 v167, 1, v170
	v_lshl_add_u32 v138, v167, 14, v169
	v_and_b32_e32 v167, 1, v170
	v_lshl_add_u32 v142, v167, 13, v169
	v_add_u32_e32 v142, 0x10000, v142
	v_xor_b32_e32 v169, 4, v168
	v_lshl_add_u32 v139, v169, 4, v138
	v_lshl_add_u32 v143, v169, 4, v142
	v_xor_b32_e32 v169, 0, v168
	v_lshl_add_u32 v138, v169, 4, v138
	v_lshl_add_u32 v142, v169, 4, v142
	v_lshl_add_u64 v[178:179], v[178:179], 0, v[182:183]
	v_lshl_add_u64 v[232:233], v[232:233], 0, v[184:185]
	v_lshl_add_u64 v[234:235], v[234:235], 0, v[182:183]
	v_lshl_add_u64 v[236:237], v[236:237], 0, v[184:185]
	v_lshl_add_u64 v[238:239], v[238:239], 0, v[182:183]
	v_lshl_add_u64 v[240:241], v[240:241], 0, v[184:185]
	v_lshl_add_u64 v[134:135], v[134:135], 0, v[182:183]
	v_lshl_add_u64 v[136:137], v[136:137], 0, v[184:185]
	v_lshl_add_u64 v[242:243], v[242:243], 0, v[182:183]
	v_lshl_add_u64 v[244:245], v[244:245], 0, v[184:185]
	v_lshl_add_u64 v[246:247], v[246:247], 0, v[182:183]
	v_lshl_add_u64 v[248:249], v[248:249], 0, v[184:185]
	s_mov_b32 s58, s53
	s_add_i32 m0, s58, 0x0
	s_nop 0
	global_load_lds_dwordx4 v[178:179], off
	s_add_i32 m0, s58, 0x400
	v_lshl_add_u64 v[178:179], v[178:179], 0, s[54:55]
	global_load_lds_dwordx4 v[232:233], off
	s_add_i32 m0, s58, 0x2000
	v_lshl_add_u64 v[232:233], v[232:233], 0, s[54:55]
	global_load_lds_dwordx4 v[234:235], off
	s_add_i32 m0, s58, 0x2400
	v_lshl_add_u64 v[234:235], v[234:235], 0, s[54:55]
	global_load_lds_dwordx4 v[236:237], off
	s_add_i32 m0, s58, 0x4000
	v_lshl_add_u64 v[236:237], v[236:237], 0, s[54:55]
	global_load_lds_dwordx4 v[238:239], off
	s_add_i32 m0, s58, 0x4400
	v_lshl_add_u64 v[238:239], v[238:239], 0, s[54:55]
	global_load_lds_dwordx4 v[240:241], off
	s_add_i32 m0, s58, 0x6000
	v_lshl_add_u64 v[240:241], v[240:241], 0, s[54:55]
	global_load_lds_dwordx4 v[134:135], off
	s_add_i32 m0, s58, 0x6400
	v_lshl_add_u64 v[134:135], v[134:135], 0, s[54:55]
	global_load_lds_dwordx4 v[136:137], off
	v_lshl_add_u64 v[136:137], v[136:137], 0, s[54:55]
	s_add_i32 s58, s53, 0x10000
	s_add_i32 m0, s58, 0x0
	s_nop 0
	global_load_lds_dwordx4 v[242:243], off
	s_add_i32 m0, s58, 0x400
	v_lshl_add_u64 v[242:243], v[242:243], 0, s[54:55]
	global_load_lds_dwordx4 v[244:245], off
	s_add_i32 m0, s58, 0x2000
	v_lshl_add_u64 v[244:245], v[244:245], 0, s[54:55]
	global_load_lds_dwordx4 v[246:247], off
	s_add_i32 m0, s58, 0x2400
	v_lshl_add_u64 v[246:247], v[246:247], 0, s[54:55]
	global_load_lds_dwordx4 v[248:249], off
	v_lshl_add_u64 v[248:249], v[248:249], 0, s[54:55]
	s_mov_b32 s14, 0
	s_mov_b32 s15, 0
	s_setprio 1

.Lg_ph8_noB:
	s_setprio 2
	s_waitcnt lgkmcnt(3)
	v_mfma_f32_16x16x32_bf16 v[0:3], v[166:169], v[190:193], v[0:3]
	v_mfma_f32_16x16x32_bf16 v[4:7], v[166:169], v[194:197], v[4:7]
	v_mfma_f32_16x16x32_bf16 v[8:11], v[166:169], v[198:201], v[8:11]
	v_mfma_f32_16x16x32_bf16 v[12:15], v[166:169], v[202:205], v[12:15]
	ds_read_b128 v[166:169], v138 offset:8192
	s_waitcnt lgkmcnt(3)
	v_mfma_f32_16x16x32_bf16 v[16:19], v[170:173], v[190:193], v[16:19]
	v_mfma_f32_16x16x32_bf16 v[20:23], v[170:173], v[194:197], v[20:23]
	v_mfma_f32_16x16x32_bf16 v[24:27], v[170:173], v[198:201], v[24:27]
	v_mfma_f32_16x16x32_bf16 v[28:31], v[170:173], v[202:205], v[28:31]
	ds_read_b128 v[170:173], v138 offset:10240
	s_waitcnt lgkmcnt(3)
	v_mfma_f32_16x16x32_bf16 v[32:35], v[174:177], v[190:193], v[32:35]
	v_mfma_f32_16x16x32_bf16 v[36:39], v[174:177], v[194:197], v[36:39]
	v_mfma_f32_16x16x32_bf16 v[40:43], v[174:177], v[198:201], v[40:43]
	v_mfma_f32_16x16x32_bf16 v[44:47], v[174:177], v[202:205], v[44:47]
	ds_read_b128 v[174:177], v138 offset:12288
	s_waitcnt lgkmcnt(3)
	v_mfma_f32_16x16x32_bf16 v[48:51], v[182:185], v[190:193], v[48:51]
	v_mfma_f32_16x16x32_bf16 v[52:55], v[182:185], v[194:197], v[52:55]
	v_mfma_f32_16x16x32_bf16 v[56:59], v[182:185], v[198:201], v[56:59]
	v_mfma_f32_16x16x32_bf16 v[60:63], v[182:185], v[202:205], v[60:63]
	ds_read_b128 v[182:185], v138 offset:14336
	s_waitcnt lgkmcnt(3)
	v_mfma_f32_16x16x32_bf16 v[64:67], v[166:169], v[190:193], v[64:67]
	v_mfma_f32_16x16x32_bf16 v[68:71], v[166:169], v[194:197], v[68:71]
	v_mfma_f32_16x16x32_bf16 v[72:75], v[166:169], v[198:201], v[72:75]
	v_mfma_f32_16x16x32_bf16 v[76:79], v[166:169], v[202:205], v[76:79]
	ds_read_b128 v[166:169], v139
	s_waitcnt lgkmcnt(3)
	v_mfma_f32_16x16x32_bf16 v[80:83], v[170:173], v[190:193], v[80:83]
	v_mfma_f32_16x16x32_bf16 v[84:87], v[170:173], v[194:197], v[84:87]
	v_mfma_f32_16x16x32_bf16 v[88:91], v[170:173], v[198:201], v[88:91]
	v_mfma_f32_16x16x32_bf16 v[92:95], v[170:173], v[202:205], v[92:95]
	ds_read_b128 v[170:173], v139 offset:2048
	s_waitcnt lgkmcnt(3)
	v_mfma_f32_16x16x32_bf16 v[96:99], v[174:177], v[190:193], v[96:99]
	v_mfma_f32_16x16x32_bf16 v[100:103], v[174:177], v[194:197], v[100:103]
	v_mfma_f32_16x16x32_bf16 v[104:107], v[174:177], v[198:201], v[104:107]
	v_mfma_f32_16x16x32_bf16 v[108:111], v[174:177], v[202:205], v[108:111]
	ds_read_b128 v[174:177], v139 offset:4096
	s_waitcnt lgkmcnt(3)
	v_mfma_f32_16x16x32_bf16 v[112:115], v[182:185], v[190:193], v[112:115]
	v_mfma_f32_16x16x32_bf16 v[116:119], v[182:185], v[194:197], v[116:119]
	v_mfma_f32_16x16x32_bf16 v[120:123], v[182:185], v[198:201], v[120:123]
	v_mfma_f32_16x16x32_bf16 v[124:127], v[182:185], v[202:205], v[124:127]
	ds_read_b128 v[182:185], v139 offset:6144
	s_waitcnt lgkmcnt(3)
	v_mfma_f32_16x16x32_bf16 v[0:3], v[166:169], v[206:209], v[0:3]
	v_mfma_f32_16x16x32_bf16 v[4:7], v[166:169], v[220:223], v[4:7]
	v_mfma_f32_16x16x32_bf16 v[8:11], v[166:169], v[224:227], v[8:11]
	v_mfma_f32_16x16x32_bf16 v[12:15], v[166:169], v[228:231], v[12:15]
	ds_read_b128 v[166:169], v139 offset:8192
	s_waitcnt lgkmcnt(3)
	v_mfma_f32_16x16x32_bf16 v[16:19], v[170:173], v[206:209], v[16:19]
	v_mfma_f32_16x16x32_bf16 v[20:23], v[170:173], v[220:223], v[20:23]
	v_mfma_f32_16x16x32_bf16 v[24:27], v[170:173], v[224:227], v[24:27]
	v_mfma_f32_16x16x32_bf16 v[28:31], v[170:173], v[228:231], v[28:31]
	ds_read_b128 v[170:173], v139 offset:10240
	s_waitcnt lgkmcnt(3)
	v_mfma_f32_16x16x32_bf16 v[32:35], v[174:177], v[206:209], v[32:35]
	v_mfma_f32_16x16x32_bf16 v[36:39], v[174:177], v[220:223], v[36:39]
	v_mfma_f32_16x16x32_bf16 v[40:43], v[174:177], v[224:227], v[40:43]
	v_mfma_f32_16x16x32_bf16 v[44:47], v[174:177], v[228:231], v[44:47]
	ds_read_b128 v[174:177], v139 offset:12288
	s_waitcnt lgkmcnt(3)
	v_mfma_f32_16x16x32_bf16 v[48:51], v[182:185], v[206:209], v[48:51]
	v_mfma_f32_16x16x32_bf16 v[52:55], v[182:185], v[220:223], v[52:55]
	v_mfma_f32_16x16x32_bf16 v[56:59], v[182:185], v[224:227], v[56:59]
	v_mfma_f32_16x16x32_bf16 v[60:63], v[182:185], v[228:231], v[60:63]
	ds_read_b128 v[182:185], v139 offset:14336
	s_waitcnt lgkmcnt(3)
	v_mfma_f32_16x16x32_bf16 v[64:67], v[166:169], v[206:209], v[64:67]
	v_mfma_f32_16x16x32_bf16 v[68:71], v[166:169], v[220:223], v[68:71]
	v_mfma_f32_16x16x32_bf16 v[72:75], v[166:169], v[224:227], v[72:75]
	v_mfma_f32_16x16x32_bf16 v[76:79], v[166:169], v[228:231], v[76:79]
	s_waitcnt lgkmcnt(2)
	v_mfma_f32_16x16x32_bf16 v[80:83], v[170:173], v[206:209], v[80:83]
	v_mfma_f32_16x16x32_bf16 v[84:87], v[170:173], v[220:223], v[84:87]
	v_mfma_f32_16x16x32_bf16 v[88:91], v[170:173], v[224:227], v[88:91]
	v_mfma_f32_16x16x32_bf16 v[92:95], v[170:173], v[228:231], v[92:95]
	s_waitcnt lgkmcnt(1)
	v_mfma_f32_16x16x32_bf16 v[96:99], v[174:177], v[206:209], v[96:99]
	v_mfma_f32_16x16x32_bf16 v[100:103], v[174:177], v[220:223], v[100:103]
	v_mfma_f32_16x16x32_bf16 v[104:107], v[174:177], v[224:227], v[104:107]
	v_mfma_f32_16x16x32_bf16 v[108:111], v[174:177], v[228:231], v[108:111]
	s_waitcnt lgkmcnt(0)
	v_mfma_f32_16x16x32_bf16 v[112:115], v[182:185], v[206:209], v[112:115]
	v_mfma_f32_16x16x32_bf16 v[116:119], v[182:185], v[220:223], v[116:119]
	v_mfma_f32_16x16x32_bf16 v[120:123], v[182:185], v[224:227], v[120:123]
	v_mfma_f32_16x16x32_bf16 v[124:127], v[182:185], v[228:231], v[124:127]
	s_setprio 1
	v_xor_b32_e32 v138, 0x8000, v138
	v_xor_b32_e32 v139, 0x8000, v139
	s_xor_b32 s15, s15, 0x8000
	s_add_i32 s14, s14, 1
	s_cmp_eq_u32 s14, 16
	s_cbranch_scc0 .Lg_ph8_top
	s_setprio 0
	s_waitcnt vmcnt(0)
	v_mov_b32_e32 v128, v180
	v_add_u32_e32 v193, 0x400, v153
	v_add_u32_e32 v192, 0x1000, v153
	v_add_u32_e32 v191, 0x1400, v153
	v_add_u32_e32 v190, 0x2000, v153
	v_add_u32_e32 v183, 0x2400, v153
	v_add_u32_e32 v184, 0x3000, v153
	v_add_u32_e32 v185, 0x3200, v153
	v_add_u32_e32 v186, 0x3400, v153
	v_add_u32_e32 v187, 0x3600, v153
	v_add_u32_e32 v189, 0x4000, v153
	v_add_u32_e32 v179, 0x4400, v153
	v_add_u32_e32 v181, 0x4800, v153
	v_add_u32_e32 v182, 0x5000, v153
	v_add_u32_e32 v176, 0x5400, v153
	v_add_u32_e32 v177, 0x5800, v153
	v_add_u32_e32 v178, 0x6000, v153
	v_add_u32_e32 v170, 0x6400, v153
	v_add_u32_e32 v171, 0x6800, v153
	v_add_u32_e32 v172, 0x7200, v153
	v_add_u32_e32 v173, 0x7400, v153
	v_add_u32_e32 v174, 0x7600, v153
	v_add_u32_e32 v175, 0x7800, v153
	v_add_u32_e32 v169, 0x8400, v153
	v_add_u32_e32 v168, 0x8800, v153
	v_add_u32_e32 v167, 0x9400, v153
	v_add_u32_e32 v166, 0x9800, v153
	v_add_u32_e32 v145, 0xa400, v153
	v_add_u32_e32 v140, 0xa800, v153
	v_add_u32_e32 v141, 0xb400, v153
	v_add_u32_e32 v142, 0xb600, v153
	v_add_u32_e32 v143, 0xb800, v153
	v_add_u32_e32 v144, 0xba00, v153
	s_waitcnt vmcnt(0)
	s_barrier
	s_and_saveexec_b64 s[14:15], s[6:7]
	s_cbranch_execz .LBB0_959
	v_and_b32_e32 v254, 63, v180
	v_lshrrev_b32_e32 v253, 4, v254
	v_mul_u32_u24_e32 v253, 0x840, v253
	v_and_b32_e32 v254, 15, v254
	v_lshl_add_u32 v253, v254, 2, v253
	v_and_b32_e32 v254, 64, v180
	v_lshl_add_u32 v253, v254, 2, v253
	ds_write_b32 v253, v0 offset:0
	ds_write_b32 v253, v1 offset:528
	ds_write_b32 v253, v2 offset:1056
	ds_write_b32 v253, v3 offset:1584
	ds_write_b32 v253, v4 offset:64
	ds_write_b32 v253, v5 offset:592
	ds_write_b32 v253, v6 offset:1120
	ds_write_b32 v253, v7 offset:1648
	ds_write_b32 v253, v8 offset:128
	ds_write_b32 v253, v9 offset:656
	ds_write_b32 v253, v10 offset:1184
	ds_write_b32 v253, v11 offset:1712
	ds_write_b32 v253, v12 offset:192
	ds_write_b32 v253, v13 offset:720
	ds_write_b32 v253, v14 offset:1248
	ds_write_b32 v253, v15 offset:1776
	ds_write_b32 v253, v16 offset:8448
	ds_write_b32 v253, v17 offset:8976
	ds_write_b32 v253, v18 offset:9504
	ds_write_b32 v253, v19 offset:10032
	ds_write_b32 v253, v20 offset:8512
	ds_write_b32 v253, v21 offset:9040
	ds_write_b32 v253, v22 offset:9568
	ds_write_b32 v253, v23 offset:10096
	ds_write_b32 v253, v24 offset:8576
	ds_write_b32 v253, v25 offset:9104
	ds_write_b32 v253, v26 offset:9632
	ds_write_b32 v253, v27 offset:10160
	ds_write_b32 v253, v28 offset:8640
	ds_write_b32 v253, v29 offset:9168
	ds_write_b32 v253, v30 offset:9696
	ds_write_b32 v253, v31 offset:10224
	ds_write_b32 v253, v32 offset:16896
	ds_write_b32 v253, v33 offset:17424
	ds_write_b32 v253, v34 offset:17952
	ds_write_b32 v253, v35 offset:18480
	ds_write_b32 v253, v36 offset:16960
	ds_write_b32 v253, v37 offset:17488
	ds_write_b32 v253, v38 offset:18016
	ds_write_b32 v253, v39 offset:18544
	ds_write_b32 v253, v40 offset:17024
	ds_write_b32 v253, v41 offset:17552
	ds_write_b32 v253, v42 offset:18080
	ds_write_b32 v253, v43 offset:18608
	ds_write_b32 v253, v44 offset:17088
	ds_write_b32 v253, v45 offset:17616
	ds_write_b32 v253, v46 offset:18144
	ds_write_b32 v253, v47 offset:18672
	ds_write_b32 v253, v48 offset:25344
	ds_write_b32 v253, v49 offset:25872
	ds_write_b32 v253, v50 offset:26400
	ds_write_b32 v253, v51 offset:26928
	ds_write_b32 v253, v52 offset:25408
	ds_write_b32 v253, v53 offset:25936
	ds_write_b32 v253, v54 offset:26464
	ds_write_b32 v253, v55 offset:26992
	ds_write_b32 v253, v56 offset:25472
	ds_write_b32 v253, v57 offset:26000
	ds_write_b32 v253, v58 offset:26528
	ds_write_b32 v253, v59 offset:27056
	ds_write_b32 v253, v60 offset:25536
	ds_write_b32 v253, v61 offset:26064
	ds_write_b32 v253, v62 offset:26592
	ds_write_b32 v253, v63 offset:27120
	ds_write_b32 v253, v64 offset:33792
	ds_write_b32 v253, v65 offset:34320
	ds_write_b32 v253, v66 offset:34848
	ds_write_b32 v253, v67 offset:35376
	ds_write_b32 v253, v68 offset:33856
	ds_write_b32 v253, v69 offset:34384
	ds_write_b32 v253, v70 offset:34912
	ds_write_b32 v253, v71 offset:35440
	ds_write_b32 v253, v72 offset:33920
	ds_write_b32 v253, v73 offset:34448
	ds_write_b32 v253, v74 offset:34976
	ds_write_b32 v253, v75 offset:35504
	ds_write_b32 v253, v76 offset:33984
	ds_write_b32 v253, v77 offset:34512
	ds_write_b32 v253, v78 offset:35040
	ds_write_b32 v253, v79 offset:35568
	ds_write_b32 v253, v80 offset:42240
	ds_write_b32 v253, v81 offset:42768
	ds_write_b32 v253, v82 offset:43296
	ds_write_b32 v253, v83 offset:43824
	ds_write_b32 v253, v84 offset:42304
	ds_write_b32 v253, v85 offset:42832
	ds_write_b32 v253, v86 offset:43360
	ds_write_b32 v253, v87 offset:43888
	ds_write_b32 v253, v88 offset:42368
	ds_write_b32 v253, v89 offset:42896
	ds_write_b32 v253, v90 offset:43424
	ds_write_b32 v253, v91 offset:43952
	ds_write_b32 v253, v92 offset:42432
	ds_write_b32 v253, v93 offset:42960
	ds_write_b32 v253, v94 offset:43488
	ds_write_b32 v253, v95 offset:44016
	ds_write_b32 v253, v96 offset:50688
	ds_write_b32 v253, v97 offset:51216
	ds_write_b32 v253, v98 offset:51744
	ds_write_b32 v253, v99 offset:52272
	ds_write_b32 v253, v100 offset:50752
	ds_write_b32 v253, v101 offset:51280
	ds_write_b32 v253, v102 offset:51808
	ds_write_b32 v253, v103 offset:52336
	ds_write_b32 v253, v104 offset:50816
	ds_write_b32 v253, v105 offset:51344
	ds_write_b32 v253, v106 offset:51872
	ds_write_b32 v253, v107 offset:52400
	ds_write_b32 v253, v108 offset:50880
	ds_write_b32 v253, v109 offset:51408
	ds_write_b32 v253, v110 offset:51936
	ds_write_b32 v253, v111 offset:52464
	ds_write_b32 v253, v112 offset:59136
	ds_write_b32 v253, v113 offset:59664
	ds_write_b32 v253, v114 offset:60192
	ds_write_b32 v253, v115 offset:60720
	ds_write_b32 v253, v116 offset:59200
	ds_write_b32 v253, v117 offset:59728
	ds_write_b32 v253, v118 offset:60256
	ds_write_b32 v253, v119 offset:60784
	ds_write_b32 v253, v120 offset:59264
	ds_write_b32 v253, v121 offset:59792
	ds_write_b32 v253, v122 offset:60320
	ds_write_b32 v253, v123 offset:60848
	ds_write_b32 v253, v124 offset:59328
	ds_write_b32 v253, v125 offset:59856
	ds_write_b32 v253, v126 offset:60384
	ds_write_b32 v253, v127 offset:60912

.LBB0_1021:
	s_lshr_b32 s4, s26, 3
	s_and_b32 s4, s4, 8
	s_lshl_b32 s16, s26, 3
	s_or_b32 s4, s4, s24
	s_and_b32 s35, s26, 1
	s_and_b32 s16, s16, 48
	s_or_b32 s36, s4, s16
	s_lshl_b32 s18, s35, 8
	s_lshl_b32 s16, s26, 4
	s_lshl_b32 s19, s36, 9
	v_or_b32_e32 v0, s18, v129
	s_and_b32 s37, s16, 0x380
	v_or_b32_e32 v0, s19, v0
	s_lshl_b32 s16, s37, 11
	s_lshl_b32 s4, s4, 21
	v_lshlrev_b32_e32 v1, 10, v0
	s_or_b32 s4, s4, s16
	s_add_u32 s16, s28, s4
	v_or_b32_e32 v0, v1, v128
	v_readfirstlane_b32 s4, v152
	v_lshlrev_b32_e32 v130, 1, v0
	s_mov_b32 m0, s4
	v_readfirstlane_b32 s4, v161
	v_add_lshl_u32 v0, v1, v158, 1
	s_waitcnt vmcnt(0)
	s_barrier
	s_nop 0
	s_mov_b32 m0, s4
	v_readfirstlane_b32 s4, v162
	s_addc_u32 s17, s29, 0
	v_add_lshl_u32 v2, v1, v159, 1
	s_nop 0
	s_mov_b32 m0, s4
	v_readfirstlane_b32 s4, v163
	v_add_lshl_u32 v4, v1, v160, 1
	v_lshl_add_u64 v[6:7], s[16:17], 0, v[132:133]
	s_nop 0
	s_mov_b32 m0, s4
	v_readfirstlane_b32 s4, v164
	v_lshl_add_u64 v[136:137], v[6:7], 0, v[134:135]
	s_nop 0
	s_mov_b32 m0, s4
	v_readfirstlane_b32 s4, v165
	v_lshl_add_u64 v[138:139], s[2:3], 0, v[130:131]
	v_mov_b32_e32 v1, v131
	v_lshl_add_u64 v[146:147], v[136:137], 0, s[10:11]
	s_nop 0
	s_mov_b32 m0, s4
	v_readfirstlane_b32 s4, v166
	v_lshl_add_u64 v[140:141], s[2:3], 0, v[0:1]
	v_mov_b32_e32 v3, v131
	s_nop 0
	v_lshl_add_u64 v[0:1], v[138:139], 0, 64
	s_mov_b32 m0, s4
	v_readfirstlane_b32 s4, v167
	v_lshl_add_u64 v[142:143], s[2:3], 0, v[2:3]
	v_mov_b32_e32 v5, v131
	s_nop 0
	v_lshl_add_u64 v[0:1], v[140:141], 0, 64
	s_mov_b32 m0, s4
	v_readfirstlane_b32 s4, v168
	v_lshl_add_u64 v[144:145], s[2:3], 0, v[4:5]
	s_nop 0
	v_lshl_add_u64 v[0:1], v[142:143], 0, 64
	s_mov_b32 m0, s4
	v_readfirstlane_b32 s4, v169
	s_nop 0
	v_lshl_add_u64 v[0:1], v[144:145], 0, 64
	s_mov_b32 m0, s4
	v_readfirstlane_b32 s4, v170
	s_nop 0
	v_lshl_add_u64 v[0:1], v[136:137], 0, 64
	s_mov_b32 m0, s4
	v_readfirstlane_b32 s4, v171
	s_nop 0
	v_lshl_add_u64 v[0:1], v[136:137], 0, s[12:13]
	s_mov_b32 m0, s4
	s_mov_b32 s16, s5
	s_nop 0
	s_mov_b32 s17, 2
	s_mov_b32 s38, s5
	v_mov_b32_e32 v0, 0
	v_mov_b32_e32 v1, v131
	v_mov_b32_e32 v2, v131
	v_mov_b32_e32 v4, v131
	v_mov_b32_e32 v6, v131
	v_mov_b32_e32 v7, v131
	v_mov_b32_e32 v8, v131
	v_mov_b32_e32 v9, v131
	v_mov_b32_e32 v10, v131
	v_mov_b32_e32 v11, v131
	v_mov_b32_e32 v12, v131
	v_mov_b32_e32 v13, v131
	v_mov_b32_e32 v14, v131
	v_mov_b32_e32 v15, v131
	v_mov_b32_e32 v16, 0
	v_mov_b32_e32 v17, v131
	v_mov_b32_e32 v18, v131
	v_mov_b32_e32 v19, v131
	v_mov_b32_e32 v20, v131
	v_mov_b32_e32 v21, v131
	v_mov_b32_e32 v22, v131
	v_mov_b32_e32 v23, v131
	v_mov_b32_e32 v24, v131
	v_mov_b32_e32 v25, v131
	v_mov_b32_e32 v26, v131
	v_mov_b32_e32 v27, v131
	v_mov_b32_e32 v28, v131
	v_mov_b32_e32 v29, v131
	v_mov_b32_e32 v30, v131
	v_mov_b32_e32 v31, v131
	v_mov_b32_e32 v32, 0
	v_mov_b32_e32 v33, v131
	v_mov_b32_e32 v34, v131
	v_mov_b32_e32 v35, v131
	v_mov_b32_e32 v36, v131
	v_mov_b32_e32 v37, v131
	v_mov_b32_e32 v38, v131
	v_mov_b32_e32 v39, v131
	v_mov_b32_e32 v40, v131
	v_mov_b32_e32 v41, v131
	v_mov_b32_e32 v42, v131
	v_mov_b32_e32 v43, v131
	v_mov_b32_e32 v44, v131
	v_mov_b32_e32 v45, v131
	v_mov_b32_e32 v46, v131
	v_mov_b32_e32 v47, v131
	v_mov_b32_e32 v48, 0
	v_mov_b32_e32 v49, v131
	v_mov_b32_e32 v50, v131
	v_mov_b32_e32 v51, v131
	v_mov_b32_e32 v52, v131
	v_mov_b32_e32 v53, v131
	v_mov_b32_e32 v54, v131
	v_mov_b32_e32 v55, v131
	v_mov_b32_e32 v56, v131
	v_mov_b32_e32 v57, v131
	v_mov_b32_e32 v58, v131
	v_mov_b32_e32 v59, v131
	v_mov_b32_e32 v60, v131
	v_mov_b32_e32 v61, v131
	v_mov_b32_e32 v62, v131
	v_mov_b32_e32 v63, v131
	v_mov_b32_e32 v64, 0
	v_mov_b32_e32 v65, v131
	v_mov_b32_e32 v66, v131
	v_mov_b32_e32 v67, v131
	v_mov_b32_e32 v68, v131
	v_mov_b32_e32 v69, v131
	v_mov_b32_e32 v70, v131
	v_mov_b32_e32 v71, v131
	v_mov_b32_e32 v72, v131
	v_mov_b32_e32 v73, v131
	v_mov_b32_e32 v74, v131
	v_mov_b32_e32 v75, v131
	v_mov_b32_e32 v76, v131
	v_mov_b32_e32 v77, v131
	v_mov_b32_e32 v78, v131
	v_mov_b32_e32 v79, v131
	v_mov_b32_e32 v80, 0
	v_mov_b32_e32 v81, v131
	v_mov_b32_e32 v82, v131
	v_mov_b32_e32 v83, v131
	v_mov_b32_e32 v84, v131
	v_mov_b32_e32 v85, v131
	v_mov_b32_e32 v86, v131
	v_mov_b32_e32 v87, v131
	v_mov_b32_e32 v88, v131
	v_mov_b32_e32 v89, v131
	v_mov_b32_e32 v90, v131
	v_mov_b32_e32 v91, v131
	v_mov_b32_e32 v92, v131
	v_mov_b32_e32 v93, v131
	v_mov_b32_e32 v94, v131
	v_mov_b32_e32 v95, v131
	v_mov_b32_e32 v96, 0
	v_mov_b32_e32 v97, v131
	v_mov_b32_e32 v98, v131
	v_mov_b32_e32 v99, v131
	v_mov_b32_e32 v100, v131
	v_mov_b32_e32 v101, v131
	v_mov_b32_e32 v102, v131
	v_mov_b32_e32 v103, v131
	v_mov_b32_e32 v104, v131
	v_mov_b32_e32 v105, v131
	v_mov_b32_e32 v106, v131
	v_mov_b32_e32 v107, v131
	v_mov_b32_e32 v108, v131
	v_mov_b32_e32 v109, v131
	v_mov_b32_e32 v110, v131
	v_mov_b32_e32 v111, v131
	v_mov_b32_e32 v112, 0
	v_mov_b32_e32 v113, v131
	v_mov_b32_e32 v114, v131
	v_mov_b32_e32 v115, v131
	v_mov_b32_e32 v116, v131
	v_mov_b32_e32 v117, v131
	v_mov_b32_e32 v118, v131
	v_mov_b32_e32 v119, v131
	v_mov_b32_e32 v120, v131
	v_mov_b32_e32 v121, v131
	v_mov_b32_e32 v122, v131
	v_mov_b32_e32 v123, v131
	v_mov_b32_e32 v124, v131
	v_mov_b32_e32 v125, v131
	v_mov_b32_e32 v126, v131
	v_mov_b32_e32 v127, v131
	s_mov_b64 s[54:55], 0x80
	v_lshrrev_b32_e32 v174, 6, v180
	v_lshlrev_b32_e32 v184, 11, v174
	v_and_b32_e32 v148, 63, v180
	v_readfirstlane_b32 s53, v184
	v_lshrrev_b32_e32 v149, 4, v148
	v_bfe_u32 v150, v148, 1, 3
	v_xor_b32_e32 v150, v149, v150
	v_and_b32_e32 v151, 31, v148
	v_lshlrev_b32_e32 v151, 7, v151
	v_lshrrev_b32_e32 v151, 3, v148
	v_lshlrev_b32_e32 v184, 4, v151
	v_add_u32_e32 v185, 0x80, v184
	v_and_b32_e32 v151, 7, v148
	v_lshrrev_b32_e32 v149, 4, v148
	v_xor_b32_e32 v149, v151, v149
	v_lshrrev_b32_e32 v151, 5, v148
	v_sub_u32_e32 v190, v149, v151
	v_xor_b32_e32 v149, 4, v149
	v_add_u32_e32 v151, 2, v151
	v_sub_u32_e32 v192, v149, v151
	v_lshlrev_b32_e32 v190, 4, v190
	v_ashrrev_i32_e32 v191, 31, v190
	v_lshlrev_b32_e32 v192, 4, v192
	v_ashrrev_i32_e32 v193, 31, v192
	ds_bpermute_b32 v246, v184, v136
	ds_bpermute_b32 v247, v184, v137
	ds_bpermute_b32 v248, v185, v136
	ds_bpermute_b32 v249, v185, v137
	ds_bpermute_b32 v250, v184, v146
	ds_bpermute_b32 v251, v184, v147
	ds_bpermute_b32 v252, v185, v146
	ds_bpermute_b32 v253, v185, v147
	s_waitcnt lgkmcnt(0)
	ds_bpermute_b32 v178, v184, v138
	ds_bpermute_b32 v179, v184, v139
	ds_bpermute_b32 v186, v185, v138
	ds_bpermute_b32 v187, v185, v139
	ds_bpermute_b32 v238, v184, v140
	ds_bpermute_b32 v239, v184, v141
	ds_bpermute_b32 v240, v185, v140
	ds_bpermute_b32 v241, v185, v141
	ds_bpermute_b32 v242, v184, v142
	ds_bpermute_b32 v243, v184, v143
	ds_bpermute_b32 v244, v185, v142
	ds_bpermute_b32 v245, v185, v143
	ds_bpermute_b32 v136, v184, v144
	ds_bpermute_b32 v137, v184, v145
	ds_bpermute_b32 v146, v185, v144
	ds_bpermute_b32 v147, v185, v145
	s_waitcnt lgkmcnt(0)
	v_and_b32_e32 v151, 15, v148
	v_lshlrev_b32_e32 v151, 7, v151
	v_lshrrev_b32_e32 v149, 1, v174
	v_lshl_add_u32 v138, v149, 14, v151
	v_and_b32_e32 v149, 1, v174
	v_lshl_add_u32 v142, v149, 13, v151
	v_add_u32_e32 v142, 0x10000, v142
	v_xor_b32_e32 v151, 4, v150
	v_lshl_add_u32 v139, v151, 4, v138
	v_lshl_add_u32 v143, v151, 4, v142
	v_xor_b32_e32 v151, 0, v150
	v_lshl_add_u32 v138, v151, 4, v138
	v_lshl_add_u32 v142, v151, 4, v142
	v_lshl_add_u64 v[178:179], v[178:179], 0, v[190:191]
	v_lshl_add_u64 v[186:187], v[186:187], 0, v[192:193]
	v_lshl_add_u64 v[238:239], v[238:239], 0, v[190:191]
	v_lshl_add_u64 v[240:241], v[240:241], 0, v[192:193]
	v_lshl_add_u64 v[242:243], v[242:243], 0, v[190:191]
	v_lshl_add_u64 v[244:245], v[244:245], 0, v[192:193]
	v_lshl_add_u64 v[136:137], v[136:137], 0, v[190:191]
	v_lshl_add_u64 v[146:147], v[146:147], 0, v[192:193]
	v_lshl_add_u64 v[246:247], v[246:247], 0, v[190:191]
	v_lshl_add_u64 v[248:249], v[248:249], 0, v[192:193]
	v_lshl_add_u64 v[250:251], v[250:251], 0, v[190:191]
	v_lshl_add_u64 v[252:253], v[252:253], 0, v[192:193]
	s_mov_b32 s58, s53
	s_add_i32 m0, s58, 0x0
	s_nop 0
	global_load_lds_dwordx4 v[178:179], off
	s_add_i32 m0, s58, 0x400
	v_lshl_add_u64 v[178:179], v[178:179], 0, s[54:55]
	global_load_lds_dwordx4 v[186:187], off
	s_add_i32 m0, s58, 0x2000
	v_lshl_add_u64 v[186:187], v[186:187], 0, s[54:55]
	global_load_lds_dwordx4 v[238:239], off
	s_add_i32 m0, s58, 0x2400
	v_lshl_add_u64 v[238:239], v[238:239], 0, s[54:55]
	global_load_lds_dwordx4 v[240:241], off
	s_add_i32 m0, s58, 0x4000
	v_lshl_add_u64 v[240:241], v[240:241], 0, s[54:55]
	global_load_lds_dwordx4 v[242:243], off
	s_add_i32 m0, s58, 0x4400
	v_lshl_add_u64 v[242:243], v[242:243], 0, s[54:55]
	global_load_lds_dwordx4 v[244:245], off
	s_add_i32 m0, s58, 0x6000
	v_lshl_add_u64 v[244:245], v[244:245], 0, s[54:55]
	global_load_lds_dwordx4 v[136:137], off
	s_add_i32 m0, s58, 0x6400
	v_lshl_add_u64 v[136:137], v[136:137], 0, s[54:55]
	global_load_lds_dwordx4 v[146:147], off
	v_lshl_add_u64 v[146:147], v[146:147], 0, s[54:55]
	s_add_i32 s58, s53, 0x10000
	s_add_i32 m0, s58, 0x0
	s_nop 0
	global_load_lds_dwordx4 v[246:247], off
	s_add_i32 m0, s58, 0x400
	v_lshl_add_u64 v[246:247], v[246:247], 0, s[54:55]
	global_load_lds_dwordx4 v[248:249], off
	s_add_i32 m0, s58, 0x2000
	v_lshl_add_u64 v[248:249], v[248:249], 0, s[54:55]
	global_load_lds_dwordx4 v[250:251], off
	s_add_i32 m0, s58, 0x2400
	v_lshl_add_u64 v[250:251], v[250:251], 0, s[54:55]
	global_load_lds_dwordx4 v[252:253], off
	v_lshl_add_u64 v[252:253], v[252:253], 0, s[54:55]
	s_mov_b32 s16, 0
	s_mov_b32 s17, 0
	s_setprio 1

.Lg_ph9_noB:
	s_setprio 2
	s_waitcnt lgkmcnt(3)
	v_mfma_f32_16x16x32_bf16 v[0:3], v[148:151], v[194:197], v[0:3]
	v_mfma_f32_16x16x32_bf16 v[4:7], v[148:151], v[198:201], v[4:7]
	v_mfma_f32_16x16x32_bf16 v[8:11], v[148:151], v[202:205], v[8:11]
	v_mfma_f32_16x16x32_bf16 v[12:15], v[148:151], v[206:209], v[12:15]
	ds_read_b128 v[148:151], v138 offset:8192
	s_waitcnt lgkmcnt(3)
	v_mfma_f32_16x16x32_bf16 v[16:19], v[174:177], v[194:197], v[16:19]
	v_mfma_f32_16x16x32_bf16 v[20:23], v[174:177], v[198:201], v[20:23]
	v_mfma_f32_16x16x32_bf16 v[24:27], v[174:177], v[202:205], v[24:27]
	v_mfma_f32_16x16x32_bf16 v[28:31], v[174:177], v[206:209], v[28:31]
	ds_read_b128 v[174:177], v138 offset:10240
	s_waitcnt lgkmcnt(3)
	v_mfma_f32_16x16x32_bf16 v[32:35], v[182:185], v[194:197], v[32:35]
	v_mfma_f32_16x16x32_bf16 v[36:39], v[182:185], v[198:201], v[36:39]
	v_mfma_f32_16x16x32_bf16 v[40:43], v[182:185], v[202:205], v[40:43]
	v_mfma_f32_16x16x32_bf16 v[44:47], v[182:185], v[206:209], v[44:47]
	ds_read_b128 v[182:185], v138 offset:12288
	s_waitcnt lgkmcnt(3)
	v_mfma_f32_16x16x32_bf16 v[48:51], v[190:193], v[194:197], v[48:51]
	v_mfma_f32_16x16x32_bf16 v[52:55], v[190:193], v[198:201], v[52:55]
	v_mfma_f32_16x16x32_bf16 v[56:59], v[190:193], v[202:205], v[56:59]
	v_mfma_f32_16x16x32_bf16 v[60:63], v[190:193], v[206:209], v[60:63]
	ds_read_b128 v[190:193], v138 offset:14336
	s_waitcnt lgkmcnt(3)
	v_mfma_f32_16x16x32_bf16 v[64:67], v[148:151], v[194:197], v[64:67]
	v_mfma_f32_16x16x32_bf16 v[68:71], v[148:151], v[198:201], v[68:71]
	v_mfma_f32_16x16x32_bf16 v[72:75], v[148:151], v[202:205], v[72:75]
	v_mfma_f32_16x16x32_bf16 v[76:79], v[148:151], v[206:209], v[76:79]
	ds_read_b128 v[148:151], v139
	s_waitcnt lgkmcnt(3)
	v_mfma_f32_16x16x32_bf16 v[80:83], v[174:177], v[194:197], v[80:83]
	v_mfma_f32_16x16x32_bf16 v[84:87], v[174:177], v[198:201], v[84:87]
	v_mfma_f32_16x16x32_bf16 v[88:91], v[174:177], v[202:205], v[88:91]
	v_mfma_f32_16x16x32_bf16 v[92:95], v[174:177], v[206:209], v[92:95]
	ds_read_b128 v[174:177], v139 offset:2048
	s_waitcnt lgkmcnt(3)
	v_mfma_f32_16x16x32_bf16 v[96:99], v[182:185], v[194:197], v[96:99]
	v_mfma_f32_16x16x32_bf16 v[100:103], v[182:185], v[198:201], v[100:103]
	v_mfma_f32_16x16x32_bf16 v[104:107], v[182:185], v[202:205], v[104:107]
	v_mfma_f32_16x16x32_bf16 v[108:111], v[182:185], v[206:209], v[108:111]
	ds_read_b128 v[182:185], v139 offset:4096
	s_waitcnt lgkmcnt(3)
	v_mfma_f32_16x16x32_bf16 v[112:115], v[190:193], v[194:197], v[112:115]
	v_mfma_f32_16x16x32_bf16 v[116:119], v[190:193], v[198:201], v[116:119]
	v_mfma_f32_16x16x32_bf16 v[120:123], v[190:193], v[202:205], v[120:123]
	v_mfma_f32_16x16x32_bf16 v[124:127], v[190:193], v[206:209], v[124:127]
	ds_read_b128 v[190:193], v139 offset:6144
	s_waitcnt lgkmcnt(3)
	v_mfma_f32_16x16x32_bf16 v[0:3], v[148:151], v[214:217], v[0:3]
	v_mfma_f32_16x16x32_bf16 v[4:7], v[148:151], v[226:229], v[4:7]
	v_mfma_f32_16x16x32_bf16 v[8:11], v[148:151], v[230:233], v[8:11]
	v_mfma_f32_16x16x32_bf16 v[12:15], v[148:151], v[234:237], v[12:15]
	ds_read_b128 v[148:151], v139 offset:8192
	s_waitcnt lgkmcnt(3)
	v_mfma_f32_16x16x32_bf16 v[16:19], v[174:177], v[214:217], v[16:19]
	v_mfma_f32_16x16x32_bf16 v[20:23], v[174:177], v[226:229], v[20:23]
	v_mfma_f32_16x16x32_bf16 v[24:27], v[174:177], v[230:233], v[24:27]
	v_mfma_f32_16x16x32_bf16 v[28:31], v[174:177], v[234:237], v[28:31]
	ds_read_b128 v[174:177], v139 offset:10240
	s_waitcnt lgkmcnt(3)
	v_mfma_f32_16x16x32_bf16 v[32:35], v[182:185], v[214:217], v[32:35]
	v_mfma_f32_16x16x32_bf16 v[36:39], v[182:185], v[226:229], v[36:39]
	v_mfma_f32_16x16x32_bf16 v[40:43], v[182:185], v[230:233], v[40:43]
	v_mfma_f32_16x16x32_bf16 v[44:47], v[182:185], v[234:237], v[44:47]
	ds_read_b128 v[182:185], v139 offset:12288
	s_waitcnt lgkmcnt(3)
	v_mfma_f32_16x16x32_bf16 v[48:51], v[190:193], v[214:217], v[48:51]
	v_mfma_f32_16x16x32_bf16 v[52:55], v[190:193], v[226:229], v[52:55]
	v_mfma_f32_16x16x32_bf16 v[56:59], v[190:193], v[230:233], v[56:59]
	v_mfma_f32_16x16x32_bf16 v[60:63], v[190:193], v[234:237], v[60:63]
	ds_read_b128 v[190:193], v139 offset:14336
	s_waitcnt lgkmcnt(3)
	v_mfma_f32_16x16x32_bf16 v[64:67], v[148:151], v[214:217], v[64:67]
	v_mfma_f32_16x16x32_bf16 v[68:71], v[148:151], v[226:229], v[68:71]
	v_mfma_f32_16x16x32_bf16 v[72:75], v[148:151], v[230:233], v[72:75]
	v_mfma_f32_16x16x32_bf16 v[76:79], v[148:151], v[234:237], v[76:79]
	s_waitcnt lgkmcnt(2)
	v_mfma_f32_16x16x32_bf16 v[80:83], v[174:177], v[214:217], v[80:83]
	v_mfma_f32_16x16x32_bf16 v[84:87], v[174:177], v[226:229], v[84:87]
	v_mfma_f32_16x16x32_bf16 v[88:91], v[174:177], v[230:233], v[88:91]
	v_mfma_f32_16x16x32_bf16 v[92:95], v[174:177], v[234:237], v[92:95]
	s_waitcnt lgkmcnt(1)
	v_mfma_f32_16x16x32_bf16 v[96:99], v[182:185], v[214:217], v[96:99]
	v_mfma_f32_16x16x32_bf16 v[100:103], v[182:185], v[226:229], v[100:103]
	v_mfma_f32_16x16x32_bf16 v[104:107], v[182:185], v[230:233], v[104:107]
	v_mfma_f32_16x16x32_bf16 v[108:111], v[182:185], v[234:237], v[108:111]
	s_waitcnt lgkmcnt(0)
	v_mfma_f32_16x16x32_bf16 v[112:115], v[190:193], v[214:217], v[112:115]
	v_mfma_f32_16x16x32_bf16 v[116:119], v[190:193], v[226:229], v[116:119]
	v_mfma_f32_16x16x32_bf16 v[120:123], v[190:193], v[230:233], v[120:123]
	v_mfma_f32_16x16x32_bf16 v[124:127], v[190:193], v[234:237], v[124:127]
	s_setprio 1
	v_xor_b32_e32 v138, 0x8000, v138
	v_xor_b32_e32 v139, 0x8000, v139
	s_xor_b32 s17, s17, 0x8000
	s_add_i32 s16, s16, 1
	s_cmp_eq_u32 s16, 16
	s_cbranch_scc0 .Lg_ph9_top
	s_setprio 0
	s_waitcnt vmcnt(0)
	v_mov_b32_e32 v146, v180
	v_add_u32_e32 v209, 0x400, v157
	v_add_u32_e32 v208, 0x1000, v157
	v_add_u32_e32 v207, 0x1400, v157
	v_add_u32_e32 v206, 0x2000, v157
	v_add_u32_e32 v200, 0x2400, v157
	v_add_u32_e32 v201, 0x3000, v157
	v_add_u32_e32 v202, 0x3200, v157
	v_add_u32_e32 v203, 0x3400, v157
	v_add_u32_e32 v204, 0x3600, v157
	v_add_u32_e32 v205, 0x4000, v157
	v_add_u32_e32 v197, 0x4400, v157
	v_add_u32_e32 v198, 0x4800, v157
	v_add_u32_e32 v199, 0x5000, v157
	v_add_u32_e32 v194, 0x5400, v157
	v_add_u32_e32 v195, 0x5800, v157
	v_add_u32_e32 v196, 0x6000, v157
	v_add_u32_e32 v187, 0x6400, v157
	v_add_u32_e32 v189, 0x6800, v157
	v_add_u32_e32 v190, 0x7200, v157
	v_add_u32_e32 v191, 0x7400, v157
	v_add_u32_e32 v192, 0x7600, v157
	v_add_u32_e32 v193, 0x7800, v157
	v_add_u32_e32 v186, 0x8400, v157
	v_add_u32_e32 v185, 0x8800, v157
	v_add_u32_e32 v184, 0x9400, v157
	v_add_u32_e32 v183, 0x9800, v157
	v_add_u32_e32 v181, 0xa400, v157
	v_add_u32_e32 v174, 0xa800, v157
	v_add_u32_e32 v175, 0xb400, v157
	v_add_u32_e32 v176, 0xb600, v157
	v_add_u32_e32 v177, 0xb800, v157
	v_add_u32_e32 v178, 0xba00, v157
	s_waitcnt vmcnt(0)
	s_barrier
	s_and_saveexec_b64 s[16:17], s[6:7]
	s_cbranch_execz .LBB0_1025
	v_and_b32_e32 v254, 63, v180
	v_lshrrev_b32_e32 v253, 4, v254
	v_mul_u32_u24_e32 v253, 0x840, v253
	v_and_b32_e32 v254, 15, v254
	v_lshl_add_u32 v253, v254, 2, v253
	v_and_b32_e32 v254, 64, v180
	v_lshl_add_u32 v253, v254, 2, v253
	ds_write_b32 v253, v0 offset:0
	ds_write_b32 v253, v1 offset:528
	ds_write_b32 v253, v2 offset:1056
	ds_write_b32 v253, v3 offset:1584
	ds_write_b32 v253, v4 offset:64
	ds_write_b32 v253, v5 offset:592
	ds_write_b32 v253, v6 offset:1120
	ds_write_b32 v253, v7 offset:1648
	ds_write_b32 v253, v8 offset:128
	ds_write_b32 v253, v9 offset:656
	ds_write_b32 v253, v10 offset:1184
	ds_write_b32 v253, v11 offset:1712
	ds_write_b32 v253, v12 offset:192
	ds_write_b32 v253, v13 offset:720
	ds_write_b32 v253, v14 offset:1248
	ds_write_b32 v253, v15 offset:1776
	ds_write_b32 v253, v16 offset:8448
	ds_write_b32 v253, v17 offset:8976
	ds_write_b32 v253, v18 offset:9504
	ds_write_b32 v253, v19 offset:10032
	ds_write_b32 v253, v20 offset:8512
	ds_write_b32 v253, v21 offset:9040
	ds_write_b32 v253, v22 offset:9568
	ds_write_b32 v253, v23 offset:10096
	ds_write_b32 v253, v24 offset:8576
	ds_write_b32 v253, v25 offset:9104
	ds_write_b32 v253, v26 offset:9632
	ds_write_b32 v253, v27 offset:10160
	ds_write_b32 v253, v28 offset:8640
	ds_write_b32 v253, v29 offset:9168
	ds_write_b32 v253, v30 offset:9696
	ds_write_b32 v253, v31 offset:10224
	ds_write_b32 v253, v32 offset:16896
	ds_write_b32 v253, v33 offset:17424
	ds_write_b32 v253, v34 offset:17952
	ds_write_b32 v253, v35 offset:18480
	ds_write_b32 v253, v36 offset:16960
	ds_write_b32 v253, v37 offset:17488
	ds_write_b32 v253, v38 offset:18016
	ds_write_b32 v253, v39 offset:18544
	ds_write_b32 v253, v40 offset:17024
	ds_write_b32 v253, v41 offset:17552
	ds_write_b32 v253, v42 offset:18080
	ds_write_b32 v253, v43 offset:18608
	ds_write_b32 v253, v44 offset:17088
	ds_write_b32 v253, v45 offset:17616
	ds_write_b32 v253, v46 offset:18144
	ds_write_b32 v253, v47 offset:18672
	ds_write_b32 v253, v48 offset:25344
	ds_write_b32 v253, v49 offset:25872
	ds_write_b32 v253, v50 offset:26400
	ds_write_b32 v253, v51 offset:26928
	ds_write_b32 v253, v52 offset:25408
	ds_write_b32 v253, v53 offset:25936
	ds_write_b32 v253, v54 offset:26464
	ds_write_b32 v253, v55 offset:26992
	ds_write_b32 v253, v56 offset:25472
	ds_write_b32 v253, v57 offset:26000
	ds_write_b32 v253, v58 offset:26528
	ds_write_b32 v253, v59 offset:27056
	ds_write_b32 v253, v60 offset:25536
	ds_write_b32 v253, v61 offset:26064
	ds_write_b32 v253, v62 offset:26592
	ds_write_b32 v253, v63 offset:27120
	ds_write_b32 v253, v64 offset:33792
	ds_write_b32 v253, v65 offset:34320
	ds_write_b32 v253, v66 offset:34848
	ds_write_b32 v253, v67 offset:35376
	ds_write_b32 v253, v68 offset:33856
	ds_write_b32 v253, v69 offset:34384
	ds_write_b32 v253, v70 offset:34912
	ds_write_b32 v253, v71 offset:35440
	ds_write_b32 v253, v72 offset:33920
	ds_write_b32 v253, v73 offset:34448
	ds_write_b32 v253, v74 offset:34976
	ds_write_b32 v253, v75 offset:35504
	ds_write_b32 v253, v76 offset:33984
	ds_write_b32 v253, v77 offset:34512
	ds_write_b32 v253, v78 offset:35040
	ds_write_b32 v253, v79 offset:35568
	ds_write_b32 v253, v80 offset:42240
	ds_write_b32 v253, v81 offset:42768
	ds_write_b32 v253, v82 offset:43296
	ds_write_b32 v253, v83 offset:43824
	ds_write_b32 v253, v84 offset:42304
	ds_write_b32 v253, v85 offset:42832
	ds_write_b32 v253, v86 offset:43360
	ds_write_b32 v253, v87 offset:43888
	ds_write_b32 v253, v88 offset:42368
	ds_write_b32 v253, v89 offset:42896
	ds_write_b32 v253, v90 offset:43424
	ds_write_b32 v253, v91 offset:43952
	ds_write_b32 v253, v92 offset:42432
	ds_write_b32 v253, v93 offset:42960
	ds_write_b32 v253, v94 offset:43488
	ds_write_b32 v253, v95 offset:44016
	ds_write_b32 v253, v96 offset:50688
	ds_write_b32 v253, v97 offset:51216
	ds_write_b32 v253, v98 offset:51744
	ds_write_b32 v253, v99 offset:52272
	ds_write_b32 v253, v100 offset:50752
	ds_write_b32 v253, v101 offset:51280
	ds_write_b32 v253, v102 offset:51808
	ds_write_b32 v253, v103 offset:52336
	ds_write_b32 v253, v104 offset:50816
	ds_write_b32 v253, v105 offset:51344
	ds_write_b32 v253, v106 offset:51872
	ds_write_b32 v253, v107 offset:52400
	ds_write_b32 v253, v108 offset:50880
	ds_write_b32 v253, v109 offset:51408
	ds_write_b32 v253, v110 offset:51936
	ds_write_b32 v253, v111 offset:52464
	ds_write_b32 v253, v112 offset:59136
	ds_write_b32 v253, v113 offset:59664
	ds_write_b32 v253, v114 offset:60192
	ds_write_b32 v253, v115 offset:60720
	ds_write_b32 v253, v116 offset:59200
	ds_write_b32 v253, v117 offset:59728
	ds_write_b32 v253, v118 offset:60256
	ds_write_b32 v253, v119 offset:60784
	ds_write_b32 v253, v120 offset:59264
	ds_write_b32 v253, v121 offset:59792
	ds_write_b32 v253, v122 offset:60320
	ds_write_b32 v253, v123 offset:60848
	ds_write_b32 v253, v124 offset:59328
	ds_write_b32 v253, v125 offset:59856
	ds_write_b32 v253, v126 offset:60384
	ds_write_b32 v253, v127 offset:60912

.LBB0_1174:
	s_and_b32 s4, s31, 0xff
	s_mulk_i32 s4, 0xab
	s_lshr_b32 s4, s4, 12
	s_add_i32 s24, s34, s4
	s_lshl_b32 s44, s24, 18
	v_or_b32_e32 v0, s44, v129
	v_or_b32_e32 v1, v0, v128
	s_mul_i32 s4, s4, 24
	v_lshlrev_b32_e32 v130, 1, v1
	v_add_lshl_u32 v1, v0, v128, 1
	s_sub_i32 s4, s31, s4
	v_add_u32_e32 v0, 0x20000, v1
	v_add_u32_e32 v2, 0x40000, v1
	v_add_u32_e32 v4, 0x60000, v1
	v_mov_b32_e32 v1, v131
	v_mov_b32_e32 v3, v131
	v_mov_b32_e32 v5, v131
	s_and_b32 s43, s4, 0xff
	v_lshl_add_u64 v[136:137], s[2:3], 0, v[130:131]
	v_lshl_add_u64 v[138:139], s[2:3], 0, v[0:1]
	v_lshl_add_u64 v[140:141], s[2:3], 0, v[2:3]
	v_lshl_add_u64 v[142:143], s[2:3], 0, v[4:5]
	s_cmp_gt_u32 s43, 15
	v_lshl_add_u64 v[150:151], v[136:137], 0, 64
	s_mov_b64 s[24:25], -1
	v_lshl_add_u64 v[148:149], v[138:139], 0, 64
	v_lshl_add_u64 v[146:147], v[140:141], 0, 64
	v_lshl_add_u64 v[144:145], v[142:143], 0, 64
	s_cbranch_scc0 .LBB0_1182
	s_lshl_b32 s4, s43, 7
	s_add_i32 s24, s4, 0xfffff800
	s_mov_b32 s25, s5
	v_readfirstlane_b32 s4, v160
	s_lshl_b64 s[26:27], s[24:25], 11
	s_mov_b32 m0, s4
	v_readfirstlane_b32 s4, v168
	s_add_u32 s26, s28, s26
	s_waitcnt vmcnt(0)
	s_barrier
	s_nop 0
	s_mov_b32 m0, s4
	v_readfirstlane_b32 s4, v169
	s_addc_u32 s27, s29, s27
	v_mov_b32_e32 v135, v131
	s_nop 0
	s_mov_b32 m0, s4
	v_readfirstlane_b32 s4, v170
	v_lshl_add_u64 v[0:1], s[26:27], 0, v[134:135]
	v_mov_b32_e32 v133, v131
	s_nop 0
	s_mov_b32 m0, s4
	v_readfirstlane_b32 s4, v171
	v_lshl_add_u64 v[152:153], v[0:1], 0, v[132:133]
	s_nop 0
	s_mov_b32 m0, s4
	v_readfirstlane_b32 s4, v172
	v_lshl_add_u64 v[154:155], v[152:153], 0, s[10:11]
	s_nop 0
	s_mov_b32 m0, s4
	v_readfirstlane_b32 s4, v173
	s_nop 0
	s_mov_b32 m0, s4
	v_readfirstlane_b32 s4, v174
	s_nop 0
	s_mov_b32 m0, s4
	v_readfirstlane_b32 s4, v175
	s_nop 0
	s_mov_b32 m0, s4
	v_readfirstlane_b32 s4, v176
	s_nop 0
	s_mov_b32 m0, s4
	v_readfirstlane_b32 s4, v177
	s_nop 0
	v_lshl_add_u64 v[0:1], v[152:153], 0, 64
	s_mov_b32 m0, s4
	v_readfirstlane_b32 s4, v178
	s_nop 0
	v_lshl_add_u64 v[0:1], v[152:153], 0, s[12:13]
	s_mov_b32 m0, s4
	s_mov_b32 s27, 2
	s_nop 0
	v_mov_b32_e32 v0, 0
	s_mov_b32 s26, 0
	s_mov_b32 s45, 0
	v_mov_b32_e32 v1, v0
	v_mov_b32_e32 v2, v0
	v_mov_b32_e32 v3, v0
	v_mov_b32_e32 v4, v0
	v_mov_b32_e32 v5, v0
	v_mov_b32_e32 v6, v0
	v_mov_b32_e32 v7, v0
	v_mov_b32_e32 v8, v0
	v_mov_b32_e32 v9, v0
	v_mov_b32_e32 v10, v0
	v_mov_b32_e32 v11, v0
	v_mov_b32_e32 v12, v0
	v_mov_b32_e32 v13, v0
	v_mov_b32_e32 v14, v0
	v_mov_b32_e32 v15, v0
	v_mov_b32_e32 v48, v0
	v_mov_b32_e32 v49, v0
	v_mov_b32_e32 v50, v0
	v_mov_b32_e32 v51, v0
	v_mov_b32_e32 v52, v0
	v_mov_b32_e32 v53, v0
	v_mov_b32_e32 v54, v0
	v_mov_b32_e32 v55, v0
	v_mov_b32_e32 v56, v0
	v_mov_b32_e32 v57, v0
	v_mov_b32_e32 v58, v0
	v_mov_b32_e32 v59, v0
	v_mov_b32_e32 v60, v0
	v_mov_b32_e32 v61, v0
	v_mov_b32_e32 v62, v0
	v_mov_b32_e32 v63, v0
	v_mov_b32_e32 v16, v0
	v_mov_b32_e32 v17, v0
	v_mov_b32_e32 v18, v0
	v_mov_b32_e32 v19, v0
	v_mov_b32_e32 v20, v0
	v_mov_b32_e32 v21, v0
	v_mov_b32_e32 v22, v0
	v_mov_b32_e32 v23, v0
	v_mov_b32_e32 v24, v0
	v_mov_b32_e32 v25, v0
	v_mov_b32_e32 v26, v0
	v_mov_b32_e32 v27, v0
	v_mov_b32_e32 v28, v0
	v_mov_b32_e32 v29, v0
	v_mov_b32_e32 v30, v0
	v_mov_b32_e32 v31, v0
	v_mov_b32_e32 v64, v0
	v_mov_b32_e32 v65, v0
	v_mov_b32_e32 v66, v0
	v_mov_b32_e32 v67, v0
	v_mov_b32_e32 v68, v0
	v_mov_b32_e32 v69, v0
	v_mov_b32_e32 v70, v0
	v_mov_b32_e32 v71, v0
	v_mov_b32_e32 v72, v0
	v_mov_b32_e32 v73, v0
	v_mov_b32_e32 v74, v0
	v_mov_b32_e32 v75, v0
	v_mov_b32_e32 v76, v0
	v_mov_b32_e32 v77, v0
	v_mov_b32_e32 v78, v0
	v_mov_b32_e32 v79, v0
	v_mov_b32_e32 v32, v0
	v_mov_b32_e32 v33, v0
	v_mov_b32_e32 v34, v0
	v_mov_b32_e32 v35, v0
	v_mov_b32_e32 v36, v0
	v_mov_b32_e32 v37, v0
	v_mov_b32_e32 v38, v0
	v_mov_b32_e32 v39, v0
	v_mov_b32_e32 v40, v0
	v_mov_b32_e32 v41, v0
	v_mov_b32_e32 v42, v0
	v_mov_b32_e32 v43, v0
	v_mov_b32_e32 v44, v0
	v_mov_b32_e32 v45, v0
	v_mov_b32_e32 v46, v0
	v_mov_b32_e32 v47, v0
	v_mov_b32_e32 v112, v0
	v_mov_b32_e32 v113, v0
	v_mov_b32_e32 v114, v0
	v_mov_b32_e32 v115, v0
	v_mov_b32_e32 v116, v0
	v_mov_b32_e32 v117, v0
	v_mov_b32_e32 v118, v0
	v_mov_b32_e32 v119, v0
	v_mov_b32_e32 v120, v0
	v_mov_b32_e32 v121, v0
	v_mov_b32_e32 v122, v0
	v_mov_b32_e32 v123, v0
	v_mov_b32_e32 v124, v0
	v_mov_b32_e32 v125, v0
	v_mov_b32_e32 v126, v0
	v_mov_b32_e32 v127, v0
	v_mov_b32_e32 v80, v0
	v_mov_b32_e32 v81, v0
	v_mov_b32_e32 v82, v0
	v_mov_b32_e32 v83, v0
	v_mov_b32_e32 v84, v0
	v_mov_b32_e32 v85, v0
	v_mov_b32_e32 v86, v0
	v_mov_b32_e32 v87, v0
	v_mov_b32_e32 v88, v0
	v_mov_b32_e32 v89, v0
	v_mov_b32_e32 v90, v0
	v_mov_b32_e32 v91, v0
	v_mov_b32_e32 v92, v0
	v_mov_b32_e32 v93, v0
	v_mov_b32_e32 v94, v0
	v_mov_b32_e32 v95, v0
	v_mov_b32_e32 v96, v0
	v_mov_b32_e32 v97, v0
	v_mov_b32_e32 v98, v0
	v_mov_b32_e32 v99, v0
	v_mov_b32_e32 v100, v0
	v_mov_b32_e32 v101, v0
	v_mov_b32_e32 v102, v0
	v_mov_b32_e32 v103, v0
	v_mov_b32_e32 v104, v0
	v_mov_b32_e32 v105, v0
	v_mov_b32_e32 v106, v0
	v_mov_b32_e32 v107, v0
	v_mov_b32_e32 v108, v0
	v_mov_b32_e32 v109, v0
	v_mov_b32_e32 v110, v0
	v_mov_b32_e32 v111, v0
	s_mov_b64 s[54:55], 0x80
	v_lshrrev_b32_e32 v182, 6, v180
	v_lshlrev_b32_e32 v192, 11, v182
	v_and_b32_e32 v156, 63, v180
	v_readfirstlane_b32 s53, v192
	v_lshrrev_b32_e32 v157, 4, v156
	v_bfe_u32 v158, v156, 1, 3
	v_xor_b32_e32 v158, v157, v158
	v_and_b32_e32 v159, 31, v156
	v_lshlrev_b32_e32 v159, 7, v159
	v_lshrrev_b32_e32 v159, 3, v156
	v_lshlrev_b32_e32 v192, 4, v159
	v_add_u32_e32 v193, 0x80, v192
	v_and_b32_e32 v159, 7, v156
	v_lshrrev_b32_e32 v157, 4, v156
	v_xor_b32_e32 v157, v159, v157
	v_lshrrev_b32_e32 v159, 5, v156
	v_sub_u32_e32 v194, v157, v159
	v_xor_b32_e32 v157, 4, v157
	v_add_u32_e32 v159, 2, v159
	v_sub_u32_e32 v196, v157, v159
	v_lshlrev_b32_e32 v194, 4, v194
	v_ashrrev_i32_e32 v195, 31, v194
	v_lshlrev_b32_e32 v196, 4, v196
	v_ashrrev_i32_e32 v197, 31, v196
	ds_bpermute_b32 v244, v192, v152
	ds_bpermute_b32 v245, v192, v153
	ds_bpermute_b32 v246, v193, v152
	ds_bpermute_b32 v247, v193, v153
	ds_bpermute_b32 v248, v192, v154
	ds_bpermute_b32 v249, v192, v155
	ds_bpermute_b32 v250, v193, v154
	ds_bpermute_b32 v251, v193, v155
	s_waitcnt lgkmcnt(0)
	ds_bpermute_b32 v186, v192, v136
	ds_bpermute_b32 v187, v192, v137
	ds_bpermute_b32 v234, v193, v136
	ds_bpermute_b32 v235, v193, v137
	ds_bpermute_b32 v236, v192, v138
	ds_bpermute_b32 v237, v192, v139
	ds_bpermute_b32 v238, v193, v138
	ds_bpermute_b32 v239, v193, v139
	ds_bpermute_b32 v240, v192, v140
	ds_bpermute_b32 v241, v192, v141
	ds_bpermute_b32 v242, v193, v140
	ds_bpermute_b32 v243, v193, v141
	ds_bpermute_b32 v152, v192, v142
	ds_bpermute_b32 v153, v192, v143
	ds_bpermute_b32 v154, v193, v142
	ds_bpermute_b32 v155, v193, v143
	s_waitcnt lgkmcnt(0)
	v_and_b32_e32 v159, 15, v156
	v_lshlrev_b32_e32 v159, 7, v159
	v_lshrrev_b32_e32 v157, 1, v182
	v_lshl_add_u32 v136, v157, 14, v159
	v_and_b32_e32 v157, 1, v182
	v_lshl_add_u32 v140, v157, 13, v159
	v_add_u32_e32 v140, 0x10000, v140
	v_xor_b32_e32 v159, 4, v158
	v_lshl_add_u32 v137, v159, 4, v136
	v_lshl_add_u32 v141, v159, 4, v140
	v_xor_b32_e32 v159, 0, v158
	v_lshl_add_u32 v136, v159, 4, v136
	v_lshl_add_u32 v140, v159, 4, v140
	v_lshl_add_u64 v[186:187], v[186:187], 0, v[194:195]
	v_lshl_add_u64 v[234:235], v[234:235], 0, v[196:197]
	v_lshl_add_u64 v[236:237], v[236:237], 0, v[194:195]
	v_lshl_add_u64 v[238:239], v[238:239], 0, v[196:197]
	v_lshl_add_u64 v[240:241], v[240:241], 0, v[194:195]
	v_lshl_add_u64 v[242:243], v[242:243], 0, v[196:197]
	v_lshl_add_u64 v[152:153], v[152:153], 0, v[194:195]
	v_lshl_add_u64 v[154:155], v[154:155], 0, v[196:197]
	v_lshl_add_u64 v[244:245], v[244:245], 0, v[194:195]
	v_lshl_add_u64 v[246:247], v[246:247], 0, v[196:197]
	v_lshl_add_u64 v[248:249], v[248:249], 0, v[194:195]
	v_lshl_add_u64 v[250:251], v[250:251], 0, v[196:197]
	s_mov_b32 s58, s53
	s_add_i32 m0, s58, 0x0
	s_nop 0
	global_load_lds_dwordx4 v[186:187], off
	s_add_i32 m0, s58, 0x400
	v_lshl_add_u64 v[186:187], v[186:187], 0, s[54:55]
	global_load_lds_dwordx4 v[234:235], off
	s_add_i32 m0, s58, 0x2000
	v_lshl_add_u64 v[234:235], v[234:235], 0, s[54:55]
	global_load_lds_dwordx4 v[236:237], off
	s_add_i32 m0, s58, 0x2400
	v_lshl_add_u64 v[236:237], v[236:237], 0, s[54:55]
	global_load_lds_dwordx4 v[238:239], off
	s_add_i32 m0, s58, 0x4000
	v_lshl_add_u64 v[238:239], v[238:239], 0, s[54:55]
	global_load_lds_dwordx4 v[240:241], off
	s_add_i32 m0, s58, 0x4400
	v_lshl_add_u64 v[240:241], v[240:241], 0, s[54:55]
	global_load_lds_dwordx4 v[242:243], off
	s_add_i32 m0, s58, 0x6000
	v_lshl_add_u64 v[242:243], v[242:243], 0, s[54:55]
	global_load_lds_dwordx4 v[152:153], off
	s_add_i32 m0, s58, 0x6400
	v_lshl_add_u64 v[152:153], v[152:153], 0, s[54:55]
	global_load_lds_dwordx4 v[154:155], off
	v_lshl_add_u64 v[154:155], v[154:155], 0, s[54:55]
	s_add_i32 s58, s53, 0x10000
	s_add_i32 m0, s58, 0x0
	s_nop 0
	global_load_lds_dwordx4 v[244:245], off
	s_add_i32 m0, s58, 0x400
	v_lshl_add_u64 v[244:245], v[244:245], 0, s[54:55]
	global_load_lds_dwordx4 v[246:247], off
	s_add_i32 m0, s58, 0x2000
	v_lshl_add_u64 v[246:247], v[246:247], 0, s[54:55]
	global_load_lds_dwordx4 v[248:249], off
	s_add_i32 m0, s58, 0x2400
	v_lshl_add_u64 v[248:249], v[248:249], 0, s[54:55]
	global_load_lds_dwordx4 v[250:251], off
	v_lshl_add_u64 v[250:251], v[250:251], 0, s[54:55]
	s_mov_b32 s26, 0
	s_mov_b32 s27, 0
	s_setprio 1

.Lg_ph11a_noB:
	s_setprio 2
	s_waitcnt lgkmcnt(3)
	v_mfma_f32_16x16x32_bf16 v[0:3], v[156:159], v[198:201], v[0:3]
	v_mfma_f32_16x16x32_bf16 v[4:7], v[156:159], v[202:205], v[4:7]
	v_mfma_f32_16x16x32_bf16 v[8:11], v[156:159], v[206:209], v[8:11]
	v_mfma_f32_16x16x32_bf16 v[12:15], v[156:159], v[214:217], v[12:15]
	ds_read_b128 v[156:159], v136 offset:8192
	s_waitcnt lgkmcnt(3)
	v_mfma_f32_16x16x32_bf16 v[16:19], v[182:185], v[198:201], v[16:19]
	v_mfma_f32_16x16x32_bf16 v[20:23], v[182:185], v[202:205], v[20:23]
	v_mfma_f32_16x16x32_bf16 v[24:27], v[182:185], v[206:209], v[24:27]
	v_mfma_f32_16x16x32_bf16 v[28:31], v[182:185], v[214:217], v[28:31]
	ds_read_b128 v[182:185], v136 offset:10240
	s_waitcnt lgkmcnt(3)
	v_mfma_f32_16x16x32_bf16 v[32:35], v[190:193], v[198:201], v[32:35]
	v_mfma_f32_16x16x32_bf16 v[36:39], v[190:193], v[202:205], v[36:39]
	v_mfma_f32_16x16x32_bf16 v[40:43], v[190:193], v[206:209], v[40:43]
	v_mfma_f32_16x16x32_bf16 v[44:47], v[190:193], v[214:217], v[44:47]
	ds_read_b128 v[190:193], v136 offset:12288
	s_waitcnt lgkmcnt(3)
	v_mfma_f32_16x16x32_bf16 v[48:51], v[194:197], v[198:201], v[48:51]
	v_mfma_f32_16x16x32_bf16 v[52:55], v[194:197], v[202:205], v[52:55]
	v_mfma_f32_16x16x32_bf16 v[56:59], v[194:197], v[206:209], v[56:59]
	v_mfma_f32_16x16x32_bf16 v[60:63], v[194:197], v[214:217], v[60:63]
	ds_read_b128 v[194:197], v136 offset:14336
	s_waitcnt lgkmcnt(3)
	v_mfma_f32_16x16x32_bf16 v[64:67], v[156:159], v[198:201], v[64:67]
	v_mfma_f32_16x16x32_bf16 v[68:71], v[156:159], v[202:205], v[68:71]
	v_mfma_f32_16x16x32_bf16 v[72:75], v[156:159], v[206:209], v[72:75]
	v_mfma_f32_16x16x32_bf16 v[76:79], v[156:159], v[214:217], v[76:79]
	ds_read_b128 v[156:159], v137
	s_waitcnt lgkmcnt(3)
	v_mfma_f32_16x16x32_bf16 v[80:83], v[182:185], v[198:201], v[80:83]
	v_mfma_f32_16x16x32_bf16 v[84:87], v[182:185], v[202:205], v[84:87]
	v_mfma_f32_16x16x32_bf16 v[88:91], v[182:185], v[206:209], v[88:91]
	v_mfma_f32_16x16x32_bf16 v[92:95], v[182:185], v[214:217], v[92:95]
	ds_read_b128 v[182:185], v137 offset:2048
	s_waitcnt lgkmcnt(3)
	v_mfma_f32_16x16x32_bf16 v[96:99], v[190:193], v[198:201], v[96:99]
	v_mfma_f32_16x16x32_bf16 v[100:103], v[190:193], v[202:205], v[100:103]
	v_mfma_f32_16x16x32_bf16 v[104:107], v[190:193], v[206:209], v[104:107]
	v_mfma_f32_16x16x32_bf16 v[108:111], v[190:193], v[214:217], v[108:111]
	ds_read_b128 v[190:193], v137 offset:4096
	s_waitcnt lgkmcnt(3)
	v_mfma_f32_16x16x32_bf16 v[112:115], v[194:197], v[198:201], v[112:115]
	v_mfma_f32_16x16x32_bf16 v[116:119], v[194:197], v[202:205], v[116:119]
	v_mfma_f32_16x16x32_bf16 v[120:123], v[194:197], v[206:209], v[120:123]
	v_mfma_f32_16x16x32_bf16 v[124:127], v[194:197], v[214:217], v[124:127]
	ds_read_b128 v[194:197], v137 offset:6144
	s_waitcnt lgkmcnt(3)
	v_mfma_f32_16x16x32_bf16 v[0:3], v[156:159], v[218:221], v[0:3]
	v_mfma_f32_16x16x32_bf16 v[4:7], v[156:159], v[222:225], v[4:7]
	v_mfma_f32_16x16x32_bf16 v[8:11], v[156:159], v[226:229], v[8:11]
	v_mfma_f32_16x16x32_bf16 v[12:15], v[156:159], v[230:233], v[12:15]
	ds_read_b128 v[156:159], v137 offset:8192
	s_waitcnt lgkmcnt(3)
	v_mfma_f32_16x16x32_bf16 v[16:19], v[182:185], v[218:221], v[16:19]
	v_mfma_f32_16x16x32_bf16 v[20:23], v[182:185], v[222:225], v[20:23]
	v_mfma_f32_16x16x32_bf16 v[24:27], v[182:185], v[226:229], v[24:27]
	v_mfma_f32_16x16x32_bf16 v[28:31], v[182:185], v[230:233], v[28:31]
	ds_read_b128 v[182:185], v137 offset:10240
	s_waitcnt lgkmcnt(3)
	v_mfma_f32_16x16x32_bf16 v[32:35], v[190:193], v[218:221], v[32:35]
	v_mfma_f32_16x16x32_bf16 v[36:39], v[190:193], v[222:225], v[36:39]
	v_mfma_f32_16x16x32_bf16 v[40:43], v[190:193], v[226:229], v[40:43]
	v_mfma_f32_16x16x32_bf16 v[44:47], v[190:193], v[230:233], v[44:47]
	ds_read_b128 v[190:193], v137 offset:12288
	s_waitcnt lgkmcnt(3)
	v_mfma_f32_16x16x32_bf16 v[48:51], v[194:197], v[218:221], v[48:51]
	v_mfma_f32_16x16x32_bf16 v[52:55], v[194:197], v[222:225], v[52:55]
	v_mfma_f32_16x16x32_bf16 v[56:59], v[194:197], v[226:229], v[56:59]
	v_mfma_f32_16x16x32_bf16 v[60:63], v[194:197], v[230:233], v[60:63]
	ds_read_b128 v[194:197], v137 offset:14336
	s_waitcnt lgkmcnt(3)
	v_mfma_f32_16x16x32_bf16 v[64:67], v[156:159], v[218:221], v[64:67]
	v_mfma_f32_16x16x32_bf16 v[68:71], v[156:159], v[222:225], v[68:71]
	v_mfma_f32_16x16x32_bf16 v[72:75], v[156:159], v[226:229], v[72:75]
	v_mfma_f32_16x16x32_bf16 v[76:79], v[156:159], v[230:233], v[76:79]
	s_waitcnt lgkmcnt(2)
	v_mfma_f32_16x16x32_bf16 v[80:83], v[182:185], v[218:221], v[80:83]
	v_mfma_f32_16x16x32_bf16 v[84:87], v[182:185], v[222:225], v[84:87]
	v_mfma_f32_16x16x32_bf16 v[88:91], v[182:185], v[226:229], v[88:91]
	v_mfma_f32_16x16x32_bf16 v[92:95], v[182:185], v[230:233], v[92:95]
	s_waitcnt lgkmcnt(1)
	v_mfma_f32_16x16x32_bf16 v[96:99], v[190:193], v[218:221], v[96:99]
	v_mfma_f32_16x16x32_bf16 v[100:103], v[190:193], v[222:225], v[100:103]
	v_mfma_f32_16x16x32_bf16 v[104:107], v[190:193], v[226:229], v[104:107]
	v_mfma_f32_16x16x32_bf16 v[108:111], v[190:193], v[230:233], v[108:111]
	s_waitcnt lgkmcnt(0)
	v_mfma_f32_16x16x32_bf16 v[112:115], v[194:197], v[218:221], v[112:115]
	v_mfma_f32_16x16x32_bf16 v[116:119], v[194:197], v[222:225], v[116:119]
	v_mfma_f32_16x16x32_bf16 v[120:123], v[194:197], v[226:229], v[120:123]
	v_mfma_f32_16x16x32_bf16 v[124:127], v[194:197], v[230:233], v[124:127]
	s_setprio 1
	v_xor_b32_e32 v136, 0x8000, v136
	v_xor_b32_e32 v137, 0x8000, v137
	s_xor_b32 s27, s27, 0x8000
	s_add_i32 s26, s26, 1
	s_cmp_eq_u32 s26, 16
	s_cbranch_scc0 .Lg_ph11a_top
	s_setprio 0
	s_waitcnt vmcnt(0)
	v_mov_b32_e32 v130, v180
	s_waitcnt vmcnt(0)
	s_barrier
	s_and_saveexec_b64 s[26:27], s[6:7]
	s_cbranch_execz .LBB0_1179
	v_and_b32_e32 v254, 63, v180
	v_lshrrev_b32_e32 v253, 4, v254
	v_mul_u32_u24_e32 v253, 0x840, v253
	v_and_b32_e32 v254, 15, v254
	v_lshl_add_u32 v253, v254, 2, v253
	v_and_b32_e32 v254, 64, v180
	v_lshl_add_u32 v253, v254, 2, v253
	ds_write_b32 v253, v0 offset:0
	ds_write_b32 v253, v1 offset:528
	ds_write_b32 v253, v2 offset:1056
	ds_write_b32 v253, v3 offset:1584
	ds_write_b32 v253, v4 offset:64
	ds_write_b32 v253, v5 offset:592
	ds_write_b32 v253, v6 offset:1120
	ds_write_b32 v253, v7 offset:1648
	ds_write_b32 v253, v8 offset:128
	ds_write_b32 v253, v9 offset:656
	ds_write_b32 v253, v10 offset:1184
	ds_write_b32 v253, v11 offset:1712
	ds_write_b32 v253, v12 offset:192
	ds_write_b32 v253, v13 offset:720
	ds_write_b32 v253, v14 offset:1248
	ds_write_b32 v253, v15 offset:1776
	ds_write_b32 v253, v16 offset:8448
	ds_write_b32 v253, v17 offset:8976
	ds_write_b32 v253, v18 offset:9504
	ds_write_b32 v253, v19 offset:10032
	ds_write_b32 v253, v20 offset:8512
	ds_write_b32 v253, v21 offset:9040
	ds_write_b32 v253, v22 offset:9568
	ds_write_b32 v253, v23 offset:10096
	ds_write_b32 v253, v24 offset:8576
	ds_write_b32 v253, v25 offset:9104
	ds_write_b32 v253, v26 offset:9632
	ds_write_b32 v253, v27 offset:10160
	ds_write_b32 v253, v28 offset:8640
	ds_write_b32 v253, v29 offset:9168
	ds_write_b32 v253, v30 offset:9696
	ds_write_b32 v253, v31 offset:10224
	ds_write_b32 v253, v32 offset:16896
	ds_write_b32 v253, v33 offset:17424
	ds_write_b32 v253, v34 offset:17952
	ds_write_b32 v253, v35 offset:18480
	ds_write_b32 v253, v36 offset:16960
	ds_write_b32 v253, v37 offset:17488
	ds_write_b32 v253, v38 offset:18016
	ds_write_b32 v253, v39 offset:18544
	ds_write_b32 v253, v40 offset:17024
	ds_write_b32 v253, v41 offset:17552
	ds_write_b32 v253, v42 offset:18080
	ds_write_b32 v253, v43 offset:18608
	ds_write_b32 v253, v44 offset:17088
	ds_write_b32 v253, v45 offset:17616
	ds_write_b32 v253, v46 offset:18144
	ds_write_b32 v253, v47 offset:18672
	ds_write_b32 v253, v48 offset:25344
	ds_write_b32 v253, v49 offset:25872
	ds_write_b32 v253, v50 offset:26400
	ds_write_b32 v253, v51 offset:26928
	ds_write_b32 v253, v52 offset:25408
	ds_write_b32 v253, v53 offset:25936
	ds_write_b32 v253, v54 offset:26464
	ds_write_b32 v253, v55 offset:26992
	ds_write_b32 v253, v56 offset:25472
	ds_write_b32 v253, v57 offset:26000
	ds_write_b32 v253, v58 offset:26528
	ds_write_b32 v253, v59 offset:27056
	ds_write_b32 v253, v60 offset:25536
	ds_write_b32 v253, v61 offset:26064
	ds_write_b32 v253, v62 offset:26592
	ds_write_b32 v253, v63 offset:27120
	ds_write_b32 v253, v64 offset:33792
	ds_write_b32 v253, v65 offset:34320
	ds_write_b32 v253, v66 offset:34848
	ds_write_b32 v253, v67 offset:35376
	ds_write_b32 v253, v68 offset:33856
	ds_write_b32 v253, v69 offset:34384
	ds_write_b32 v253, v70 offset:34912
	ds_write_b32 v253, v71 offset:35440
	ds_write_b32 v253, v72 offset:33920
	ds_write_b32 v253, v73 offset:34448
	ds_write_b32 v253, v74 offset:34976
	ds_write_b32 v253, v75 offset:35504
	ds_write_b32 v253, v76 offset:33984
	ds_write_b32 v253, v77 offset:34512
	ds_write_b32 v253, v78 offset:35040
	ds_write_b32 v253, v79 offset:35568
	ds_write_b32 v253, v80 offset:42240
	ds_write_b32 v253, v81 offset:42768
	ds_write_b32 v253, v82 offset:43296
	ds_write_b32 v253, v83 offset:43824
	ds_write_b32 v253, v84 offset:42304
	ds_write_b32 v253, v85 offset:42832
	ds_write_b32 v253, v86 offset:43360
	ds_write_b32 v253, v87 offset:43888
	ds_write_b32 v253, v88 offset:42368
	ds_write_b32 v253, v89 offset:42896
	ds_write_b32 v253, v90 offset:43424
	ds_write_b32 v253, v91 offset:43952
	ds_write_b32 v253, v92 offset:42432
	ds_write_b32 v253, v93 offset:42960
	ds_write_b32 v253, v94 offset:43488
	ds_write_b32 v253, v95 offset:44016
	ds_write_b32 v253, v96 offset:50688
	ds_write_b32 v253, v97 offset:51216
	ds_write_b32 v253, v98 offset:51744
	ds_write_b32 v253, v99 offset:52272
	ds_write_b32 v253, v100 offset:50752
	ds_write_b32 v253, v101 offset:51280
	ds_write_b32 v253, v102 offset:51808
	ds_write_b32 v253, v103 offset:52336
	ds_write_b32 v253, v104 offset:50816
	ds_write_b32 v253, v105 offset:51344
	ds_write_b32 v253, v106 offset:51872
	ds_write_b32 v253, v107 offset:52400
	ds_write_b32 v253, v108 offset:50880
	ds_write_b32 v253, v109 offset:51408
	ds_write_b32 v253, v110 offset:51936
	ds_write_b32 v253, v111 offset:52464
	ds_write_b32 v253, v112 offset:59136
	ds_write_b32 v253, v113 offset:59664
	ds_write_b32 v253, v114 offset:60192
	ds_write_b32 v253, v115 offset:60720
	ds_write_b32 v253, v116 offset:59200
	ds_write_b32 v253, v117 offset:59728
	ds_write_b32 v253, v118 offset:60256
	ds_write_b32 v253, v119 offset:60784
	ds_write_b32 v253, v120 offset:59264
	ds_write_b32 v253, v121 offset:59792
	ds_write_b32 v253, v122 offset:60320
	ds_write_b32 v253, v123 offset:60848
	ds_write_b32 v253, v124 offset:59328
	ds_write_b32 v253, v125 offset:59856
	ds_write_b32 v253, v126 offset:60384
	ds_write_b32 v253, v127 offset:60912

.LBB0_1182:
	s_and_b64 vcc, exec, s[24:25]
	s_cbranch_vccz .LBB0_1173
	s_lshl_b32 s4, s43, 17
	s_add_u32 s24, s28, s4
	v_readfirstlane_b32 s4, v160
	s_mov_b32 m0, s4
	v_readfirstlane_b32 s4, v168
	s_addc_u32 s25, s29, 0
	v_mov_b32_e32 v135, v131
	s_waitcnt vmcnt(0)
	s_barrier
	s_nop 0
	s_mov_b32 m0, s4
	v_readfirstlane_b32 s4, v169
	v_lshl_add_u64 v[0:1], s[24:25], 0, v[134:135]
	v_mov_b32_e32 v133, v131
	s_nop 0
	s_mov_b32 m0, s4
	v_readfirstlane_b32 s4, v170
	v_lshl_add_u64 v[0:1], v[0:1], 0, v[132:133]
	s_nop 0
	s_mov_b32 m0, s4
	v_readfirstlane_b32 s4, v171
	v_lshl_add_u64 v[152:153], v[0:1], 0, s[16:17]
	s_nop 0
	s_mov_b32 m0, s4
	v_readfirstlane_b32 s4, v172
	v_lshl_add_u64 v[154:155], v[0:1], 0, s[18:19]
	s_nop 0
	s_mov_b32 m0, s4
	v_readfirstlane_b32 s4, v173
	s_nop 0
	s_mov_b32 m0, s4
	v_readfirstlane_b32 s4, v174
	s_nop 0
	s_mov_b32 m0, s4
	v_readfirstlane_b32 s4, v175
	s_nop 0
	s_mov_b32 m0, s4
	v_readfirstlane_b32 s4, v176
	s_nop 0
	s_mov_b32 m0, s4
	v_readfirstlane_b32 s4, v177
	s_nop 0
	v_lshl_add_u64 v[2:3], v[0:1], 0, s[20:21]
	s_mov_b32 m0, s4
	v_readfirstlane_b32 s4, v178
	s_nop 0
	v_lshl_add_u64 v[0:1], v[0:1], 0, s[22:23]
	s_mov_b32 m0, s4
	s_mov_b32 s25, 2
	s_nop 0
	v_mov_b32_e32 v0, 0
	s_mov_b32 s24, 0
	s_mov_b32 s26, 0
	v_mov_b32_e32 v1, v0
	v_mov_b32_e32 v2, v0
	v_mov_b32_e32 v3, v0
	v_mov_b32_e32 v4, v0
	v_mov_b32_e32 v5, v0
	v_mov_b32_e32 v6, v0
	v_mov_b32_e32 v7, v0
	v_mov_b32_e32 v8, v0
	v_mov_b32_e32 v9, v0
	v_mov_b32_e32 v10, v0
	v_mov_b32_e32 v11, v0
	v_mov_b32_e32 v12, v0
	v_mov_b32_e32 v13, v0
	v_mov_b32_e32 v14, v0
	v_mov_b32_e32 v15, v0
	v_mov_b32_e32 v16, v0
	v_mov_b32_e32 v17, v0
	v_mov_b32_e32 v18, v0
	v_mov_b32_e32 v19, v0
	v_mov_b32_e32 v20, v0
	v_mov_b32_e32 v21, v0
	v_mov_b32_e32 v22, v0
	v_mov_b32_e32 v23, v0
	v_mov_b32_e32 v24, v0
	v_mov_b32_e32 v25, v0
	v_mov_b32_e32 v26, v0
	v_mov_b32_e32 v27, v0
	v_mov_b32_e32 v28, v0
	v_mov_b32_e32 v29, v0
	v_mov_b32_e32 v30, v0
	v_mov_b32_e32 v31, v0
	v_mov_b32_e32 v32, v0
	v_mov_b32_e32 v33, v0
	v_mov_b32_e32 v34, v0
	v_mov_b32_e32 v35, v0
	v_mov_b32_e32 v36, v0
	v_mov_b32_e32 v37, v0
	v_mov_b32_e32 v38, v0
	v_mov_b32_e32 v39, v0
	v_mov_b32_e32 v40, v0
	v_mov_b32_e32 v41, v0
	v_mov_b32_e32 v42, v0
	v_mov_b32_e32 v43, v0
	v_mov_b32_e32 v44, v0
	v_mov_b32_e32 v45, v0
	v_mov_b32_e32 v46, v0
	v_mov_b32_e32 v47, v0
	v_mov_b32_e32 v48, v0
	v_mov_b32_e32 v49, v0
	v_mov_b32_e32 v50, v0
	v_mov_b32_e32 v51, v0
	v_mov_b32_e32 v52, v0
	v_mov_b32_e32 v53, v0
	v_mov_b32_e32 v54, v0
	v_mov_b32_e32 v55, v0
	v_mov_b32_e32 v56, v0
	v_mov_b32_e32 v57, v0
	v_mov_b32_e32 v58, v0
	v_mov_b32_e32 v59, v0
	v_mov_b32_e32 v60, v0
	v_mov_b32_e32 v61, v0
	v_mov_b32_e32 v62, v0
	v_mov_b32_e32 v63, v0
	v_mov_b32_e32 v64, v0
	v_mov_b32_e32 v65, v0
	v_mov_b32_e32 v66, v0
	v_mov_b32_e32 v67, v0
	v_mov_b32_e32 v68, v0
	v_mov_b32_e32 v69, v0
	v_mov_b32_e32 v70, v0
	v_mov_b32_e32 v71, v0
	v_mov_b32_e32 v72, v0
	v_mov_b32_e32 v73, v0
	v_mov_b32_e32 v74, v0
	v_mov_b32_e32 v75, v0
	v_mov_b32_e32 v76, v0
	v_mov_b32_e32 v77, v0
	v_mov_b32_e32 v78, v0
	v_mov_b32_e32 v79, v0
	v_mov_b32_e32 v112, v0
	v_mov_b32_e32 v113, v0
	v_mov_b32_e32 v114, v0
	v_mov_b32_e32 v115, v0
	v_mov_b32_e32 v116, v0
	v_mov_b32_e32 v117, v0
	v_mov_b32_e32 v118, v0
	v_mov_b32_e32 v119, v0
	v_mov_b32_e32 v120, v0
	v_mov_b32_e32 v121, v0
	v_mov_b32_e32 v122, v0
	v_mov_b32_e32 v123, v0
	v_mov_b32_e32 v124, v0
	v_mov_b32_e32 v125, v0
	v_mov_b32_e32 v126, v0
	v_mov_b32_e32 v127, v0
	v_mov_b32_e32 v80, v0
	v_mov_b32_e32 v81, v0
	v_mov_b32_e32 v82, v0
	v_mov_b32_e32 v83, v0
	v_mov_b32_e32 v84, v0
	v_mov_b32_e32 v85, v0
	v_mov_b32_e32 v86, v0
	v_mov_b32_e32 v87, v0
	v_mov_b32_e32 v88, v0
	v_mov_b32_e32 v89, v0
	v_mov_b32_e32 v90, v0
	v_mov_b32_e32 v91, v0
	v_mov_b32_e32 v92, v0
	v_mov_b32_e32 v93, v0
	v_mov_b32_e32 v94, v0
	v_mov_b32_e32 v95, v0
	v_mov_b32_e32 v96, v0
	v_mov_b32_e32 v97, v0
	v_mov_b32_e32 v98, v0
	v_mov_b32_e32 v99, v0
	v_mov_b32_e32 v100, v0
	v_mov_b32_e32 v101, v0
	v_mov_b32_e32 v102, v0
	v_mov_b32_e32 v103, v0
	v_mov_b32_e32 v104, v0
	v_mov_b32_e32 v105, v0
	v_mov_b32_e32 v106, v0
	v_mov_b32_e32 v107, v0
	v_mov_b32_e32 v108, v0
	v_mov_b32_e32 v109, v0
	v_mov_b32_e32 v110, v0
	v_mov_b32_e32 v111, v0
	s_mov_b64 s[54:55], 0x80
	v_lshrrev_b32_e32 v148, 6, v180
	v_lshlrev_b32_e32 v158, 11, v148
	v_and_b32_e32 v144, 63, v180
	v_readfirstlane_b32 s53, v158
	v_lshrrev_b32_e32 v145, 4, v144
	v_bfe_u32 v146, v144, 1, 3
	v_xor_b32_e32 v146, v145, v146
	v_and_b32_e32 v147, 31, v144
	v_lshlrev_b32_e32 v147, 7, v147
	v_lshrrev_b32_e32 v147, 3, v144
	v_lshlrev_b32_e32 v158, 4, v147
	v_add_u32_e32 v159, 0x80, v158
	v_and_b32_e32 v147, 7, v144
	v_lshrrev_b32_e32 v145, 4, v144
	v_xor_b32_e32 v145, v147, v145
	v_lshrrev_b32_e32 v147, 5, v144
	v_sub_u32_e32 v182, v145, v147
	v_xor_b32_e32 v145, 4, v145
	v_add_u32_e32 v147, 2, v147
	v_sub_u32_e32 v184, v145, v147
	v_lshlrev_b32_e32 v182, 4, v182
	v_ashrrev_i32_e32 v183, 31, v182
	v_lshlrev_b32_e32 v184, 4, v184
	v_ashrrev_i32_e32 v185, 31, v184
	ds_bpermute_b32 v244, v158, v152
	ds_bpermute_b32 v245, v158, v153
	ds_bpermute_b32 v246, v159, v152
	ds_bpermute_b32 v247, v159, v153
	ds_bpermute_b32 v248, v158, v154
	ds_bpermute_b32 v249, v158, v155
	ds_bpermute_b32 v250, v159, v154
	ds_bpermute_b32 v251, v159, v155
	s_waitcnt lgkmcnt(0)
	ds_bpermute_b32 v186, v158, v136
	ds_bpermute_b32 v187, v158, v137
	ds_bpermute_b32 v234, v159, v136
	ds_bpermute_b32 v235, v159, v137
	ds_bpermute_b32 v236, v158, v138
	ds_bpermute_b32 v237, v158, v139
	ds_bpermute_b32 v238, v159, v138
	ds_bpermute_b32 v239, v159, v139
	ds_bpermute_b32 v240, v158, v140
	ds_bpermute_b32 v241, v158, v141
	ds_bpermute_b32 v242, v159, v140
	ds_bpermute_b32 v243, v159, v141
	ds_bpermute_b32 v152, v158, v142
	ds_bpermute_b32 v153, v158, v143
	ds_bpermute_b32 v154, v159, v142
	ds_bpermute_b32 v155, v159, v143
	s_waitcnt lgkmcnt(0)
	v_and_b32_e32 v147, 15, v144
	v_lshlrev_b32_e32 v147, 7, v147
	v_lshrrev_b32_e32 v145, 1, v148
	v_lshl_add_u32 v136, v145, 14, v147
	v_and_b32_e32 v145, 1, v148
	v_lshl_add_u32 v140, v145, 13, v147
	v_add_u32_e32 v140, 0x10000, v140
	v_xor_b32_e32 v147, 4, v146
	v_lshl_add_u32 v137, v147, 4, v136
	v_lshl_add_u32 v141, v147, 4, v140
	v_xor_b32_e32 v147, 0, v146
	v_lshl_add_u32 v136, v147, 4, v136
	v_lshl_add_u32 v140, v147, 4, v140
	v_lshl_add_u64 v[186:187], v[186:187], 0, v[182:183]
	v_lshl_add_u64 v[234:235], v[234:235], 0, v[184:185]
	v_lshl_add_u64 v[236:237], v[236:237], 0, v[182:183]
	v_lshl_add_u64 v[238:239], v[238:239], 0, v[184:185]
	v_lshl_add_u64 v[240:241], v[240:241], 0, v[182:183]
	v_lshl_add_u64 v[242:243], v[242:243], 0, v[184:185]
	v_lshl_add_u64 v[152:153], v[152:153], 0, v[182:183]
	v_lshl_add_u64 v[154:155], v[154:155], 0, v[184:185]
	v_lshl_add_u64 v[244:245], v[244:245], 0, v[182:183]
	v_lshl_add_u64 v[246:247], v[246:247], 0, v[184:185]
	v_lshl_add_u64 v[248:249], v[248:249], 0, v[182:183]
	v_lshl_add_u64 v[250:251], v[250:251], 0, v[184:185]
	s_mov_b32 s58, s53
	s_add_i32 m0, s58, 0x0
	s_nop 0
	global_load_lds_dwordx4 v[186:187], off
	s_add_i32 m0, s58, 0x400
	v_lshl_add_u64 v[186:187], v[186:187], 0, s[54:55]
	global_load_lds_dwordx4 v[234:235], off
	s_add_i32 m0, s58, 0x2000
	v_lshl_add_u64 v[234:235], v[234:235], 0, s[54:55]
	global_load_lds_dwordx4 v[236:237], off
	s_add_i32 m0, s58, 0x2400
	v_lshl_add_u64 v[236:237], v[236:237], 0, s[54:55]
	global_load_lds_dwordx4 v[238:239], off
	s_add_i32 m0, s58, 0x4000
	v_lshl_add_u64 v[238:239], v[238:239], 0, s[54:55]
	global_load_lds_dwordx4 v[240:241], off
	s_add_i32 m0, s58, 0x4400
	v_lshl_add_u64 v[240:241], v[240:241], 0, s[54:55]
	global_load_lds_dwordx4 v[242:243], off
	s_add_i32 m0, s58, 0x6000
	v_lshl_add_u64 v[242:243], v[242:243], 0, s[54:55]
	global_load_lds_dwordx4 v[152:153], off
	s_add_i32 m0, s58, 0x6400
	v_lshl_add_u64 v[152:153], v[152:153], 0, s[54:55]
	global_load_lds_dwordx4 v[154:155], off
	v_lshl_add_u64 v[154:155], v[154:155], 0, s[54:55]
	s_add_i32 s58, s53, 0x10000
	s_add_i32 m0, s58, 0x0
	s_nop 0
	global_load_lds_dwordx4 v[244:245], off
	s_add_i32 m0, s58, 0x400
	v_lshl_add_u64 v[244:245], v[244:245], 0, s[54:55]
	global_load_lds_dwordx4 v[246:247], off
	s_add_i32 m0, s58, 0x2000
	v_lshl_add_u64 v[246:247], v[246:247], 0, s[54:55]
	global_load_lds_dwordx4 v[248:249], off
	s_add_i32 m0, s58, 0x2400
	v_lshl_add_u64 v[248:249], v[248:249], 0, s[54:55]
	global_load_lds_dwordx4 v[250:251], off
	v_lshl_add_u64 v[250:251], v[250:251], 0, s[54:55]
	s_mov_b32 s24, 0
	s_mov_b32 s25, 0
	s_setprio 1

.Lg_ph11b_noB:
	s_setprio 2
	s_waitcnt lgkmcnt(3)
	v_mfma_f32_16x16x32_bf16 v[0:3], v[144:147], v[190:193], v[0:3]
	v_mfma_f32_16x16x32_bf16 v[4:7], v[144:147], v[194:197], v[4:7]
	v_mfma_f32_16x16x32_bf16 v[8:11], v[144:147], v[198:201], v[8:11]
	v_mfma_f32_16x16x32_bf16 v[12:15], v[144:147], v[202:205], v[12:15]
	ds_read_b128 v[144:147], v136 offset:8192
	s_waitcnt lgkmcnt(3)
	v_mfma_f32_16x16x32_bf16 v[16:19], v[148:151], v[190:193], v[16:19]
	v_mfma_f32_16x16x32_bf16 v[20:23], v[148:151], v[194:197], v[20:23]
	v_mfma_f32_16x16x32_bf16 v[24:27], v[148:151], v[198:201], v[24:27]
	v_mfma_f32_16x16x32_bf16 v[28:31], v[148:151], v[202:205], v[28:31]
	ds_read_b128 v[148:151], v136 offset:10240
	s_waitcnt lgkmcnt(3)
	v_mfma_f32_16x16x32_bf16 v[32:35], v[156:159], v[190:193], v[32:35]
	v_mfma_f32_16x16x32_bf16 v[36:39], v[156:159], v[194:197], v[36:39]
	v_mfma_f32_16x16x32_bf16 v[40:43], v[156:159], v[198:201], v[40:43]
	v_mfma_f32_16x16x32_bf16 v[44:47], v[156:159], v[202:205], v[44:47]
	ds_read_b128 v[156:159], v136 offset:12288
	s_waitcnt lgkmcnt(3)
	v_mfma_f32_16x16x32_bf16 v[48:51], v[182:185], v[190:193], v[48:51]
	v_mfma_f32_16x16x32_bf16 v[52:55], v[182:185], v[194:197], v[52:55]
	v_mfma_f32_16x16x32_bf16 v[56:59], v[182:185], v[198:201], v[56:59]
	v_mfma_f32_16x16x32_bf16 v[60:63], v[182:185], v[202:205], v[60:63]
	ds_read_b128 v[182:185], v136 offset:14336
	s_waitcnt lgkmcnt(3)
	v_mfma_f32_16x16x32_bf16 v[64:67], v[144:147], v[190:193], v[64:67]
	v_mfma_f32_16x16x32_bf16 v[68:71], v[144:147], v[194:197], v[68:71]
	v_mfma_f32_16x16x32_bf16 v[72:75], v[144:147], v[198:201], v[72:75]
	v_mfma_f32_16x16x32_bf16 v[76:79], v[144:147], v[202:205], v[76:79]
	ds_read_b128 v[144:147], v137
	s_waitcnt lgkmcnt(3)
	v_mfma_f32_16x16x32_bf16 v[80:83], v[148:151], v[190:193], v[80:83]
	v_mfma_f32_16x16x32_bf16 v[84:87], v[148:151], v[194:197], v[84:87]
	v_mfma_f32_16x16x32_bf16 v[88:91], v[148:151], v[198:201], v[88:91]
	v_mfma_f32_16x16x32_bf16 v[92:95], v[148:151], v[202:205], v[92:95]
	ds_read_b128 v[148:151], v137 offset:2048
	s_waitcnt lgkmcnt(3)
	v_mfma_f32_16x16x32_bf16 v[96:99], v[156:159], v[190:193], v[96:99]
	v_mfma_f32_16x16x32_bf16 v[100:103], v[156:159], v[194:197], v[100:103]
	v_mfma_f32_16x16x32_bf16 v[104:107], v[156:159], v[198:201], v[104:107]
	v_mfma_f32_16x16x32_bf16 v[108:111], v[156:159], v[202:205], v[108:111]
	ds_read_b128 v[156:159], v137 offset:4096
	s_waitcnt lgkmcnt(3)
	v_mfma_f32_16x16x32_bf16 v[112:115], v[182:185], v[190:193], v[112:115]
	v_mfma_f32_16x16x32_bf16 v[116:119], v[182:185], v[194:197], v[116:119]
	v_mfma_f32_16x16x32_bf16 v[120:123], v[182:185], v[198:201], v[120:123]
	v_mfma_f32_16x16x32_bf16 v[124:127], v[182:185], v[202:205], v[124:127]
	ds_read_b128 v[182:185], v137 offset:6144
	s_waitcnt lgkmcnt(3)
	v_mfma_f32_16x16x32_bf16 v[0:3], v[144:147], v[206:209], v[0:3]
	v_mfma_f32_16x16x32_bf16 v[4:7], v[144:147], v[222:225], v[4:7]
	v_mfma_f32_16x16x32_bf16 v[8:11], v[144:147], v[226:229], v[8:11]
	v_mfma_f32_16x16x32_bf16 v[12:15], v[144:147], v[230:233], v[12:15]
	ds_read_b128 v[144:147], v137 offset:8192
	s_waitcnt lgkmcnt(3)
	v_mfma_f32_16x16x32_bf16 v[16:19], v[148:151], v[206:209], v[16:19]
	v_mfma_f32_16x16x32_bf16 v[20:23], v[148:151], v[222:225], v[20:23]
	v_mfma_f32_16x16x32_bf16 v[24:27], v[148:151], v[226:229], v[24:27]
	v_mfma_f32_16x16x32_bf16 v[28:31], v[148:151], v[230:233], v[28:31]
	ds_read_b128 v[148:151], v137 offset:10240
	s_waitcnt lgkmcnt(3)
	v_mfma_f32_16x16x32_bf16 v[32:35], v[156:159], v[206:209], v[32:35]
	v_mfma_f32_16x16x32_bf16 v[36:39], v[156:159], v[222:225], v[36:39]
	v_mfma_f32_16x16x32_bf16 v[40:43], v[156:159], v[226:229], v[40:43]
	v_mfma_f32_16x16x32_bf16 v[44:47], v[156:159], v[230:233], v[44:47]
	ds_read_b128 v[156:159], v137 offset:12288
	s_waitcnt lgkmcnt(3)
	v_mfma_f32_16x16x32_bf16 v[48:51], v[182:185], v[206:209], v[48:51]
	v_mfma_f32_16x16x32_bf16 v[52:55], v[182:185], v[222:225], v[52:55]
	v_mfma_f32_16x16x32_bf16 v[56:59], v[182:185], v[226:229], v[56:59]
	v_mfma_f32_16x16x32_bf16 v[60:63], v[182:185], v[230:233], v[60:63]
	ds_read_b128 v[182:185], v137 offset:14336
	s_waitcnt lgkmcnt(3)
	v_mfma_f32_16x16x32_bf16 v[64:67], v[144:147], v[206:209], v[64:67]
	v_mfma_f32_16x16x32_bf16 v[68:71], v[144:147], v[222:225], v[68:71]
	v_mfma_f32_16x16x32_bf16 v[72:75], v[144:147], v[226:229], v[72:75]
	v_mfma_f32_16x16x32_bf16 v[76:79], v[144:147], v[230:233], v[76:79]
	s_waitcnt lgkmcnt(2)
	v_mfma_f32_16x16x32_bf16 v[80:83], v[148:151], v[206:209], v[80:83]
	v_mfma_f32_16x16x32_bf16 v[84:87], v[148:151], v[222:225], v[84:87]
	v_mfma_f32_16x16x32_bf16 v[88:91], v[148:151], v[226:229], v[88:91]
	v_mfma_f32_16x16x32_bf16 v[92:95], v[148:151], v[230:233], v[92:95]
	s_waitcnt lgkmcnt(1)
	v_mfma_f32_16x16x32_bf16 v[96:99], v[156:159], v[206:209], v[96:99]
	v_mfma_f32_16x16x32_bf16 v[100:103], v[156:159], v[222:225], v[100:103]
	v_mfma_f32_16x16x32_bf16 v[104:107], v[156:159], v[226:229], v[104:107]
	v_mfma_f32_16x16x32_bf16 v[108:111], v[156:159], v[230:233], v[108:111]
	s_waitcnt lgkmcnt(0)
	v_mfma_f32_16x16x32_bf16 v[112:115], v[182:185], v[206:209], v[112:115]
	v_mfma_f32_16x16x32_bf16 v[116:119], v[182:185], v[222:225], v[116:119]
	v_mfma_f32_16x16x32_bf16 v[120:123], v[182:185], v[226:229], v[120:123]
	v_mfma_f32_16x16x32_bf16 v[124:127], v[182:185], v[230:233], v[124:127]
	s_setprio 1
	v_xor_b32_e32 v136, 0x8000, v136
	v_xor_b32_e32 v137, 0x8000, v137
	s_xor_b32 s25, s25, 0x8000
	s_add_i32 s24, s24, 1
	s_cmp_eq_u32 s24, 16
	s_cbranch_scc0 .Lg_ph11b_top
	s_setprio 0
	s_waitcnt vmcnt(0)
	v_mov_b32_e32 v130, v180
	v_add_u32_e32 v192, 0x400, v166
	v_add_u32_e32 v191, 0x1000, v166
	v_add_u32_e32 v190, 0x1400, v166
	v_add_u32_e32 v189, 0x2000, v166
	v_add_u32_e32 v182, 0x2400, v166
	v_add_u32_e32 v183, 0x3000, v166
	v_add_u32_e32 v184, 0x3200, v166
	v_add_u32_e32 v185, 0x3400, v166
	v_add_u32_e32 v186, 0x3600, v166
	v_add_u32_e32 v187, 0x4000, v166
	v_add_u32_e32 v159, 0x4400, v166
	v_add_u32_e32 v179, 0x4800, v166
	v_add_u32_e32 v181, 0x5000, v166
	v_add_u32_e32 v156, 0x5400, v166
	v_add_u32_e32 v157, 0x5800, v166
	v_add_u32_e32 v158, 0x6000, v166
	v_add_u32_e32 v150, 0x6400, v166
	v_add_u32_e32 v151, 0x6800, v166
	v_add_u32_e32 v152, 0x7200, v166
	v_add_u32_e32 v153, 0x7400, v166
	v_add_u32_e32 v154, 0x7600, v166
	v_add_u32_e32 v155, 0x7800, v166
	v_add_u32_e32 v149, 0x8400, v166
	v_add_u32_e32 v148, 0x8800, v166
	v_add_u32_e32 v147, 0x9400, v166
	v_add_u32_e32 v146, 0x9800, v166
	v_add_u32_e32 v145, 0xa400, v166
	v_add_u32_e32 v140, 0xa800, v166
	v_add_u32_e32 v141, 0xb400, v166
	v_add_u32_e32 v142, 0xb600, v166
	v_add_u32_e32 v143, 0xb800, v166
	v_add_u32_e32 v144, 0xba00, v166
	s_waitcnt vmcnt(0)
	s_barrier
	s_and_saveexec_b64 s[24:25], s[6:7]
	s_cbranch_execz .LBB0_1187
	v_and_b32_e32 v254, 63, v180
	v_lshrrev_b32_e32 v253, 4, v254
	v_mul_u32_u24_e32 v253, 0x840, v253
	v_and_b32_e32 v254, 15, v254
	v_lshl_add_u32 v253, v254, 2, v253
	v_and_b32_e32 v254, 64, v180
	v_lshl_add_u32 v253, v254, 2, v253
	ds_write_b32 v253, v0 offset:0
	ds_write_b32 v253, v1 offset:528
	ds_write_b32 v253, v2 offset:1056
	ds_write_b32 v253, v3 offset:1584
	ds_write_b32 v253, v4 offset:64
	ds_write_b32 v253, v5 offset:592
	ds_write_b32 v253, v6 offset:1120
	ds_write_b32 v253, v7 offset:1648
	ds_write_b32 v253, v8 offset:128
	ds_write_b32 v253, v9 offset:656
	ds_write_b32 v253, v10 offset:1184
	ds_write_b32 v253, v11 offset:1712
	ds_write_b32 v253, v12 offset:192
	ds_write_b32 v253, v13 offset:720
	ds_write_b32 v253, v14 offset:1248
	ds_write_b32 v253, v15 offset:1776
	ds_write_b32 v253, v16 offset:8448
	ds_write_b32 v253, v17 offset:8976
	ds_write_b32 v253, v18 offset:9504
	ds_write_b32 v253, v19 offset:10032
	ds_write_b32 v253, v20 offset:8512
	ds_write_b32 v253, v21 offset:9040
	ds_write_b32 v253, v22 offset:9568
	ds_write_b32 v253, v23 offset:10096
	ds_write_b32 v253, v24 offset:8576
	ds_write_b32 v253, v25 offset:9104
	ds_write_b32 v253, v26 offset:9632
	ds_write_b32 v253, v27 offset:10160
	ds_write_b32 v253, v28 offset:8640
	ds_write_b32 v253, v29 offset:9168
	ds_write_b32 v253, v30 offset:9696
	ds_write_b32 v253, v31 offset:10224
	ds_write_b32 v253, v32 offset:16896
	ds_write_b32 v253, v33 offset:17424
	ds_write_b32 v253, v34 offset:17952
	ds_write_b32 v253, v35 offset:18480
	ds_write_b32 v253, v36 offset:16960
	ds_write_b32 v253, v37 offset:17488
	ds_write_b32 v253, v38 offset:18016
	ds_write_b32 v253, v39 offset:18544
	ds_write_b32 v253, v40 offset:17024
	ds_write_b32 v253, v41 offset:17552
	ds_write_b32 v253, v42 offset:18080
	ds_write_b32 v253, v43 offset:18608
	ds_write_b32 v253, v44 offset:17088
	ds_write_b32 v253, v45 offset:17616
	ds_write_b32 v253, v46 offset:18144
	ds_write_b32 v253, v47 offset:18672
	ds_write_b32 v253, v48 offset:25344
	ds_write_b32 v253, v49 offset:25872
	ds_write_b32 v253, v50 offset:26400
	ds_write_b32 v253, v51 offset:26928
	ds_write_b32 v253, v52 offset:25408
	ds_write_b32 v253, v53 offset:25936
	ds_write_b32 v253, v54 offset:26464
	ds_write_b32 v253, v55 offset:26992
	ds_write_b32 v253, v56 offset:25472
	ds_write_b32 v253, v57 offset:26000
	ds_write_b32 v253, v58 offset:26528
	ds_write_b32 v253, v59 offset:27056
	ds_write_b32 v253, v60 offset:25536
	ds_write_b32 v253, v61 offset:26064
	ds_write_b32 v253, v62 offset:26592
	ds_write_b32 v253, v63 offset:27120
	ds_write_b32 v253, v64 offset:33792
	ds_write_b32 v253, v65 offset:34320
	ds_write_b32 v253, v66 offset:34848
	ds_write_b32 v253, v67 offset:35376
	ds_write_b32 v253, v68 offset:33856
	ds_write_b32 v253, v69 offset:34384
	ds_write_b32 v253, v70 offset:34912
	ds_write_b32 v253, v71 offset:35440
	ds_write_b32 v253, v72 offset:33920
	ds_write_b32 v253, v73 offset:34448
	ds_write_b32 v253, v74 offset:34976
	ds_write_b32 v253, v75 offset:35504
	ds_write_b32 v253, v76 offset:33984
	ds_write_b32 v253, v77 offset:34512
	ds_write_b32 v253, v78 offset:35040
	ds_write_b32 v253, v79 offset:35568
	ds_write_b32 v253, v80 offset:42240
	ds_write_b32 v253, v81 offset:42768
	ds_write_b32 v253, v82 offset:43296
	ds_write_b32 v253, v83 offset:43824
	ds_write_b32 v253, v84 offset:42304
	ds_write_b32 v253, v85 offset:42832
	ds_write_b32 v253, v86 offset:43360
	ds_write_b32 v253, v87 offset:43888
	ds_write_b32 v253, v88 offset:42368
	ds_write_b32 v253, v89 offset:42896
	ds_write_b32 v253, v90 offset:43424
	ds_write_b32 v253, v91 offset:43952
	ds_write_b32 v253, v92 offset:42432
	ds_write_b32 v253, v93 offset:42960
	ds_write_b32 v253, v94 offset:43488
	ds_write_b32 v253, v95 offset:44016
	ds_write_b32 v253, v96 offset:50688
	ds_write_b32 v253, v97 offset:51216
	ds_write_b32 v253, v98 offset:51744
	ds_write_b32 v253, v99 offset:52272
	ds_write_b32 v253, v100 offset:50752
	ds_write_b32 v253, v101 offset:51280
	ds_write_b32 v253, v102 offset:51808
	ds_write_b32 v253, v103 offset:52336
	ds_write_b32 v253, v104 offset:50816
	ds_write_b32 v253, v105 offset:51344
	ds_write_b32 v253, v106 offset:51872
	ds_write_b32 v253, v107 offset:52400
	ds_write_b32 v253, v108 offset:50880
	ds_write_b32 v253, v109 offset:51408
	ds_write_b32 v253, v110 offset:51936
	ds_write_b32 v253, v111 offset:52464
	ds_write_b32 v253, v112 offset:59136
	ds_write_b32 v253, v113 offset:59664
	ds_write_b32 v253, v114 offset:60192
	ds_write_b32 v253, v115 offset:60720
	ds_write_b32 v253, v116 offset:59200
	ds_write_b32 v253, v117 offset:59728
	ds_write_b32 v253, v118 offset:60256
	ds_write_b32 v253, v119 offset:60784
	ds_write_b32 v253, v120 offset:59264
	ds_write_b32 v253, v121 offset:59792
	ds_write_b32 v253, v122 offset:60320
	ds_write_b32 v253, v123 offset:60848
	ds_write_b32 v253, v124 offset:59328
	ds_write_b32 v253, v125 offset:59856
	ds_write_b32 v253, v126 offset:60384
	ds_write_b32 v253, v127 offset:60912

.LBB0_1315:
	s_lshr_b32 s4, s23, 3
	s_or_b32 s4, s4, s24
	s_lshl_b32 s30, s4, 18
	s_and_b32 s29, s23, 7
	v_or_b32_e32 v1, s30, v129
	s_lshl_b32 s4, s29, 18
	s_add_u32 s16, s18, s4
	v_or_b32_e32 v0, v1, v128
	v_readfirstlane_b32 s4, v148
	v_lshlrev_b32_e32 v130, 1, v0
	s_mov_b32 m0, s4
	v_readfirstlane_b32 s4, v157
	v_add_lshl_u32 v0, v1, v154, 1
	s_waitcnt vmcnt(0)
	s_barrier
	s_nop 0
	s_mov_b32 m0, s4
	v_readfirstlane_b32 s4, v158
	s_addc_u32 s17, s19, 0
	v_add_lshl_u32 v2, v1, v155, 1
	s_nop 0
	s_mov_b32 m0, s4
	v_readfirstlane_b32 s4, v159
	v_add_lshl_u32 v4, v1, v156, 1
	v_lshl_add_u64 v[6:7], s[16:17], 0, v[132:133]
	s_nop 0
	s_mov_b32 m0, s4
	v_readfirstlane_b32 s4, v160
	v_lshl_add_u64 v[136:137], v[6:7], 0, v[134:135]
	s_nop 0
	s_mov_b32 m0, s4
	v_readfirstlane_b32 s4, v161
	v_lshl_add_u64 v[138:139], s[2:3], 0, v[130:131]
	v_mov_b32_e32 v1, v131
	v_lshl_add_u64 v[146:147], v[136:137], 0, s[10:11]
	s_nop 0
	s_mov_b32 m0, s4
	v_readfirstlane_b32 s4, v162
	v_lshl_add_u64 v[140:141], s[2:3], 0, v[0:1]
	v_mov_b32_e32 v3, v131
	s_nop 0
	v_lshl_add_u64 v[0:1], v[138:139], 0, 64
	s_mov_b32 m0, s4
	v_readfirstlane_b32 s4, v163
	v_lshl_add_u64 v[142:143], s[2:3], 0, v[2:3]
	v_mov_b32_e32 v5, v131
	s_nop 0
	v_lshl_add_u64 v[0:1], v[140:141], 0, 64
	s_mov_b32 m0, s4
	v_readfirstlane_b32 s4, v164
	v_lshl_add_u64 v[144:145], s[2:3], 0, v[4:5]
	s_nop 0
	v_lshl_add_u64 v[0:1], v[142:143], 0, 64
	s_mov_b32 m0, s4
	v_readfirstlane_b32 s4, v165
	s_nop 0
	v_lshl_add_u64 v[0:1], v[144:145], 0, 64
	s_mov_b32 m0, s4
	v_readfirstlane_b32 s4, v166
	s_nop 0
	v_lshl_add_u64 v[0:1], v[136:137], 0, 64
	s_mov_b32 m0, s4
	v_readfirstlane_b32 s4, v167
	s_nop 0
	v_lshl_add_u64 v[0:1], v[136:137], 0, s[12:13]
	s_mov_b32 m0, s4
	s_mov_b32 s16, s5
	s_nop 0
	s_mov_b32 s17, 2
	s_mov_b32 s31, s5
	v_mov_b32_e32 v0, 0
	v_mov_b32_e32 v1, v131
	v_mov_b32_e32 v2, v131
	v_mov_b32_e32 v4, v131
	v_mov_b32_e32 v6, v131
	v_mov_b32_e32 v7, v131
	v_mov_b32_e32 v8, v131
	v_mov_b32_e32 v9, v131
	v_mov_b32_e32 v10, v131
	v_mov_b32_e32 v11, v131
	v_mov_b32_e32 v12, v131
	v_mov_b32_e32 v13, v131
	v_mov_b32_e32 v14, v131
	v_mov_b32_e32 v15, v131
	v_mov_b32_e32 v16, 0
	v_mov_b32_e32 v17, v131
	v_mov_b32_e32 v18, v131
	v_mov_b32_e32 v19, v131
	v_mov_b32_e32 v20, v131
	v_mov_b32_e32 v21, v131
	v_mov_b32_e32 v22, v131
	v_mov_b32_e32 v23, v131
	v_mov_b32_e32 v24, v131
	v_mov_b32_e32 v25, v131
	v_mov_b32_e32 v26, v131
	v_mov_b32_e32 v27, v131
	v_mov_b32_e32 v28, v131
	v_mov_b32_e32 v29, v131
	v_mov_b32_e32 v30, v131
	v_mov_b32_e32 v31, v131
	v_mov_b32_e32 v32, 0
	v_mov_b32_e32 v33, v131
	v_mov_b32_e32 v34, v131
	v_mov_b32_e32 v35, v131
	v_mov_b32_e32 v36, v131
	v_mov_b32_e32 v37, v131
	v_mov_b32_e32 v38, v131
	v_mov_b32_e32 v39, v131
	v_mov_b32_e32 v40, v131
	v_mov_b32_e32 v41, v131
	v_mov_b32_e32 v42, v131
	v_mov_b32_e32 v43, v131
	v_mov_b32_e32 v44, v131
	v_mov_b32_e32 v45, v131
	v_mov_b32_e32 v46, v131
	v_mov_b32_e32 v47, v131
	v_mov_b32_e32 v48, 0
	v_mov_b32_e32 v49, v131
	v_mov_b32_e32 v50, v131
	v_mov_b32_e32 v51, v131
	v_mov_b32_e32 v52, v131
	v_mov_b32_e32 v53, v131
	v_mov_b32_e32 v54, v131
	v_mov_b32_e32 v55, v131
	v_mov_b32_e32 v56, v131
	v_mov_b32_e32 v57, v131
	v_mov_b32_e32 v58, v131
	v_mov_b32_e32 v59, v131
	v_mov_b32_e32 v60, v131
	v_mov_b32_e32 v61, v131
	v_mov_b32_e32 v62, v131
	v_mov_b32_e32 v63, v131
	v_mov_b32_e32 v64, 0
	v_mov_b32_e32 v65, v131
	v_mov_b32_e32 v66, v131
	v_mov_b32_e32 v67, v131
	v_mov_b32_e32 v68, v131
	v_mov_b32_e32 v69, v131
	v_mov_b32_e32 v70, v131
	v_mov_b32_e32 v71, v131
	v_mov_b32_e32 v72, v131
	v_mov_b32_e32 v73, v131
	v_mov_b32_e32 v74, v131
	v_mov_b32_e32 v75, v131
	v_mov_b32_e32 v76, v131
	v_mov_b32_e32 v77, v131
	v_mov_b32_e32 v78, v131
	v_mov_b32_e32 v79, v131
	v_mov_b32_e32 v80, 0
	v_mov_b32_e32 v81, v131
	v_mov_b32_e32 v82, v131
	v_mov_b32_e32 v83, v131
	v_mov_b32_e32 v84, v131
	v_mov_b32_e32 v85, v131
	v_mov_b32_e32 v86, v131
	v_mov_b32_e32 v87, v131
	v_mov_b32_e32 v88, v131
	v_mov_b32_e32 v89, v131
	v_mov_b32_e32 v90, v131
	v_mov_b32_e32 v91, v131
	v_mov_b32_e32 v92, v131
	v_mov_b32_e32 v93, v131
	v_mov_b32_e32 v94, v131
	v_mov_b32_e32 v95, v131
	v_mov_b32_e32 v96, 0
	v_mov_b32_e32 v97, v131
	v_mov_b32_e32 v98, v131
	v_mov_b32_e32 v99, v131
	v_mov_b32_e32 v100, v131
	v_mov_b32_e32 v101, v131
	v_mov_b32_e32 v102, v131
	v_mov_b32_e32 v103, v131
	v_mov_b32_e32 v104, v131
	v_mov_b32_e32 v105, v131
	v_mov_b32_e32 v106, v131
	v_mov_b32_e32 v107, v131
	v_mov_b32_e32 v108, v131
	v_mov_b32_e32 v109, v131
	v_mov_b32_e32 v110, v131
	v_mov_b32_e32 v111, v131
	v_mov_b32_e32 v112, 0
	v_mov_b32_e32 v113, v131
	v_mov_b32_e32 v114, v131
	v_mov_b32_e32 v115, v131
	v_mov_b32_e32 v116, v131
	v_mov_b32_e32 v117, v131
	v_mov_b32_e32 v118, v131
	v_mov_b32_e32 v119, v131
	v_mov_b32_e32 v120, v131
	v_mov_b32_e32 v121, v131
	v_mov_b32_e32 v122, v131
	v_mov_b32_e32 v123, v131
	v_mov_b32_e32 v124, v131
	v_mov_b32_e32 v125, v131
	v_mov_b32_e32 v126, v131
	v_mov_b32_e32 v127, v131
	s_mov_b64 s[54:55], 0x80
	v_lshrrev_b32_e32 v174, 6, v180
	v_lshlrev_b32_e32 v184, 11, v174
	v_and_b32_e32 v170, 63, v180
	v_readfirstlane_b32 s53, v184
	v_lshrrev_b32_e32 v171, 4, v170
	v_bfe_u32 v172, v170, 1, 3
	v_xor_b32_e32 v172, v171, v172
	v_and_b32_e32 v173, 31, v170
	v_lshlrev_b32_e32 v173, 7, v173
	v_lshrrev_b32_e32 v173, 3, v170
	v_lshlrev_b32_e32 v184, 4, v173
	v_add_u32_e32 v185, 0x80, v184
	v_and_b32_e32 v173, 7, v170
	v_lshrrev_b32_e32 v171, 4, v170
	v_xor_b32_e32 v171, v173, v171
	v_lshrrev_b32_e32 v173, 5, v170
	v_sub_u32_e32 v190, v171, v173
	v_xor_b32_e32 v171, 4, v171
	v_add_u32_e32 v173, 2, v173
	v_sub_u32_e32 v192, v171, v173
	v_lshlrev_b32_e32 v190, 4, v190
	v_ashrrev_i32_e32 v191, 31, v190
	v_lshlrev_b32_e32 v192, 4, v192
	v_ashrrev_i32_e32 v193, 31, v192
	ds_bpermute_b32 v242, v184, v136
	ds_bpermute_b32 v243, v184, v137
	ds_bpermute_b32 v244, v185, v136
	ds_bpermute_b32 v245, v185, v137
	ds_bpermute_b32 v246, v184, v146
	ds_bpermute_b32 v247, v184, v147
	ds_bpermute_b32 v248, v185, v146
	ds_bpermute_b32 v249, v185, v147
	s_waitcnt lgkmcnt(0)
	ds_bpermute_b32 v178, v184, v138
	ds_bpermute_b32 v179, v184, v139
	ds_bpermute_b32 v186, v185, v138
	ds_bpermute_b32 v187, v185, v139
	ds_bpermute_b32 v234, v184, v140
	ds_bpermute_b32 v235, v184, v141
	ds_bpermute_b32 v236, v185, v140
	ds_bpermute_b32 v237, v185, v141
	ds_bpermute_b32 v238, v184, v142
	ds_bpermute_b32 v239, v184, v143
	ds_bpermute_b32 v240, v185, v142
	ds_bpermute_b32 v241, v185, v143
	ds_bpermute_b32 v136, v184, v144
	ds_bpermute_b32 v137, v184, v145
	ds_bpermute_b32 v146, v185, v144
	ds_bpermute_b32 v147, v185, v145
	s_waitcnt lgkmcnt(0)
	v_and_b32_e32 v173, 15, v170
	v_lshlrev_b32_e32 v173, 7, v173
	v_lshrrev_b32_e32 v171, 1, v174
	v_lshl_add_u32 v138, v171, 14, v173
	v_and_b32_e32 v171, 1, v174
	v_lshl_add_u32 v142, v171, 13, v173
	v_add_u32_e32 v142, 0x10000, v142
	v_xor_b32_e32 v173, 4, v172
	v_lshl_add_u32 v139, v173, 4, v138
	v_lshl_add_u32 v143, v173, 4, v142
	v_xor_b32_e32 v173, 0, v172
	v_lshl_add_u32 v138, v173, 4, v138
	v_lshl_add_u32 v142, v173, 4, v142
	v_lshl_add_u64 v[178:179], v[178:179], 0, v[190:191]
	v_lshl_add_u64 v[186:187], v[186:187], 0, v[192:193]
	v_lshl_add_u64 v[234:235], v[234:235], 0, v[190:191]
	v_lshl_add_u64 v[236:237], v[236:237], 0, v[192:193]
	v_lshl_add_u64 v[238:239], v[238:239], 0, v[190:191]
	v_lshl_add_u64 v[240:241], v[240:241], 0, v[192:193]
	v_lshl_add_u64 v[136:137], v[136:137], 0, v[190:191]
	v_lshl_add_u64 v[146:147], v[146:147], 0, v[192:193]
	v_lshl_add_u64 v[242:243], v[242:243], 0, v[190:191]
	v_lshl_add_u64 v[244:245], v[244:245], 0, v[192:193]
	v_lshl_add_u64 v[246:247], v[246:247], 0, v[190:191]
	v_lshl_add_u64 v[248:249], v[248:249], 0, v[192:193]
	s_mov_b32 s58, s53
	s_add_i32 m0, s58, 0x0
	s_nop 0
	global_load_lds_dwordx4 v[178:179], off
	s_add_i32 m0, s58, 0x400
	v_lshl_add_u64 v[178:179], v[178:179], 0, s[54:55]
	global_load_lds_dwordx4 v[186:187], off
	s_add_i32 m0, s58, 0x2000
	v_lshl_add_u64 v[186:187], v[186:187], 0, s[54:55]
	global_load_lds_dwordx4 v[234:235], off
	s_add_i32 m0, s58, 0x2400
	v_lshl_add_u64 v[234:235], v[234:235], 0, s[54:55]
	global_load_lds_dwordx4 v[236:237], off
	s_add_i32 m0, s58, 0x4000
	v_lshl_add_u64 v[236:237], v[236:237], 0, s[54:55]
	global_load_lds_dwordx4 v[238:239], off
	s_add_i32 m0, s58, 0x4400
	v_lshl_add_u64 v[238:239], v[238:239], 0, s[54:55]
	global_load_lds_dwordx4 v[240:241], off
	s_add_i32 m0, s58, 0x6000
	v_lshl_add_u64 v[240:241], v[240:241], 0, s[54:55]
	global_load_lds_dwordx4 v[136:137], off
	s_add_i32 m0, s58, 0x6400
	v_lshl_add_u64 v[136:137], v[136:137], 0, s[54:55]
	global_load_lds_dwordx4 v[146:147], off
	v_lshl_add_u64 v[146:147], v[146:147], 0, s[54:55]
	s_add_i32 s58, s53, 0x10000
	s_add_i32 m0, s58, 0x0
	s_nop 0
	global_load_lds_dwordx4 v[242:243], off
	s_add_i32 m0, s58, 0x400
	v_lshl_add_u64 v[242:243], v[242:243], 0, s[54:55]
	global_load_lds_dwordx4 v[244:245], off
	s_add_i32 m0, s58, 0x2000
	v_lshl_add_u64 v[244:245], v[244:245], 0, s[54:55]
	global_load_lds_dwordx4 v[246:247], off
	s_add_i32 m0, s58, 0x2400
	v_lshl_add_u64 v[246:247], v[246:247], 0, s[54:55]
	global_load_lds_dwordx4 v[248:249], off
	v_lshl_add_u64 v[248:249], v[248:249], 0, s[54:55]
	s_mov_b32 s16, 0
	s_mov_b32 s17, 0
	s_setprio 1

.Lg_ph13_noB:
	s_setprio 2
	s_waitcnt lgkmcnt(3)
	v_mfma_f32_16x16x32_bf16 v[0:3], v[170:173], v[194:197], v[0:3]
	v_mfma_f32_16x16x32_bf16 v[4:7], v[170:173], v[198:201], v[4:7]
	v_mfma_f32_16x16x32_bf16 v[8:11], v[170:173], v[202:205], v[8:11]
	v_mfma_f32_16x16x32_bf16 v[12:15], v[170:173], v[206:209], v[12:15]
	ds_read_b128 v[170:173], v138 offset:8192
	s_waitcnt lgkmcnt(3)
	v_mfma_f32_16x16x32_bf16 v[16:19], v[174:177], v[194:197], v[16:19]
	v_mfma_f32_16x16x32_bf16 v[20:23], v[174:177], v[198:201], v[20:23]
	v_mfma_f32_16x16x32_bf16 v[24:27], v[174:177], v[202:205], v[24:27]
	v_mfma_f32_16x16x32_bf16 v[28:31], v[174:177], v[206:209], v[28:31]
	ds_read_b128 v[174:177], v138 offset:10240
	s_waitcnt lgkmcnt(3)
	v_mfma_f32_16x16x32_bf16 v[32:35], v[182:185], v[194:197], v[32:35]
	v_mfma_f32_16x16x32_bf16 v[36:39], v[182:185], v[198:201], v[36:39]
	v_mfma_f32_16x16x32_bf16 v[40:43], v[182:185], v[202:205], v[40:43]
	v_mfma_f32_16x16x32_bf16 v[44:47], v[182:185], v[206:209], v[44:47]
	ds_read_b128 v[182:185], v138 offset:12288
	s_waitcnt lgkmcnt(3)
	v_mfma_f32_16x16x32_bf16 v[48:51], v[190:193], v[194:197], v[48:51]
	v_mfma_f32_16x16x32_bf16 v[52:55], v[190:193], v[198:201], v[52:55]
	v_mfma_f32_16x16x32_bf16 v[56:59], v[190:193], v[202:205], v[56:59]
	v_mfma_f32_16x16x32_bf16 v[60:63], v[190:193], v[206:209], v[60:63]
	ds_read_b128 v[190:193], v138 offset:14336
	s_waitcnt lgkmcnt(3)
	v_mfma_f32_16x16x32_bf16 v[64:67], v[170:173], v[194:197], v[64:67]
	v_mfma_f32_16x16x32_bf16 v[68:71], v[170:173], v[198:201], v[68:71]
	v_mfma_f32_16x16x32_bf16 v[72:75], v[170:173], v[202:205], v[72:75]
	v_mfma_f32_16x16x32_bf16 v[76:79], v[170:173], v[206:209], v[76:79]
	ds_read_b128 v[170:173], v139
	s_waitcnt lgkmcnt(3)
	v_mfma_f32_16x16x32_bf16 v[80:83], v[174:177], v[194:197], v[80:83]
	v_mfma_f32_16x16x32_bf16 v[84:87], v[174:177], v[198:201], v[84:87]
	v_mfma_f32_16x16x32_bf16 v[88:91], v[174:177], v[202:205], v[88:91]
	v_mfma_f32_16x16x32_bf16 v[92:95], v[174:177], v[206:209], v[92:95]
	ds_read_b128 v[174:177], v139 offset:2048
	s_waitcnt lgkmcnt(3)
	v_mfma_f32_16x16x32_bf16 v[96:99], v[182:185], v[194:197], v[96:99]
	v_mfma_f32_16x16x32_bf16 v[100:103], v[182:185], v[198:201], v[100:103]
	v_mfma_f32_16x16x32_bf16 v[104:107], v[182:185], v[202:205], v[104:107]
	v_mfma_f32_16x16x32_bf16 v[108:111], v[182:185], v[206:209], v[108:111]
	ds_read_b128 v[182:185], v139 offset:4096
	s_waitcnt lgkmcnt(3)
	v_mfma_f32_16x16x32_bf16 v[112:115], v[190:193], v[194:197], v[112:115]
	v_mfma_f32_16x16x32_bf16 v[116:119], v[190:193], v[198:201], v[116:119]
	v_mfma_f32_16x16x32_bf16 v[120:123], v[190:193], v[202:205], v[120:123]
	v_mfma_f32_16x16x32_bf16 v[124:127], v[190:193], v[206:209], v[124:127]
	ds_read_b128 v[190:193], v139 offset:6144
	s_waitcnt lgkmcnt(3)
	v_mfma_f32_16x16x32_bf16 v[0:3], v[170:173], v[214:217], v[0:3]
	v_mfma_f32_16x16x32_bf16 v[4:7], v[170:173], v[222:225], v[4:7]
	v_mfma_f32_16x16x32_bf16 v[8:11], v[170:173], v[226:229], v[8:11]
	v_mfma_f32_16x16x32_bf16 v[12:15], v[170:173], v[230:233], v[12:15]
	ds_read_b128 v[170:173], v139 offset:8192
	s_waitcnt lgkmcnt(3)
	v_mfma_f32_16x16x32_bf16 v[16:19], v[174:177], v[214:217], v[16:19]
	v_mfma_f32_16x16x32_bf16 v[20:23], v[174:177], v[222:225], v[20:23]
	v_mfma_f32_16x16x32_bf16 v[24:27], v[174:177], v[226:229], v[24:27]
	v_mfma_f32_16x16x32_bf16 v[28:31], v[174:177], v[230:233], v[28:31]
	ds_read_b128 v[174:177], v139 offset:10240
	s_waitcnt lgkmcnt(3)
	v_mfma_f32_16x16x32_bf16 v[32:35], v[182:185], v[214:217], v[32:35]
	v_mfma_f32_16x16x32_bf16 v[36:39], v[182:185], v[222:225], v[36:39]
	v_mfma_f32_16x16x32_bf16 v[40:43], v[182:185], v[226:229], v[40:43]
	v_mfma_f32_16x16x32_bf16 v[44:47], v[182:185], v[230:233], v[44:47]
	ds_read_b128 v[182:185], v139 offset:12288
	s_waitcnt lgkmcnt(3)
	v_mfma_f32_16x16x32_bf16 v[48:51], v[190:193], v[214:217], v[48:51]
	v_mfma_f32_16x16x32_bf16 v[52:55], v[190:193], v[222:225], v[52:55]
	v_mfma_f32_16x16x32_bf16 v[56:59], v[190:193], v[226:229], v[56:59]
	v_mfma_f32_16x16x32_bf16 v[60:63], v[190:193], v[230:233], v[60:63]
	ds_read_b128 v[190:193], v139 offset:14336
	s_waitcnt lgkmcnt(3)
	v_mfma_f32_16x16x32_bf16 v[64:67], v[170:173], v[214:217], v[64:67]
	v_mfma_f32_16x16x32_bf16 v[68:71], v[170:173], v[222:225], v[68:71]
	v_mfma_f32_16x16x32_bf16 v[72:75], v[170:173], v[226:229], v[72:75]
	v_mfma_f32_16x16x32_bf16 v[76:79], v[170:173], v[230:233], v[76:79]
	s_waitcnt lgkmcnt(2)
	v_mfma_f32_16x16x32_bf16 v[80:83], v[174:177], v[214:217], v[80:83]
	v_mfma_f32_16x16x32_bf16 v[84:87], v[174:177], v[222:225], v[84:87]
	v_mfma_f32_16x16x32_bf16 v[88:91], v[174:177], v[226:229], v[88:91]
	v_mfma_f32_16x16x32_bf16 v[92:95], v[174:177], v[230:233], v[92:95]
	s_waitcnt lgkmcnt(1)
	v_mfma_f32_16x16x32_bf16 v[96:99], v[182:185], v[214:217], v[96:99]
	v_mfma_f32_16x16x32_bf16 v[100:103], v[182:185], v[222:225], v[100:103]
	v_mfma_f32_16x16x32_bf16 v[104:107], v[182:185], v[226:229], v[104:107]
	v_mfma_f32_16x16x32_bf16 v[108:111], v[182:185], v[230:233], v[108:111]
	s_waitcnt lgkmcnt(0)
	v_mfma_f32_16x16x32_bf16 v[112:115], v[190:193], v[214:217], v[112:115]
	v_mfma_f32_16x16x32_bf16 v[116:119], v[190:193], v[222:225], v[116:119]
	v_mfma_f32_16x16x32_bf16 v[120:123], v[190:193], v[226:229], v[120:123]
	v_mfma_f32_16x16x32_bf16 v[124:127], v[190:193], v[230:233], v[124:127]
	s_setprio 1
	v_xor_b32_e32 v138, 0x8000, v138
	v_xor_b32_e32 v139, 0x8000, v139
	s_xor_b32 s17, s17, 0x8000
	s_add_i32 s16, s16, 1
	s_cmp_eq_u32 s16, 16
	s_cbranch_scc0 .Lg_ph13_top
	s_setprio 0
	s_waitcnt vmcnt(0)
	v_mov_b32_e32 v130, v180
	v_add_u32_e32 v202, 0x400, v153
	v_add_u32_e32 v201, 0x1000, v153
	v_add_u32_e32 v200, 0x1400, v153
	v_add_u32_e32 v199, 0x2000, v153
	v_add_u32_e32 v193, 0x2400, v153
	v_add_u32_e32 v194, 0x3000, v153
	v_add_u32_e32 v195, 0x3200, v153
	v_add_u32_e32 v196, 0x3400, v153
	v_add_u32_e32 v197, 0x3600, v153
	v_add_u32_e32 v198, 0x4000, v153
	v_add_u32_e32 v190, 0x4400, v153
	v_add_u32_e32 v191, 0x4800, v153
	v_add_u32_e32 v192, 0x5000, v153
	v_add_u32_e32 v186, 0x5400, v153
	v_add_u32_e32 v187, 0x5800, v153
	v_add_u32_e32 v189, 0x6000, v153
	v_add_u32_e32 v179, 0x6400, v153
	v_add_u32_e32 v181, 0x6800, v153
	v_add_u32_e32 v182, 0x7200, v153
	v_add_u32_e32 v183, 0x7400, v153
	v_add_u32_e32 v184, 0x7600, v153
	v_add_u32_e32 v185, 0x7800, v153
	v_add_u32_e32 v178, 0x8400, v153
	v_add_u32_e32 v177, 0x8800, v153
	v_add_u32_e32 v176, 0x9400, v153
	v_add_u32_e32 v175, 0x9800, v153
	v_add_u32_e32 v174, 0xa400, v153
	v_add_u32_e32 v147, 0xa800, v153
	v_add_u32_e32 v169, 0xb400, v153
	v_add_u32_e32 v170, 0xb600, v153
	v_add_u32_e32 v171, 0xb800, v153
	v_add_u32_e32 v172, 0xba00, v153
	s_waitcnt vmcnt(0)
	s_barrier
	s_and_saveexec_b64 s[16:17], s[6:7]
	s_cbranch_execz .LBB0_1319
	v_and_b32_e32 v254, 63, v180
	v_lshrrev_b32_e32 v253, 4, v254
	v_mul_u32_u24_e32 v253, 0x840, v253
	v_and_b32_e32 v254, 15, v254
	v_lshl_add_u32 v253, v254, 2, v253
	v_and_b32_e32 v254, 64, v180
	v_lshl_add_u32 v253, v254, 2, v253
	ds_write_b32 v253, v0 offset:0
	ds_write_b32 v253, v1 offset:528
	ds_write_b32 v253, v2 offset:1056
	ds_write_b32 v253, v3 offset:1584
	ds_write_b32 v253, v4 offset:64
	ds_write_b32 v253, v5 offset:592
	ds_write_b32 v253, v6 offset:1120
	ds_write_b32 v253, v7 offset:1648
	ds_write_b32 v253, v8 offset:128
	ds_write_b32 v253, v9 offset:656
	ds_write_b32 v253, v10 offset:1184
	ds_write_b32 v253, v11 offset:1712
	ds_write_b32 v253, v12 offset:192
	ds_write_b32 v253, v13 offset:720
	ds_write_b32 v253, v14 offset:1248
	ds_write_b32 v253, v15 offset:1776
	ds_write_b32 v253, v16 offset:8448
	ds_write_b32 v253, v17 offset:8976
	ds_write_b32 v253, v18 offset:9504
	ds_write_b32 v253, v19 offset:10032
	ds_write_b32 v253, v20 offset:8512
	ds_write_b32 v253, v21 offset:9040
	ds_write_b32 v253, v22 offset:9568
	ds_write_b32 v253, v23 offset:10096
	ds_write_b32 v253, v24 offset:8576
	ds_write_b32 v253, v25 offset:9104
	ds_write_b32 v253, v26 offset:9632
	ds_write_b32 v253, v27 offset:10160
	ds_write_b32 v253, v28 offset:8640
	ds_write_b32 v253, v29 offset:9168
	ds_write_b32 v253, v30 offset:9696
	ds_write_b32 v253, v31 offset:10224
	ds_write_b32 v253, v32 offset:16896
	ds_write_b32 v253, v33 offset:17424
	ds_write_b32 v253, v34 offset:17952
	ds_write_b32 v253, v35 offset:18480
	ds_write_b32 v253, v36 offset:16960
	ds_write_b32 v253, v37 offset:17488
	ds_write_b32 v253, v38 offset:18016
	ds_write_b32 v253, v39 offset:18544
	ds_write_b32 v253, v40 offset:17024
	ds_write_b32 v253, v41 offset:17552
	ds_write_b32 v253, v42 offset:18080
	ds_write_b32 v253, v43 offset:18608
	ds_write_b32 v253, v44 offset:17088
	ds_write_b32 v253, v45 offset:17616
	ds_write_b32 v253, v46 offset:18144
	ds_write_b32 v253, v47 offset:18672
	ds_write_b32 v253, v48 offset:25344
	ds_write_b32 v253, v49 offset:25872
	ds_write_b32 v253, v50 offset:26400
	ds_write_b32 v253, v51 offset:26928
	ds_write_b32 v253, v52 offset:25408
	ds_write_b32 v253, v53 offset:25936
	ds_write_b32 v253, v54 offset:26464
	ds_write_b32 v253, v55 offset:26992
	ds_write_b32 v253, v56 offset:25472
	ds_write_b32 v253, v57 offset:26000
	ds_write_b32 v253, v58 offset:26528
	ds_write_b32 v253, v59 offset:27056
	ds_write_b32 v253, v60 offset:25536
	ds_write_b32 v253, v61 offset:26064
	ds_write_b32 v253, v62 offset:26592
	ds_write_b32 v253, v63 offset:27120
	ds_write_b32 v253, v64 offset:33792
	ds_write_b32 v253, v65 offset:34320
	ds_write_b32 v253, v66 offset:34848
	ds_write_b32 v253, v67 offset:35376
	ds_write_b32 v253, v68 offset:33856
	ds_write_b32 v253, v69 offset:34384
	ds_write_b32 v253, v70 offset:34912
	ds_write_b32 v253, v71 offset:35440
	ds_write_b32 v253, v72 offset:33920
	ds_write_b32 v253, v73 offset:34448
	ds_write_b32 v253, v74 offset:34976
	ds_write_b32 v253, v75 offset:35504
	ds_write_b32 v253, v76 offset:33984
	ds_write_b32 v253, v77 offset:34512
	ds_write_b32 v253, v78 offset:35040
	ds_write_b32 v253, v79 offset:35568
	ds_write_b32 v253, v80 offset:42240
	ds_write_b32 v253, v81 offset:42768
	ds_write_b32 v253, v82 offset:43296
	ds_write_b32 v253, v83 offset:43824
	ds_write_b32 v253, v84 offset:42304
	ds_write_b32 v253, v85 offset:42832
	ds_write_b32 v253, v86 offset:43360
	ds_write_b32 v253, v87 offset:43888
	ds_write_b32 v253, v88 offset:42368
	ds_write_b32 v253, v89 offset:42896
	ds_write_b32 v253, v90 offset:43424
	ds_write_b32 v253, v91 offset:43952
	ds_write_b32 v253, v92 offset:42432
	ds_write_b32 v253, v93 offset:42960
	ds_write_b32 v253, v94 offset:43488
	ds_write_b32 v253, v95 offset:44016
	ds_write_b32 v253, v96 offset:50688
	ds_write_b32 v253, v97 offset:51216
	ds_write_b32 v253, v98 offset:51744
	ds_write_b32 v253, v99 offset:52272
	ds_write_b32 v253, v100 offset:50752
	ds_write_b32 v253, v101 offset:51280
	ds_write_b32 v253, v102 offset:51808
	ds_write_b32 v253, v103 offset:52336
	ds_write_b32 v253, v104 offset:50816
	ds_write_b32 v253, v105 offset:51344
	ds_write_b32 v253, v106 offset:51872
	ds_write_b32 v253, v107 offset:52400
	ds_write_b32 v253, v108 offset:50880
	ds_write_b32 v253, v109 offset:51408
	ds_write_b32 v253, v110 offset:51936
	ds_write_b32 v253, v111 offset:52464
	ds_write_b32 v253, v112 offset:59136
	ds_write_b32 v253, v113 offset:59664
	ds_write_b32 v253, v114 offset:60192
	ds_write_b32 v253, v115 offset:60720
	ds_write_b32 v253, v116 offset:59200
	ds_write_b32 v253, v117 offset:59728
	ds_write_b32 v253, v118 offset:60256
	ds_write_b32 v253, v119 offset:60784
	ds_write_b32 v253, v120 offset:59264
	ds_write_b32 v253, v121 offset:59792
	ds_write_b32 v253, v122 offset:60320
	ds_write_b32 v253, v123 offset:60848
	ds_write_b32 v253, v124 offset:59328
	ds_write_b32 v253, v125 offset:59856
	ds_write_b32 v253, v126 offset:60384
	ds_write_b32 v253, v127 offset:60912

.LBB0_1670:
	s_lshr_b32 s10, s19, 4
	s_and_b32 s10, s10, 12
	s_bfe_u32 s15, s19, 0x20001
	s_or_b32 s10, s10, s20
	s_lshl_b32 s14, s15, 4
	s_and_b32 s26, s19, 1
	s_or_b32 s27, s14, s10
	s_lshl_b32 s14, s27, 9
	s_lshl_b32 s28, s26, 8
	s_or_b32 s14, s14, s28
	v_or_b32_e32 v0, s14, v146
	v_lshlrev_b32_e32 v0, 2, v0
	global_load_dword v2, v0, s[2:3]
	global_load_dword v4, v0, s[2:3] offset:256
	global_load_dword v10, v0, s[2:3] offset:512
	global_load_dword v11, v0, s[2:3] offset:768
	s_lshl_b32 s15, s15, 22
	s_bfe_u32 s28, s19, 0x30003
	v_readfirstlane_b32 s29, v148
	v_readfirstlane_b32 s30, v154
	s_or_b32 s28, s28, s21
	s_mov_b32 m0, s29
	v_readfirstlane_b32 s31, v155
	s_lshl_b32 s43, s28, 17
	s_lshl_b32 s10, s10, 21
	s_waitcnt vmcnt(0)
	s_barrier
	v_readfirstlane_b32 s34, v156
	s_or_b32 s10, s10, s43
	v_readfirstlane_b32 s35, v157
	s_bitset1_b32 s10, 25
	v_readfirstlane_b32 s36, v158
	v_lshl_add_u64 v[134:135], v[130:131], 0, s[10:11]
	v_mov_b32_e32 v1, v129
	v_readfirstlane_b32 s37, v159
	v_lshl_add_u64 v[136:137], v[132:133], 0, s[10:11]
	v_mov_b32_e32 v3, v129
	v_readfirstlane_b32 s38, v160
	v_mov_b32_e32 v5, v129
	v_readfirstlane_b32 s39, v161
	v_readfirstlane_b32 s40, v162
	v_readfirstlane_b32 s41, v163
	v_readfirstlane_b32 s42, v164
	v_lshl_add_u64 v[6:7], v[134:135], 0, 64
	v_lshl_add_u64 v[8:9], v[136:137], 0, 64
	s_mov_b32 s14, s11
	s_mov_b32 s29, s11
	v_mov_b32_e32 v16, 0
	v_mov_b32_e32 v17, v129
	v_mov_b32_e32 v18, v129
	v_mov_b32_e32 v19, v129
	v_mov_b32_e32 v20, v129
	v_mov_b32_e32 v21, v129
	v_mov_b32_e32 v22, v129
	v_mov_b32_e32 v23, v129
	v_mov_b32_e32 v24, v129
	v_mov_b32_e32 v25, v129
	v_mov_b32_e32 v26, v129
	v_mov_b32_e32 v27, v129
	v_mov_b32_e32 v28, v129
	v_mov_b32_e32 v29, v129
	v_mov_b32_e32 v30, v129
	v_mov_b32_e32 v31, v129
	v_mov_b32_e32 v32, 0
	v_mov_b32_e32 v33, v129
	v_mov_b32_e32 v34, v129
	v_mov_b32_e32 v35, v129
	v_mov_b32_e32 v36, v129
	v_mov_b32_e32 v37, v129
	v_mov_b32_e32 v38, v129
	v_mov_b32_e32 v39, v129
	v_mov_b32_e32 v40, v129
	v_mov_b32_e32 v41, v129
	v_mov_b32_e32 v42, v129
	v_mov_b32_e32 v43, v129
	v_mov_b32_e32 v44, v129
	v_mov_b32_e32 v45, v129
	v_mov_b32_e32 v46, v129
	v_mov_b32_e32 v47, v129
	v_mov_b32_e32 v48, 0
	v_mov_b32_e32 v49, v129
	v_mov_b32_e32 v50, v129
	v_mov_b32_e32 v51, v129
	v_mov_b32_e32 v52, v129
	v_mov_b32_e32 v53, v129
	v_mov_b32_e32 v54, v129
	v_mov_b32_e32 v55, v129
	v_mov_b32_e32 v56, v129
	v_mov_b32_e32 v57, v129
	v_mov_b32_e32 v58, v129
	s_waitcnt vmcnt(3)
	v_lshl_add_u32 v0, v2, 10, s15
	s_waitcnt vmcnt(2)
	v_lshl_add_u32 v2, v4, 10, s15
	v_or_b32_e32 v0, v0, v147
	s_waitcnt vmcnt(1)
	v_lshl_add_u32 v4, v10, 10, s15
	v_or_b32_e32 v2, v2, v147
	v_lshlrev_b32_e32 v128, 1, v0
	s_waitcnt vmcnt(0)
	v_lshl_add_u32 v10, v11, 10, s15
	v_or_b32_e32 v4, v4, v147
	v_lshlrev_b32_e32 v0, 1, v2
	s_nop 0
	s_mov_b32 m0, s30
	v_or_b32_e32 v10, v10, v147
	v_lshlrev_b32_e32 v2, 1, v4
	s_nop 0
	s_mov_b32 m0, s31
	v_lshlrev_b32_e32 v4, 1, v10
	s_nop 0
	s_mov_b32 m0, s34
	v_lshl_add_u64 v[138:139], s[4:5], 0, v[128:129]
	s_nop 0
	s_mov_b32 m0, s35
	v_lshl_add_u64 v[140:141], s[4:5], 0, v[0:1]
	s_nop 0
	s_mov_b32 m0, s36
	v_lshl_add_u64 v[0:1], v[138:139], 0, 64
	s_nop 0
	s_mov_b32 m0, s37
	v_lshl_add_u64 v[142:143], s[4:5], 0, v[2:3]
	v_lshl_add_u64 v[10:11], v[140:141], 0, 64
	s_nop 0
	s_mov_b32 m0, s38
	v_lshl_add_u64 v[144:145], s[4:5], 0, v[4:5]
	v_lshl_add_u64 v[12:13], v[142:143], 0, 64
	s_nop 0
	s_mov_b32 m0, s39
	v_lshl_add_u64 v[14:15], v[144:145], 0, 64
	s_nop 0
	s_mov_b32 m0, s40
	s_mov_b32 s15, 2
	s_nop 0
	s_mov_b32 m0, s41
	v_mov_b32_e32 v0, 0
	s_nop 0
	s_mov_b32 m0, s42
	v_mov_b32_e32 v1, v129
	s_nop 0
	v_mov_b32_e32 v2, v129
	v_mov_b32_e32 v4, v129
	v_mov_b32_e32 v6, v129
	v_mov_b32_e32 v7, v129
	v_mov_b32_e32 v8, v129
	v_mov_b32_e32 v9, v129
	v_mov_b32_e32 v10, v129
	v_mov_b32_e32 v11, v129
	v_mov_b32_e32 v12, v129
	v_mov_b32_e32 v13, v129
	v_mov_b32_e32 v14, v129
	v_mov_b32_e32 v15, v129
	v_mov_b32_e32 v59, v129
	v_mov_b32_e32 v60, v129
	v_mov_b32_e32 v61, v129
	v_mov_b32_e32 v62, v129
	v_mov_b32_e32 v63, v129
	v_mov_b32_e32 v64, 0
	v_mov_b32_e32 v65, v129
	v_mov_b32_e32 v66, v129
	v_mov_b32_e32 v67, v129
	v_mov_b32_e32 v68, v129
	v_mov_b32_e32 v69, v129
	v_mov_b32_e32 v70, v129
	v_mov_b32_e32 v71, v129
	v_mov_b32_e32 v72, v129
	v_mov_b32_e32 v73, v129
	v_mov_b32_e32 v74, v129
	v_mov_b32_e32 v75, v129
	v_mov_b32_e32 v76, v129
	v_mov_b32_e32 v77, v129
	v_mov_b32_e32 v78, v129
	v_mov_b32_e32 v79, v129
	v_mov_b32_e32 v80, 0
	v_mov_b32_e32 v81, v129
	v_mov_b32_e32 v82, v129
	v_mov_b32_e32 v83, v129
	v_mov_b32_e32 v84, v129
	v_mov_b32_e32 v85, v129
	v_mov_b32_e32 v86, v129
	v_mov_b32_e32 v87, v129
	v_mov_b32_e32 v88, v129
	v_mov_b32_e32 v89, v129
	v_mov_b32_e32 v90, v129
	v_mov_b32_e32 v91, v129
	v_mov_b32_e32 v92, v129
	v_mov_b32_e32 v93, v129
	v_mov_b32_e32 v94, v129
	v_mov_b32_e32 v95, v129
	v_mov_b32_e32 v96, 0
	v_mov_b32_e32 v97, v129
	v_mov_b32_e32 v98, v129
	v_mov_b32_e32 v99, v129
	v_mov_b32_e32 v100, v129
	v_mov_b32_e32 v101, v129
	v_mov_b32_e32 v102, v129
	v_mov_b32_e32 v103, v129
	v_mov_b32_e32 v104, v129
	v_mov_b32_e32 v105, v129
	v_mov_b32_e32 v106, v129
	v_mov_b32_e32 v107, v129
	v_mov_b32_e32 v108, v129
	v_mov_b32_e32 v109, v129
	v_mov_b32_e32 v110, v129
	v_mov_b32_e32 v111, v129
	v_mov_b32_e32 v112, 0
	v_mov_b32_e32 v113, v129
	v_mov_b32_e32 v114, v129
	v_mov_b32_e32 v115, v129
	v_mov_b32_e32 v116, v129
	v_mov_b32_e32 v117, v129
	v_mov_b32_e32 v118, v129
	v_mov_b32_e32 v119, v129
	v_mov_b32_e32 v120, v129
	v_mov_b32_e32 v121, v129
	v_mov_b32_e32 v122, v129
	v_mov_b32_e32 v123, v129
	v_mov_b32_e32 v124, v129
	v_mov_b32_e32 v125, v129
	v_mov_b32_e32 v126, v129
	v_mov_b32_e32 v127, v129
	s_mov_b64 s[54:55], 0x80
	v_lshrrev_b32_e32 v170, 6, v180
	v_lshlrev_b32_e32 v176, 11, v170
	v_and_b32_e32 v166, 63, v180
	v_readfirstlane_b32 s53, v176
	v_lshrrev_b32_e32 v167, 4, v166
	v_bfe_u32 v168, v166, 1, 3
	v_xor_b32_e32 v168, v167, v168
	v_and_b32_e32 v169, 31, v166
	v_lshlrev_b32_e32 v169, 7, v169
	v_lshrrev_b32_e32 v169, 3, v166
	v_lshlrev_b32_e32 v176, 4, v169
	v_add_u32_e32 v177, 0x80, v176
	v_and_b32_e32 v169, 7, v166
	v_lshrrev_b32_e32 v167, 4, v166
	v_xor_b32_e32 v167, v169, v167
	v_lshrrev_b32_e32 v169, 5, v166
	v_sub_u32_e32 v182, v167, v169
	v_xor_b32_e32 v167, 4, v167
	v_add_u32_e32 v169, 2, v169
	v_sub_u32_e32 v184, v167, v169
	v_lshlrev_b32_e32 v182, 4, v182
	v_ashrrev_i32_e32 v183, 31, v182
	v_lshlrev_b32_e32 v184, 4, v184
	v_ashrrev_i32_e32 v185, 31, v184
	ds_bpermute_b32 v240, v176, v134
	ds_bpermute_b32 v241, v176, v135
	ds_bpermute_b32 v242, v177, v134
	ds_bpermute_b32 v243, v177, v135
	ds_bpermute_b32 v244, v176, v136
	ds_bpermute_b32 v245, v176, v137
	ds_bpermute_b32 v246, v177, v136
	ds_bpermute_b32 v247, v177, v137
	s_waitcnt lgkmcnt(0)
	ds_bpermute_b32 v178, v176, v138
	ds_bpermute_b32 v179, v176, v139
	ds_bpermute_b32 v230, v177, v138
	ds_bpermute_b32 v231, v177, v139
	ds_bpermute_b32 v232, v176, v140
	ds_bpermute_b32 v233, v176, v141
	ds_bpermute_b32 v234, v177, v140
	ds_bpermute_b32 v235, v177, v141
	ds_bpermute_b32 v236, v176, v142
	ds_bpermute_b32 v237, v176, v143
	ds_bpermute_b32 v238, v177, v142
	ds_bpermute_b32 v239, v177, v143
	ds_bpermute_b32 v134, v176, v144
	ds_bpermute_b32 v135, v176, v145
	ds_bpermute_b32 v136, v177, v144
	ds_bpermute_b32 v137, v177, v145
	s_waitcnt lgkmcnt(0)
	v_and_b32_e32 v169, 15, v166
	v_lshlrev_b32_e32 v169, 7, v169
	v_lshrrev_b32_e32 v167, 1, v170
	v_lshl_add_u32 v138, v167, 14, v169
	v_and_b32_e32 v167, 1, v170
	v_lshl_add_u32 v142, v167, 13, v169
	v_add_u32_e32 v142, 0x10000, v142
	v_xor_b32_e32 v169, 4, v168
	v_lshl_add_u32 v139, v169, 4, v138
	v_lshl_add_u32 v143, v169, 4, v142
	v_xor_b32_e32 v169, 0, v168
	v_lshl_add_u32 v138, v169, 4, v138
	v_lshl_add_u32 v142, v169, 4, v142
	v_lshl_add_u64 v[178:179], v[178:179], 0, v[182:183]
	v_lshl_add_u64 v[230:231], v[230:231], 0, v[184:185]
	v_lshl_add_u64 v[232:233], v[232:233], 0, v[182:183]
	v_lshl_add_u64 v[234:235], v[234:235], 0, v[184:185]
	v_lshl_add_u64 v[236:237], v[236:237], 0, v[182:183]
	v_lshl_add_u64 v[238:239], v[238:239], 0, v[184:185]
	v_lshl_add_u64 v[134:135], v[134:135], 0, v[182:183]
	v_lshl_add_u64 v[136:137], v[136:137], 0, v[184:185]
	v_lshl_add_u64 v[240:241], v[240:241], 0, v[182:183]
	v_lshl_add_u64 v[242:243], v[242:243], 0, v[184:185]
	v_lshl_add_u64 v[244:245], v[244:245], 0, v[182:183]
	v_lshl_add_u64 v[246:247], v[246:247], 0, v[184:185]
	s_mov_b32 s58, s53
	s_add_i32 m0, s58, 0x0
	s_nop 0
	global_load_lds_dwordx4 v[178:179], off
	s_add_i32 m0, s58, 0x400
	v_lshl_add_u64 v[178:179], v[178:179], 0, s[54:55]
	global_load_lds_dwordx4 v[230:231], off
	s_add_i32 m0, s58, 0x2000
	v_lshl_add_u64 v[230:231], v[230:231], 0, s[54:55]
	global_load_lds_dwordx4 v[232:233], off
	s_add_i32 m0, s58, 0x2400
	v_lshl_add_u64 v[232:233], v[232:233], 0, s[54:55]
	global_load_lds_dwordx4 v[234:235], off
	s_add_i32 m0, s58, 0x4000
	v_lshl_add_u64 v[234:235], v[234:235], 0, s[54:55]
	global_load_lds_dwordx4 v[236:237], off
	s_add_i32 m0, s58, 0x4400
	v_lshl_add_u64 v[236:237], v[236:237], 0, s[54:55]
	global_load_lds_dwordx4 v[238:239], off
	s_add_i32 m0, s58, 0x6000
	v_lshl_add_u64 v[238:239], v[238:239], 0, s[54:55]
	global_load_lds_dwordx4 v[134:135], off
	s_add_i32 m0, s58, 0x6400
	v_lshl_add_u64 v[134:135], v[134:135], 0, s[54:55]
	global_load_lds_dwordx4 v[136:137], off
	v_lshl_add_u64 v[136:137], v[136:137], 0, s[54:55]
	s_add_i32 s58, s53, 0x10000
	s_add_i32 m0, s58, 0x0
	s_nop 0
	global_load_lds_dwordx4 v[240:241], off
	s_add_i32 m0, s58, 0x400
	v_lshl_add_u64 v[240:241], v[240:241], 0, s[54:55]
	global_load_lds_dwordx4 v[242:243], off
	s_add_i32 m0, s58, 0x2000
	v_lshl_add_u64 v[242:243], v[242:243], 0, s[54:55]
	global_load_lds_dwordx4 v[244:245], off
	s_add_i32 m0, s58, 0x2400
	v_lshl_add_u64 v[244:245], v[244:245], 0, s[54:55]
	global_load_lds_dwordx4 v[246:247], off
	v_lshl_add_u64 v[246:247], v[246:247], 0, s[54:55]
	s_mov_b32 s14, 0
	s_mov_b32 s15, 0
	s_setprio 1

.Lg_ph16_noB:
	s_setprio 2
	s_waitcnt lgkmcnt(3)
	v_mfma_f32_16x16x32_bf16 v[0:3], v[166:169], v[186:189], v[0:3]
	v_mfma_f32_16x16x32_bf16 v[4:7], v[166:169], v[190:193], v[4:7]
	v_mfma_f32_16x16x32_bf16 v[8:11], v[166:169], v[194:197], v[8:11]
	v_mfma_f32_16x16x32_bf16 v[12:15], v[166:169], v[198:201], v[12:15]
	ds_read_b128 v[166:169], v138 offset:8192
	s_waitcnt lgkmcnt(3)
	v_mfma_f32_16x16x32_bf16 v[16:19], v[170:173], v[186:189], v[16:19]
	v_mfma_f32_16x16x32_bf16 v[20:23], v[170:173], v[190:193], v[20:23]
	v_mfma_f32_16x16x32_bf16 v[24:27], v[170:173], v[194:197], v[24:27]
	v_mfma_f32_16x16x32_bf16 v[28:31], v[170:173], v[198:201], v[28:31]
	ds_read_b128 v[170:173], v138 offset:10240
	s_waitcnt lgkmcnt(3)
	v_mfma_f32_16x16x32_bf16 v[32:35], v[174:177], v[186:189], v[32:35]
	v_mfma_f32_16x16x32_bf16 v[36:39], v[174:177], v[190:193], v[36:39]
	v_mfma_f32_16x16x32_bf16 v[40:43], v[174:177], v[194:197], v[40:43]
	v_mfma_f32_16x16x32_bf16 v[44:47], v[174:177], v[198:201], v[44:47]
	ds_read_b128 v[174:177], v138 offset:12288
	s_waitcnt lgkmcnt(3)
	v_mfma_f32_16x16x32_bf16 v[48:51], v[182:185], v[186:189], v[48:51]
	v_mfma_f32_16x16x32_bf16 v[52:55], v[182:185], v[190:193], v[52:55]
	v_mfma_f32_16x16x32_bf16 v[56:59], v[182:185], v[194:197], v[56:59]
	v_mfma_f32_16x16x32_bf16 v[60:63], v[182:185], v[198:201], v[60:63]
	ds_read_b128 v[182:185], v138 offset:14336
	s_waitcnt lgkmcnt(3)
	v_mfma_f32_16x16x32_bf16 v[64:67], v[166:169], v[186:189], v[64:67]
	v_mfma_f32_16x16x32_bf16 v[68:71], v[166:169], v[190:193], v[68:71]
	v_mfma_f32_16x16x32_bf16 v[72:75], v[166:169], v[194:197], v[72:75]
	v_mfma_f32_16x16x32_bf16 v[76:79], v[166:169], v[198:201], v[76:79]
	ds_read_b128 v[166:169], v139
	s_waitcnt lgkmcnt(3)
	v_mfma_f32_16x16x32_bf16 v[80:83], v[170:173], v[186:189], v[80:83]
	v_mfma_f32_16x16x32_bf16 v[84:87], v[170:173], v[190:193], v[84:87]
	v_mfma_f32_16x16x32_bf16 v[88:91], v[170:173], v[194:197], v[88:91]
	v_mfma_f32_16x16x32_bf16 v[92:95], v[170:173], v[198:201], v[92:95]
	ds_read_b128 v[170:173], v139 offset:2048
	s_waitcnt lgkmcnt(3)
	v_mfma_f32_16x16x32_bf16 v[96:99], v[174:177], v[186:189], v[96:99]
	v_mfma_f32_16x16x32_bf16 v[100:103], v[174:177], v[190:193], v[100:103]
	v_mfma_f32_16x16x32_bf16 v[104:107], v[174:177], v[194:197], v[104:107]
	v_mfma_f32_16x16x32_bf16 v[108:111], v[174:177], v[198:201], v[108:111]
	ds_read_b128 v[174:177], v139 offset:4096
	s_waitcnt lgkmcnt(3)
	v_mfma_f32_16x16x32_bf16 v[112:115], v[182:185], v[186:189], v[112:115]
	v_mfma_f32_16x16x32_bf16 v[116:119], v[182:185], v[190:193], v[116:119]
	v_mfma_f32_16x16x32_bf16 v[120:123], v[182:185], v[194:197], v[120:123]
	v_mfma_f32_16x16x32_bf16 v[124:127], v[182:185], v[198:201], v[124:127]
	ds_read_b128 v[182:185], v139 offset:6144
	s_waitcnt lgkmcnt(3)
	v_mfma_f32_16x16x32_bf16 v[0:3], v[166:169], v[202:205], v[0:3]
	v_mfma_f32_16x16x32_bf16 v[4:7], v[166:169], v[218:221], v[4:7]
	v_mfma_f32_16x16x32_bf16 v[8:11], v[166:169], v[222:225], v[8:11]
	v_mfma_f32_16x16x32_bf16 v[12:15], v[166:169], v[226:229], v[12:15]
	ds_read_b128 v[166:169], v139 offset:8192
	s_waitcnt lgkmcnt(3)
	v_mfma_f32_16x16x32_bf16 v[16:19], v[170:173], v[202:205], v[16:19]
	v_mfma_f32_16x16x32_bf16 v[20:23], v[170:173], v[218:221], v[20:23]
	v_mfma_f32_16x16x32_bf16 v[24:27], v[170:173], v[222:225], v[24:27]
	v_mfma_f32_16x16x32_bf16 v[28:31], v[170:173], v[226:229], v[28:31]
	ds_read_b128 v[170:173], v139 offset:10240
	s_waitcnt lgkmcnt(3)
	v_mfma_f32_16x16x32_bf16 v[32:35], v[174:177], v[202:205], v[32:35]
	v_mfma_f32_16x16x32_bf16 v[36:39], v[174:177], v[218:221], v[36:39]
	v_mfma_f32_16x16x32_bf16 v[40:43], v[174:177], v[222:225], v[40:43]
	v_mfma_f32_16x16x32_bf16 v[44:47], v[174:177], v[226:229], v[44:47]
	ds_read_b128 v[174:177], v139 offset:12288
	s_waitcnt lgkmcnt(3)
	v_mfma_f32_16x16x32_bf16 v[48:51], v[182:185], v[202:205], v[48:51]
	v_mfma_f32_16x16x32_bf16 v[52:55], v[182:185], v[218:221], v[52:55]
	v_mfma_f32_16x16x32_bf16 v[56:59], v[182:185], v[222:225], v[56:59]
	v_mfma_f32_16x16x32_bf16 v[60:63], v[182:185], v[226:229], v[60:63]
	ds_read_b128 v[182:185], v139 offset:14336
	s_waitcnt lgkmcnt(3)
	v_mfma_f32_16x16x32_bf16 v[64:67], v[166:169], v[202:205], v[64:67]
	v_mfma_f32_16x16x32_bf16 v[68:71], v[166:169], v[218:221], v[68:71]
	v_mfma_f32_16x16x32_bf16 v[72:75], v[166:169], v[222:225], v[72:75]
	v_mfma_f32_16x16x32_bf16 v[76:79], v[166:169], v[226:229], v[76:79]
	s_waitcnt lgkmcnt(2)
	v_mfma_f32_16x16x32_bf16 v[80:83], v[170:173], v[202:205], v[80:83]
	v_mfma_f32_16x16x32_bf16 v[84:87], v[170:173], v[218:221], v[84:87]
	v_mfma_f32_16x16x32_bf16 v[88:91], v[170:173], v[222:225], v[88:91]
	v_mfma_f32_16x16x32_bf16 v[92:95], v[170:173], v[226:229], v[92:95]
	s_waitcnt lgkmcnt(1)
	v_mfma_f32_16x16x32_bf16 v[96:99], v[174:177], v[202:205], v[96:99]
	v_mfma_f32_16x16x32_bf16 v[100:103], v[174:177], v[218:221], v[100:103]
	v_mfma_f32_16x16x32_bf16 v[104:107], v[174:177], v[222:225], v[104:107]
	v_mfma_f32_16x16x32_bf16 v[108:111], v[174:177], v[226:229], v[108:111]
	s_waitcnt lgkmcnt(0)
	v_mfma_f32_16x16x32_bf16 v[112:115], v[182:185], v[202:205], v[112:115]
	v_mfma_f32_16x16x32_bf16 v[116:119], v[182:185], v[218:221], v[116:119]
	v_mfma_f32_16x16x32_bf16 v[120:123], v[182:185], v[222:225], v[120:123]
	v_mfma_f32_16x16x32_bf16 v[124:127], v[182:185], v[226:229], v[124:127]
	s_setprio 1
	v_xor_b32_e32 v138, 0x8000, v138
	v_xor_b32_e32 v139, 0x8000, v139
	s_xor_b32 s15, s15, 0x8000
	s_add_i32 s14, s14, 1
	s_cmp_eq_u32 s14, 16
	s_cbranch_scc0 .Lg_ph16_top
	s_setprio 0
	s_waitcnt vmcnt(0)
	v_mov_b32_e32 v128, v180
	v_add_u32_e32 v192, 0x400, v153
	v_add_u32_e32 v191, 0x1000, v153
	v_add_u32_e32 v190, 0x1400, v153
	v_add_u32_e32 v189, 0x2000, v153
	v_add_u32_e32 v183, 0x2400, v153
	v_add_u32_e32 v184, 0x3000, v153
	v_add_u32_e32 v185, 0x3200, v153
	v_add_u32_e32 v186, 0x3400, v153
	v_add_u32_e32 v187, 0x3600, v153
	v_add_u32_e32 v188, 0x4000, v153
	v_add_u32_e32 v179, 0x4400, v153
	v_add_u32_e32 v181, 0x4800, v153
	v_add_u32_e32 v182, 0x5000, v153
	v_add_u32_e32 v176, 0x5400, v153
	v_add_u32_e32 v177, 0x5800, v153
	v_add_u32_e32 v178, 0x6000, v153
	v_add_u32_e32 v170, 0x6400, v153
	v_add_u32_e32 v171, 0x6800, v153
	v_add_u32_e32 v172, 0x7200, v153
	v_add_u32_e32 v173, 0x7400, v153
	v_add_u32_e32 v174, 0x7600, v153
	v_add_u32_e32 v175, 0x7800, v153
	v_add_u32_e32 v169, 0x8400, v153
	v_add_u32_e32 v168, 0x8800, v153
	v_add_u32_e32 v167, 0x9400, v153
	v_add_u32_e32 v166, 0x9800, v153
	v_add_u32_e32 v145, 0xa400, v153
	v_add_u32_e32 v140, 0xa800, v153
	v_add_u32_e32 v141, 0xb400, v153
	v_add_u32_e32 v142, 0xb600, v153
	v_add_u32_e32 v143, 0xb800, v153
	v_add_u32_e32 v144, 0xba00, v153
	s_waitcnt vmcnt(0)
	s_barrier
	s_and_saveexec_b64 s[14:15], s[6:7]
	s_cbranch_execz .LBB0_1674
	v_and_b32_e32 v254, 63, v180
	v_lshrrev_b32_e32 v253, 4, v254
	v_mul_u32_u24_e32 v253, 0x840, v253
	v_and_b32_e32 v254, 15, v254
	v_lshl_add_u32 v253, v254, 2, v253
	v_and_b32_e32 v254, 64, v180
	v_lshl_add_u32 v253, v254, 2, v253
	ds_write_b32 v253, v0 offset:0
	ds_write_b32 v253, v1 offset:528
	ds_write_b32 v253, v2 offset:1056
	ds_write_b32 v253, v3 offset:1584
	ds_write_b32 v253, v4 offset:64
	ds_write_b32 v253, v5 offset:592
	ds_write_b32 v253, v6 offset:1120
	ds_write_b32 v253, v7 offset:1648
	ds_write_b32 v253, v8 offset:128
	ds_write_b32 v253, v9 offset:656
	ds_write_b32 v253, v10 offset:1184
	ds_write_b32 v253, v11 offset:1712
	ds_write_b32 v253, v12 offset:192
	ds_write_b32 v253, v13 offset:720
	ds_write_b32 v253, v14 offset:1248
	ds_write_b32 v253, v15 offset:1776
	ds_write_b32 v253, v16 offset:8448
	ds_write_b32 v253, v17 offset:8976
	ds_write_b32 v253, v18 offset:9504
	ds_write_b32 v253, v19 offset:10032
	ds_write_b32 v253, v20 offset:8512
	ds_write_b32 v253, v21 offset:9040
	ds_write_b32 v253, v22 offset:9568
	ds_write_b32 v253, v23 offset:10096
	ds_write_b32 v253, v24 offset:8576
	ds_write_b32 v253, v25 offset:9104
	ds_write_b32 v253, v26 offset:9632
	ds_write_b32 v253, v27 offset:10160
	ds_write_b32 v253, v28 offset:8640
	ds_write_b32 v253, v29 offset:9168
	ds_write_b32 v253, v30 offset:9696
	ds_write_b32 v253, v31 offset:10224
	ds_write_b32 v253, v32 offset:16896
	ds_write_b32 v253, v33 offset:17424
	ds_write_b32 v253, v34 offset:17952
	ds_write_b32 v253, v35 offset:18480
	ds_write_b32 v253, v36 offset:16960
	ds_write_b32 v253, v37 offset:17488
	ds_write_b32 v253, v38 offset:18016
	ds_write_b32 v253, v39 offset:18544
	ds_write_b32 v253, v40 offset:17024
	ds_write_b32 v253, v41 offset:17552
	ds_write_b32 v253, v42 offset:18080
	ds_write_b32 v253, v43 offset:18608
	ds_write_b32 v253, v44 offset:17088
	ds_write_b32 v253, v45 offset:17616
	ds_write_b32 v253, v46 offset:18144
	ds_write_b32 v253, v47 offset:18672
	ds_write_b32 v253, v48 offset:25344
	ds_write_b32 v253, v49 offset:25872
	ds_write_b32 v253, v50 offset:26400
	ds_write_b32 v253, v51 offset:26928
	ds_write_b32 v253, v52 offset:25408
	ds_write_b32 v253, v53 offset:25936
	ds_write_b32 v253, v54 offset:26464
	ds_write_b32 v253, v55 offset:26992
	ds_write_b32 v253, v56 offset:25472
	ds_write_b32 v253, v57 offset:26000
	ds_write_b32 v253, v58 offset:26528
	ds_write_b32 v253, v59 offset:27056
	ds_write_b32 v253, v60 offset:25536
	ds_write_b32 v253, v61 offset:26064
	ds_write_b32 v253, v62 offset:26592
	ds_write_b32 v253, v63 offset:27120
	ds_write_b32 v253, v64 offset:33792
	ds_write_b32 v253, v65 offset:34320
	ds_write_b32 v253, v66 offset:34848
	ds_write_b32 v253, v67 offset:35376
	ds_write_b32 v253, v68 offset:33856
	ds_write_b32 v253, v69 offset:34384
	ds_write_b32 v253, v70 offset:34912
	ds_write_b32 v253, v71 offset:35440
	ds_write_b32 v253, v72 offset:33920
	ds_write_b32 v253, v73 offset:34448
	ds_write_b32 v253, v74 offset:34976
	ds_write_b32 v253, v75 offset:35504
	ds_write_b32 v253, v76 offset:33984
	ds_write_b32 v253, v77 offset:34512
	ds_write_b32 v253, v78 offset:35040
	ds_write_b32 v253, v79 offset:35568
	ds_write_b32 v253, v80 offset:42240
	ds_write_b32 v253, v81 offset:42768
	ds_write_b32 v253, v82 offset:43296
	ds_write_b32 v253, v83 offset:43824
	ds_write_b32 v253, v84 offset:42304
	ds_write_b32 v253, v85 offset:42832
	ds_write_b32 v253, v86 offset:43360
	ds_write_b32 v253, v87 offset:43888
	ds_write_b32 v253, v88 offset:42368
	ds_write_b32 v253, v89 offset:42896
	ds_write_b32 v253, v90 offset:43424
	ds_write_b32 v253, v91 offset:43952
	ds_write_b32 v253, v92 offset:42432
	ds_write_b32 v253, v93 offset:42960
	ds_write_b32 v253, v94 offset:43488
	ds_write_b32 v253, v95 offset:44016
	ds_write_b32 v253, v96 offset:50688
	ds_write_b32 v253, v97 offset:51216
	ds_write_b32 v253, v98 offset:51744
	ds_write_b32 v253, v99 offset:52272
	ds_write_b32 v253, v100 offset:50752
	ds_write_b32 v253, v101 offset:51280
	ds_write_b32 v253, v102 offset:51808
	ds_write_b32 v253, v103 offset:52336
	ds_write_b32 v253, v104 offset:50816
	ds_write_b32 v253, v105 offset:51344
	ds_write_b32 v253, v106 offset:51872
	ds_write_b32 v253, v107 offset:52400
	ds_write_b32 v253, v108 offset:50880
	ds_write_b32 v253, v109 offset:51408
	ds_write_b32 v253, v110 offset:51936
	ds_write_b32 v253, v111 offset:52464
	ds_write_b32 v253, v112 offset:59136
	ds_write_b32 v253, v113 offset:59664
	ds_write_b32 v253, v114 offset:60192
	ds_write_b32 v253, v115 offset:60720
	ds_write_b32 v253, v116 offset:59200
	ds_write_b32 v253, v117 offset:59728
	ds_write_b32 v253, v118 offset:60256
	ds_write_b32 v253, v119 offset:60784
	ds_write_b32 v253, v120 offset:59264
	ds_write_b32 v253, v121 offset:59792
	ds_write_b32 v253, v122 offset:60320
	ds_write_b32 v253, v123 offset:60848
	ds_write_b32 v253, v124 offset:59328
	ds_write_b32 v253, v125 offset:59856
	ds_write_b32 v253, v126 offset:60384
	ds_write_b32 v253, v127 offset:60912

.LBB0_1736:
	s_lshr_b32 s4, s30, 3
	s_and_b32 s4, s4, 8
	s_lshl_b32 s20, s30, 3
	s_or_b32 s4, s4, s28
	s_and_b32 s37, s30, 1
	s_and_b32 s20, s20, 48
	s_or_b32 s38, s4, s20
	s_lshl_b32 s22, s37, 8
	s_lshl_b32 s20, s30, 4
	s_lshl_b32 s23, s38, 9
	v_or_b32_e32 v0, s22, v129
	s_and_b32 s39, s20, 0x380
	v_or_b32_e32 v0, s23, v0
	s_lshl_b32 s20, s39, 11
	s_lshl_b32 s4, s4, 21
	v_lshlrev_b32_e32 v1, 10, v0
	s_or_b32 s4, s4, s20
	s_add_u32 s20, s94, s4
	v_or_b32_e32 v0, v1, v128
	v_readfirstlane_b32 s4, v152
	v_lshlrev_b32_e32 v130, 1, v0
	s_mov_b32 m0, s4
	v_readfirstlane_b32 s4, v161
	s_addc_u32 s21, s95, 0
	v_add_lshl_u32 v0, v1, v158, 1
	s_waitcnt vmcnt(0)
	s_barrier
	s_nop 0
	s_mov_b32 m0, s4
	v_readfirstlane_b32 s4, v162
	v_add_lshl_u32 v2, v1, v159, 1
	v_lshl_add_u64 v[6:7], s[20:21], 0, v[132:133]
	s_nop 0
	s_mov_b32 m0, s4
	v_readfirstlane_b32 s4, v163
	v_add_lshl_u32 v4, v1, v160, 1
	v_lshl_add_u64 v[6:7], v[6:7], 0, v[134:135]
	s_nop 0
	s_mov_b32 m0, s4
	v_readfirstlane_b32 s4, v164
	v_lshl_add_u64 v[136:137], v[6:7], 0, s[10:11]
	s_nop 0
	s_mov_b32 m0, s4
	v_readfirstlane_b32 s4, v165
	v_lshl_add_u64 v[138:139], s[2:3], 0, v[130:131]
	v_mov_b32_e32 v1, v131
	v_lshl_add_u64 v[146:147], v[6:7], 0, s[12:13]
	s_nop 0
	s_mov_b32 m0, s4
	v_readfirstlane_b32 s4, v166
	v_lshl_add_u64 v[140:141], s[2:3], 0, v[0:1]
	v_mov_b32_e32 v3, v131
	s_nop 0
	v_lshl_add_u64 v[0:1], v[138:139], 0, 64
	s_mov_b32 m0, s4
	v_readfirstlane_b32 s4, v167
	v_lshl_add_u64 v[142:143], s[2:3], 0, v[2:3]
	v_mov_b32_e32 v5, v131
	s_nop 0
	v_lshl_add_u64 v[0:1], v[140:141], 0, 64
	s_mov_b32 m0, s4
	v_readfirstlane_b32 s4, v168
	v_lshl_add_u64 v[144:145], s[2:3], 0, v[4:5]
	s_nop 0
	v_lshl_add_u64 v[0:1], v[142:143], 0, 64
	s_mov_b32 m0, s4
	v_readfirstlane_b32 s4, v169
	s_nop 0
	v_lshl_add_u64 v[0:1], v[144:145], 0, 64
	s_mov_b32 m0, s4
	v_readfirstlane_b32 s4, v170
	s_nop 0
	v_lshl_add_u64 v[0:1], v[6:7], 0, s[14:15]
	s_mov_b32 m0, s4
	v_readfirstlane_b32 s4, v171
	s_nop 0
	v_lshl_add_u64 v[0:1], v[6:7], 0, s[16:17]
	s_mov_b32 m0, s4
	s_mov_b32 s20, s5
	s_nop 0
	s_mov_b32 s21, 2
	s_mov_b32 s40, s5
	v_mov_b32_e32 v0, 0
	v_mov_b32_e32 v1, v131
	v_mov_b32_e32 v2, v131
	v_mov_b32_e32 v4, v131
	v_mov_b32_e32 v6, v131
	v_mov_b32_e32 v7, v131
	v_mov_b32_e32 v8, v131
	v_mov_b32_e32 v9, v131
	v_mov_b32_e32 v10, v131
	v_mov_b32_e32 v11, v131
	v_mov_b32_e32 v12, v131
	v_mov_b32_e32 v13, v131
	v_mov_b32_e32 v14, v131
	v_mov_b32_e32 v15, v131
	v_mov_b32_e32 v16, 0
	v_mov_b32_e32 v17, v131
	v_mov_b32_e32 v18, v131
	v_mov_b32_e32 v19, v131
	v_mov_b32_e32 v20, v131
	v_mov_b32_e32 v21, v131
	v_mov_b32_e32 v22, v131
	v_mov_b32_e32 v23, v131
	v_mov_b32_e32 v24, v131
	v_mov_b32_e32 v25, v131
	v_mov_b32_e32 v26, v131
	v_mov_b32_e32 v27, v131
	v_mov_b32_e32 v28, v131
	v_mov_b32_e32 v29, v131
	v_mov_b32_e32 v30, v131
	v_mov_b32_e32 v31, v131
	v_mov_b32_e32 v32, 0
	v_mov_b32_e32 v33, v131
	v_mov_b32_e32 v34, v131
	v_mov_b32_e32 v35, v131
	v_mov_b32_e32 v36, v131
	v_mov_b32_e32 v37, v131
	v_mov_b32_e32 v38, v131
	v_mov_b32_e32 v39, v131
	v_mov_b32_e32 v40, v131
	v_mov_b32_e32 v41, v131
	v_mov_b32_e32 v42, v131
	v_mov_b32_e32 v43, v131
	v_mov_b32_e32 v44, v131
	v_mov_b32_e32 v45, v131
	v_mov_b32_e32 v46, v131
	v_mov_b32_e32 v47, v131
	v_mov_b32_e32 v48, 0
	v_mov_b32_e32 v49, v131
	v_mov_b32_e32 v50, v131
	v_mov_b32_e32 v51, v131
	v_mov_b32_e32 v52, v131
	v_mov_b32_e32 v53, v131
	v_mov_b32_e32 v54, v131
	v_mov_b32_e32 v55, v131
	v_mov_b32_e32 v56, v131
	v_mov_b32_e32 v57, v131
	v_mov_b32_e32 v58, v131
	v_mov_b32_e32 v59, v131
	v_mov_b32_e32 v60, v131
	v_mov_b32_e32 v61, v131
	v_mov_b32_e32 v62, v131
	v_mov_b32_e32 v63, v131
	v_mov_b32_e32 v64, 0
	v_mov_b32_e32 v65, v131
	v_mov_b32_e32 v66, v131
	v_mov_b32_e32 v67, v131
	v_mov_b32_e32 v68, v131
	v_mov_b32_e32 v69, v131
	v_mov_b32_e32 v70, v131
	v_mov_b32_e32 v71, v131
	v_mov_b32_e32 v72, v131
	v_mov_b32_e32 v73, v131
	v_mov_b32_e32 v74, v131
	v_mov_b32_e32 v75, v131
	v_mov_b32_e32 v76, v131
	v_mov_b32_e32 v77, v131
	v_mov_b32_e32 v78, v131
	v_mov_b32_e32 v79, v131
	v_mov_b32_e32 v80, 0
	v_mov_b32_e32 v81, v131
	v_mov_b32_e32 v82, v131
	v_mov_b32_e32 v83, v131
	v_mov_b32_e32 v84, v131
	v_mov_b32_e32 v85, v131
	v_mov_b32_e32 v86, v131
	v_mov_b32_e32 v87, v131
	v_mov_b32_e32 v88, v131
	v_mov_b32_e32 v89, v131
	v_mov_b32_e32 v90, v131
	v_mov_b32_e32 v91, v131
	v_mov_b32_e32 v92, v131
	v_mov_b32_e32 v93, v131
	v_mov_b32_e32 v94, v131
	v_mov_b32_e32 v95, v131
	v_mov_b32_e32 v96, 0
	v_mov_b32_e32 v97, v131
	v_mov_b32_e32 v98, v131
	v_mov_b32_e32 v99, v131
	v_mov_b32_e32 v100, v131
	v_mov_b32_e32 v101, v131
	v_mov_b32_e32 v102, v131
	v_mov_b32_e32 v103, v131
	v_mov_b32_e32 v104, v131
	v_mov_b32_e32 v105, v131
	v_mov_b32_e32 v106, v131
	v_mov_b32_e32 v107, v131
	v_mov_b32_e32 v108, v131
	v_mov_b32_e32 v109, v131
	v_mov_b32_e32 v110, v131
	v_mov_b32_e32 v111, v131
	v_mov_b32_e32 v112, 0
	v_mov_b32_e32 v113, v131
	v_mov_b32_e32 v114, v131
	v_mov_b32_e32 v115, v131
	v_mov_b32_e32 v116, v131
	v_mov_b32_e32 v117, v131
	v_mov_b32_e32 v118, v131
	v_mov_b32_e32 v119, v131
	v_mov_b32_e32 v120, v131
	v_mov_b32_e32 v121, v131
	v_mov_b32_e32 v122, v131
	v_mov_b32_e32 v123, v131
	v_mov_b32_e32 v124, v131
	v_mov_b32_e32 v125, v131
	v_mov_b32_e32 v126, v131
	v_mov_b32_e32 v127, v131
	s_mov_b64 s[54:55], 0x80
	v_lshrrev_b32_e32 v174, 6, v180
	v_lshlrev_b32_e32 v184, 11, v174
	v_and_b32_e32 v148, 63, v180
	v_readfirstlane_b32 s53, v184
	v_lshrrev_b32_e32 v149, 4, v148
	v_bfe_u32 v150, v148, 1, 3
	v_xor_b32_e32 v150, v149, v150
	v_and_b32_e32 v151, 31, v148
	v_lshlrev_b32_e32 v151, 7, v151
	v_lshrrev_b32_e32 v151, 3, v148
	v_lshlrev_b32_e32 v184, 4, v151
	v_add_u32_e32 v185, 0x80, v184
	v_and_b32_e32 v151, 7, v148
	v_lshrrev_b32_e32 v149, 4, v148
	v_xor_b32_e32 v149, v151, v149
	v_lshrrev_b32_e32 v151, 5, v148
	v_sub_u32_e32 v186, v149, v151
	v_xor_b32_e32 v149, 4, v149
	v_add_u32_e32 v151, 2, v151
	v_sub_u32_e32 v188, v149, v151
	v_lshlrev_b32_e32 v186, 4, v186
	v_ashrrev_i32_e32 v187, 31, v186
	v_lshlrev_b32_e32 v188, 4, v188
	v_ashrrev_i32_e32 v189, 31, v188
	ds_bpermute_b32 v246, v184, v136
	ds_bpermute_b32 v247, v184, v137
	ds_bpermute_b32 v248, v185, v136
	ds_bpermute_b32 v249, v185, v137
	ds_bpermute_b32 v250, v184, v146
	ds_bpermute_b32 v251, v184, v147
	ds_bpermute_b32 v252, v185, v146
	ds_bpermute_b32 v253, v185, v147
	s_waitcnt lgkmcnt(0)
	ds_bpermute_b32 v178, v184, v138
	ds_bpermute_b32 v179, v184, v139
	ds_bpermute_b32 v236, v185, v138
	ds_bpermute_b32 v237, v185, v139
	ds_bpermute_b32 v238, v184, v140
	ds_bpermute_b32 v239, v184, v141
	ds_bpermute_b32 v240, v185, v140
	ds_bpermute_b32 v241, v185, v141
	ds_bpermute_b32 v242, v184, v142
	ds_bpermute_b32 v243, v184, v143
	ds_bpermute_b32 v244, v185, v142
	ds_bpermute_b32 v245, v185, v143
	ds_bpermute_b32 v136, v184, v144
	ds_bpermute_b32 v137, v184, v145
	ds_bpermute_b32 v146, v185, v144
	ds_bpermute_b32 v147, v185, v145
	s_waitcnt lgkmcnt(0)
	v_and_b32_e32 v151, 15, v148
	v_lshlrev_b32_e32 v151, 7, v151
	v_lshrrev_b32_e32 v149, 1, v174
	v_lshl_add_u32 v138, v149, 14, v151
	v_and_b32_e32 v149, 1, v174
	v_lshl_add_u32 v142, v149, 13, v151
	v_add_u32_e32 v142, 0x10000, v142
	v_xor_b32_e32 v151, 4, v150
	v_lshl_add_u32 v139, v151, 4, v138
	v_lshl_add_u32 v143, v151, 4, v142
	v_xor_b32_e32 v151, 0, v150
	v_lshl_add_u32 v138, v151, 4, v138
	v_lshl_add_u32 v142, v151, 4, v142
	v_lshl_add_u64 v[178:179], v[178:179], 0, v[186:187]
	v_lshl_add_u64 v[236:237], v[236:237], 0, v[188:189]
	v_lshl_add_u64 v[238:239], v[238:239], 0, v[186:187]
	v_lshl_add_u64 v[240:241], v[240:241], 0, v[188:189]
	v_lshl_add_u64 v[242:243], v[242:243], 0, v[186:187]
	v_lshl_add_u64 v[244:245], v[244:245], 0, v[188:189]
	v_lshl_add_u64 v[136:137], v[136:137], 0, v[186:187]
	v_lshl_add_u64 v[146:147], v[146:147], 0, v[188:189]
	v_lshl_add_u64 v[246:247], v[246:247], 0, v[186:187]
	v_lshl_add_u64 v[248:249], v[248:249], 0, v[188:189]
	v_lshl_add_u64 v[250:251], v[250:251], 0, v[186:187]
	v_lshl_add_u64 v[252:253], v[252:253], 0, v[188:189]
	s_mov_b32 s58, s53
	s_add_i32 m0, s58, 0x0
	s_nop 0
	global_load_lds_dwordx4 v[178:179], off
	s_add_i32 m0, s58, 0x400
	v_lshl_add_u64 v[178:179], v[178:179], 0, s[54:55]
	global_load_lds_dwordx4 v[236:237], off
	s_add_i32 m0, s58, 0x2000
	v_lshl_add_u64 v[236:237], v[236:237], 0, s[54:55]
	global_load_lds_dwordx4 v[238:239], off
	s_add_i32 m0, s58, 0x2400
	v_lshl_add_u64 v[238:239], v[238:239], 0, s[54:55]
	global_load_lds_dwordx4 v[240:241], off
	s_add_i32 m0, s58, 0x4000
	v_lshl_add_u64 v[240:241], v[240:241], 0, s[54:55]
	global_load_lds_dwordx4 v[242:243], off
	s_add_i32 m0, s58, 0x4400
	v_lshl_add_u64 v[242:243], v[242:243], 0, s[54:55]
	global_load_lds_dwordx4 v[244:245], off
	s_add_i32 m0, s58, 0x6000
	v_lshl_add_u64 v[244:245], v[244:245], 0, s[54:55]
	global_load_lds_dwordx4 v[136:137], off
	s_add_i32 m0, s58, 0x6400
	v_lshl_add_u64 v[136:137], v[136:137], 0, s[54:55]
	global_load_lds_dwordx4 v[146:147], off
	v_lshl_add_u64 v[146:147], v[146:147], 0, s[54:55]
	s_add_i32 s58, s53, 0x10000
	s_add_i32 m0, s58, 0x0
	s_nop 0
	global_load_lds_dwordx4 v[246:247], off
	s_add_i32 m0, s58, 0x400
	v_lshl_add_u64 v[246:247], v[246:247], 0, s[54:55]
	global_load_lds_dwordx4 v[248:249], off
	s_add_i32 m0, s58, 0x2000
	v_lshl_add_u64 v[248:249], v[248:249], 0, s[54:55]
	global_load_lds_dwordx4 v[250:251], off
	s_add_i32 m0, s58, 0x2400
	v_lshl_add_u64 v[250:251], v[250:251], 0, s[54:55]
	global_load_lds_dwordx4 v[252:253], off
	v_lshl_add_u64 v[252:253], v[252:253], 0, s[54:55]
	s_mov_b32 s20, 0
	s_mov_b32 s21, 0
	s_setprio 1

.Lg_ph17_noB:
	s_setprio 2
	s_waitcnt lgkmcnt(3)
	v_mfma_f32_16x16x32_bf16 v[0:3], v[148:151], v[190:193], v[0:3]
	v_mfma_f32_16x16x32_bf16 v[4:7], v[148:151], v[194:197], v[4:7]
	v_mfma_f32_16x16x32_bf16 v[8:11], v[148:151], v[198:201], v[8:11]
	v_mfma_f32_16x16x32_bf16 v[12:15], v[148:151], v[202:205], v[12:15]
	ds_read_b128 v[148:151], v138 offset:8192
	s_waitcnt lgkmcnt(3)
	v_mfma_f32_16x16x32_bf16 v[16:19], v[174:177], v[190:193], v[16:19]
	v_mfma_f32_16x16x32_bf16 v[20:23], v[174:177], v[194:197], v[20:23]
	v_mfma_f32_16x16x32_bf16 v[24:27], v[174:177], v[198:201], v[24:27]
	v_mfma_f32_16x16x32_bf16 v[28:31], v[174:177], v[202:205], v[28:31]
	ds_read_b128 v[174:177], v138 offset:10240
	s_waitcnt lgkmcnt(3)
	v_mfma_f32_16x16x32_bf16 v[32:35], v[182:185], v[190:193], v[32:35]
	v_mfma_f32_16x16x32_bf16 v[36:39], v[182:185], v[194:197], v[36:39]
	v_mfma_f32_16x16x32_bf16 v[40:43], v[182:185], v[198:201], v[40:43]
	v_mfma_f32_16x16x32_bf16 v[44:47], v[182:185], v[202:205], v[44:47]
	ds_read_b128 v[182:185], v138 offset:12288
	s_waitcnt lgkmcnt(3)
	v_mfma_f32_16x16x32_bf16 v[48:51], v[186:189], v[190:193], v[48:51]
	v_mfma_f32_16x16x32_bf16 v[52:55], v[186:189], v[194:197], v[52:55]
	v_mfma_f32_16x16x32_bf16 v[56:59], v[186:189], v[198:201], v[56:59]
	v_mfma_f32_16x16x32_bf16 v[60:63], v[186:189], v[202:205], v[60:63]
	ds_read_b128 v[186:189], v138 offset:14336
	s_waitcnt lgkmcnt(3)
	v_mfma_f32_16x16x32_bf16 v[64:67], v[148:151], v[190:193], v[64:67]
	v_mfma_f32_16x16x32_bf16 v[68:71], v[148:151], v[194:197], v[68:71]
	v_mfma_f32_16x16x32_bf16 v[72:75], v[148:151], v[198:201], v[72:75]
	v_mfma_f32_16x16x32_bf16 v[76:79], v[148:151], v[202:205], v[76:79]
	ds_read_b128 v[148:151], v139
	s_waitcnt lgkmcnt(3)
	v_mfma_f32_16x16x32_bf16 v[80:83], v[174:177], v[190:193], v[80:83]
	v_mfma_f32_16x16x32_bf16 v[84:87], v[174:177], v[194:197], v[84:87]
	v_mfma_f32_16x16x32_bf16 v[88:91], v[174:177], v[198:201], v[88:91]
	v_mfma_f32_16x16x32_bf16 v[92:95], v[174:177], v[202:205], v[92:95]
	ds_read_b128 v[174:177], v139 offset:2048
	s_waitcnt lgkmcnt(3)
	v_mfma_f32_16x16x32_bf16 v[96:99], v[182:185], v[190:193], v[96:99]
	v_mfma_f32_16x16x32_bf16 v[100:103], v[182:185], v[194:197], v[100:103]
	v_mfma_f32_16x16x32_bf16 v[104:107], v[182:185], v[198:201], v[104:107]
	v_mfma_f32_16x16x32_bf16 v[108:111], v[182:185], v[202:205], v[108:111]
	ds_read_b128 v[182:185], v139 offset:4096
	s_waitcnt lgkmcnt(3)
	v_mfma_f32_16x16x32_bf16 v[112:115], v[186:189], v[190:193], v[112:115]
	v_mfma_f32_16x16x32_bf16 v[116:119], v[186:189], v[194:197], v[116:119]
	v_mfma_f32_16x16x32_bf16 v[120:123], v[186:189], v[198:201], v[120:123]
	v_mfma_f32_16x16x32_bf16 v[124:127], v[186:189], v[202:205], v[124:127]
	ds_read_b128 v[186:189], v139 offset:6144
	s_waitcnt lgkmcnt(3)
	v_mfma_f32_16x16x32_bf16 v[0:3], v[148:151], v[206:209], v[0:3]
	v_mfma_f32_16x16x32_bf16 v[4:7], v[148:151], v[224:227], v[4:7]
	v_mfma_f32_16x16x32_bf16 v[8:11], v[148:151], v[228:231], v[8:11]
	v_mfma_f32_16x16x32_bf16 v[12:15], v[148:151], v[232:235], v[12:15]
	ds_read_b128 v[148:151], v139 offset:8192
	s_waitcnt lgkmcnt(3)
	v_mfma_f32_16x16x32_bf16 v[16:19], v[174:177], v[206:209], v[16:19]
	v_mfma_f32_16x16x32_bf16 v[20:23], v[174:177], v[224:227], v[20:23]
	v_mfma_f32_16x16x32_bf16 v[24:27], v[174:177], v[228:231], v[24:27]
	v_mfma_f32_16x16x32_bf16 v[28:31], v[174:177], v[232:235], v[28:31]
	ds_read_b128 v[174:177], v139 offset:10240
	s_waitcnt lgkmcnt(3)
	v_mfma_f32_16x16x32_bf16 v[32:35], v[182:185], v[206:209], v[32:35]
	v_mfma_f32_16x16x32_bf16 v[36:39], v[182:185], v[224:227], v[36:39]
	v_mfma_f32_16x16x32_bf16 v[40:43], v[182:185], v[228:231], v[40:43]
	v_mfma_f32_16x16x32_bf16 v[44:47], v[182:185], v[232:235], v[44:47]
	ds_read_b128 v[182:185], v139 offset:12288
	s_waitcnt lgkmcnt(3)
	v_mfma_f32_16x16x32_bf16 v[48:51], v[186:189], v[206:209], v[48:51]
	v_mfma_f32_16x16x32_bf16 v[52:55], v[186:189], v[224:227], v[52:55]
	v_mfma_f32_16x16x32_bf16 v[56:59], v[186:189], v[228:231], v[56:59]
	v_mfma_f32_16x16x32_bf16 v[60:63], v[186:189], v[232:235], v[60:63]
	ds_read_b128 v[186:189], v139 offset:14336
	s_waitcnt lgkmcnt(3)
	v_mfma_f32_16x16x32_bf16 v[64:67], v[148:151], v[206:209], v[64:67]
	v_mfma_f32_16x16x32_bf16 v[68:71], v[148:151], v[224:227], v[68:71]
	v_mfma_f32_16x16x32_bf16 v[72:75], v[148:151], v[228:231], v[72:75]
	v_mfma_f32_16x16x32_bf16 v[76:79], v[148:151], v[232:235], v[76:79]
	s_waitcnt lgkmcnt(2)
	v_mfma_f32_16x16x32_bf16 v[80:83], v[174:177], v[206:209], v[80:83]
	v_mfma_f32_16x16x32_bf16 v[84:87], v[174:177], v[224:227], v[84:87]
	v_mfma_f32_16x16x32_bf16 v[88:91], v[174:177], v[228:231], v[88:91]
	v_mfma_f32_16x16x32_bf16 v[92:95], v[174:177], v[232:235], v[92:95]
	s_waitcnt lgkmcnt(1)
	v_mfma_f32_16x16x32_bf16 v[96:99], v[182:185], v[206:209], v[96:99]
	v_mfma_f32_16x16x32_bf16 v[100:103], v[182:185], v[224:227], v[100:103]
	v_mfma_f32_16x16x32_bf16 v[104:107], v[182:185], v[228:231], v[104:107]
	v_mfma_f32_16x16x32_bf16 v[108:111], v[182:185], v[232:235], v[108:111]
	s_waitcnt lgkmcnt(0)
	v_mfma_f32_16x16x32_bf16 v[112:115], v[186:189], v[206:209], v[112:115]
	v_mfma_f32_16x16x32_bf16 v[116:119], v[186:189], v[224:227], v[116:119]
	v_mfma_f32_16x16x32_bf16 v[120:123], v[186:189], v[228:231], v[120:123]
	v_mfma_f32_16x16x32_bf16 v[124:127], v[186:189], v[232:235], v[124:127]
	s_setprio 1
	v_xor_b32_e32 v138, 0x8000, v138
	v_xor_b32_e32 v139, 0x8000, v139
	s_xor_b32 s21, s21, 0x8000
	s_add_i32 s20, s20, 1
	s_cmp_eq_u32 s20, 16
	s_cbranch_scc0 .Lg_ph17_top
	s_setprio 0
	s_waitcnt vmcnt(0)
	v_mov_b32_e32 v146, v180
	v_add_u32_e32 v208, 0x400, v157
	v_add_u32_e32 v207, 0x1000, v157
	v_add_u32_e32 v206, 0x1400, v157
	v_add_u32_e32 v205, 0x2000, v157
	v_add_u32_e32 v199, 0x2400, v157
	v_add_u32_e32 v200, 0x3000, v157
	v_add_u32_e32 v201, 0x3200, v157
	v_add_u32_e32 v202, 0x3400, v157
	v_add_u32_e32 v203, 0x3600, v157
	v_add_u32_e32 v204, 0x4000, v157
	v_add_u32_e32 v196, 0x4400, v157
	v_add_u32_e32 v197, 0x4800, v157
	v_add_u32_e32 v198, 0x5000, v157
	v_add_u32_e32 v193, 0x5400, v157
	v_add_u32_e32 v194, 0x5800, v157
	v_add_u32_e32 v195, 0x6000, v157
	v_add_u32_e32 v187, 0x6400, v157
	v_add_u32_e32 v188, 0x6800, v157
	v_add_u32_e32 v189, 0x7200, v157
	v_add_u32_e32 v190, 0x7400, v157
	v_add_u32_e32 v191, 0x7600, v157
	v_add_u32_e32 v192, 0x7800, v157
	v_add_u32_e32 v186, 0x8400, v157
	v_add_u32_e32 v185, 0x8800, v157
	v_add_u32_e32 v184, 0x9400, v157
	v_add_u32_e32 v183, 0x9800, v157
	v_add_u32_e32 v181, 0xa400, v157
	v_add_u32_e32 v174, 0xa800, v157
	v_add_u32_e32 v175, 0xb400, v157
	v_add_u32_e32 v176, 0xb600, v157
	v_add_u32_e32 v177, 0xb800, v157
	v_add_u32_e32 v178, 0xba00, v157
	s_waitcnt vmcnt(0)
	s_barrier
	s_and_saveexec_b64 s[20:21], s[6:7]
	s_cbranch_execz .LBB0_1740
	v_and_b32_e32 v254, 63, v180
	v_lshrrev_b32_e32 v253, 4, v254
	v_mul_u32_u24_e32 v253, 0x840, v253
	v_and_b32_e32 v254, 15, v254
	v_lshl_add_u32 v253, v254, 2, v253
	v_and_b32_e32 v254, 64, v180
	v_lshl_add_u32 v253, v254, 2, v253
	ds_write_b32 v253, v0 offset:0
	ds_write_b32 v253, v1 offset:528
	ds_write_b32 v253, v2 offset:1056
	ds_write_b32 v253, v3 offset:1584
	ds_write_b32 v253, v4 offset:64
	ds_write_b32 v253, v5 offset:592
	ds_write_b32 v253, v6 offset:1120
	ds_write_b32 v253, v7 offset:1648
	ds_write_b32 v253, v8 offset:128
	ds_write_b32 v253, v9 offset:656
	ds_write_b32 v253, v10 offset:1184
	ds_write_b32 v253, v11 offset:1712
	ds_write_b32 v253, v12 offset:192
	ds_write_b32 v253, v13 offset:720
	ds_write_b32 v253, v14 offset:1248
	ds_write_b32 v253, v15 offset:1776
	ds_write_b32 v253, v16 offset:8448
	ds_write_b32 v253, v17 offset:8976
	ds_write_b32 v253, v18 offset:9504
	ds_write_b32 v253, v19 offset:10032
	ds_write_b32 v253, v20 offset:8512
	ds_write_b32 v253, v21 offset:9040
	ds_write_b32 v253, v22 offset:9568
	ds_write_b32 v253, v23 offset:10096
	ds_write_b32 v253, v24 offset:8576
	ds_write_b32 v253, v25 offset:9104
	ds_write_b32 v253, v26 offset:9632
	ds_write_b32 v253, v27 offset:10160
	ds_write_b32 v253, v28 offset:8640
	ds_write_b32 v253, v29 offset:9168
	ds_write_b32 v253, v30 offset:9696
	ds_write_b32 v253, v31 offset:10224
	ds_write_b32 v253, v32 offset:16896
	ds_write_b32 v253, v33 offset:17424
	ds_write_b32 v253, v34 offset:17952
	ds_write_b32 v253, v35 offset:18480
	ds_write_b32 v253, v36 offset:16960
	ds_write_b32 v253, v37 offset:17488
	ds_write_b32 v253, v38 offset:18016
	ds_write_b32 v253, v39 offset:18544
	ds_write_b32 v253, v40 offset:17024
	ds_write_b32 v253, v41 offset:17552
	ds_write_b32 v253, v42 offset:18080
	ds_write_b32 v253, v43 offset:18608
	ds_write_b32 v253, v44 offset:17088
	ds_write_b32 v253, v45 offset:17616
	ds_write_b32 v253, v46 offset:18144
	ds_write_b32 v253, v47 offset:18672
	ds_write_b32 v253, v48 offset:25344
	ds_write_b32 v253, v49 offset:25872
	ds_write_b32 v253, v50 offset:26400
	ds_write_b32 v253, v51 offset:26928
	ds_write_b32 v253, v52 offset:25408
	ds_write_b32 v253, v53 offset:25936
	ds_write_b32 v253, v54 offset:26464
	ds_write_b32 v253, v55 offset:26992
	ds_write_b32 v253, v56 offset:25472
	ds_write_b32 v253, v57 offset:26000
	ds_write_b32 v253, v58 offset:26528
	ds_write_b32 v253, v59 offset:27056
	ds_write_b32 v253, v60 offset:25536
	ds_write_b32 v253, v61 offset:26064
	ds_write_b32 v253, v62 offset:26592
	ds_write_b32 v253, v63 offset:27120
	ds_write_b32 v253, v64 offset:33792
	ds_write_b32 v253, v65 offset:34320
	ds_write_b32 v253, v66 offset:34848
	ds_write_b32 v253, v67 offset:35376
	ds_write_b32 v253, v68 offset:33856
	ds_write_b32 v253, v69 offset:34384
	ds_write_b32 v253, v70 offset:34912
	ds_write_b32 v253, v71 offset:35440
	ds_write_b32 v253, v72 offset:33920
	ds_write_b32 v253, v73 offset:34448
	ds_write_b32 v253, v74 offset:34976
	ds_write_b32 v253, v75 offset:35504
	ds_write_b32 v253, v76 offset:33984
	ds_write_b32 v253, v77 offset:34512
	ds_write_b32 v253, v78 offset:35040
	ds_write_b32 v253, v79 offset:35568
	ds_write_b32 v253, v80 offset:42240
	ds_write_b32 v253, v81 offset:42768
	ds_write_b32 v253, v82 offset:43296
	ds_write_b32 v253, v83 offset:43824
	ds_write_b32 v253, v84 offset:42304
	ds_write_b32 v253, v85 offset:42832
	ds_write_b32 v253, v86 offset:43360
	ds_write_b32 v253, v87 offset:43888
	ds_write_b32 v253, v88 offset:42368
	ds_write_b32 v253, v89 offset:42896
	ds_write_b32 v253, v90 offset:43424
	ds_write_b32 v253, v91 offset:43952
	ds_write_b32 v253, v92 offset:42432
	ds_write_b32 v253, v93 offset:42960
	ds_write_b32 v253, v94 offset:43488
	ds_write_b32 v253, v95 offset:44016
	ds_write_b32 v253, v96 offset:50688
	ds_write_b32 v253, v97 offset:51216
	ds_write_b32 v253, v98 offset:51744
	ds_write_b32 v253, v99 offset:52272
	ds_write_b32 v253, v100 offset:50752
	ds_write_b32 v253, v101 offset:51280
	ds_write_b32 v253, v102 offset:51808
	ds_write_b32 v253, v103 offset:52336
	ds_write_b32 v253, v104 offset:50816
	ds_write_b32 v253, v105 offset:51344
	ds_write_b32 v253, v106 offset:51872
	ds_write_b32 v253, v107 offset:52400
	ds_write_b32 v253, v108 offset:50880
	ds_write_b32 v253, v109 offset:51408
	ds_write_b32 v253, v110 offset:51936
	ds_write_b32 v253, v111 offset:52464
	ds_write_b32 v253, v112 offset:59136
	ds_write_b32 v253, v113 offset:59664
	ds_write_b32 v253, v114 offset:60192
	ds_write_b32 v253, v115 offset:60720
	ds_write_b32 v253, v116 offset:59200
	ds_write_b32 v253, v117 offset:59728
	ds_write_b32 v253, v118 offset:60256
	ds_write_b32 v253, v119 offset:60784
	ds_write_b32 v253, v120 offset:59264
	ds_write_b32 v253, v121 offset:59792
	ds_write_b32 v253, v122 offset:60320
	ds_write_b32 v253, v123 offset:60848
	ds_write_b32 v253, v124 offset:59328
	ds_write_b32 v253, v125 offset:59856
	ds_write_b32 v253, v126 offset:60384
	ds_write_b32 v253, v127 offset:60912
